# LDS-DMA double-buffered K-loops now also in resid and merge GEMMs
# speedup vs baseline: 1.0188x; 1.0188x over previous
; __device__ __forceinline__ int tidx() { int t = threadIdx.x; asm volatile("" : "+v"(t)); return t; }
; template <int NT>
; __device__ __forceinline__ void gemm_tile(f32x4 (&acc)[4][NT], const bf16_t* A, int lda, const bf16_t* B, int ldb, int K, bf16_t* sm) {
;     const int tid_ = tidx();
;     bf16_t* sA = sm; bf16_t* sB = sm + 128 * LDT;
;     const int tid = tid_, lane = tid & 63, wid = tid >> 6, wr = wid >> 1, wc = wid & 1;
;     const int fr = lane & 15, fq = lane >> 4;
;     const int lrow = tid >> 3, lkc = tid & 7;
;     const bf16_t* ga = A + (size_t)lrow * lda + lkc * 8;
;     const bf16_t* gb = B + (size_t)lrow * ldb + lkc * 8;
;     int sbrow[NT];
; #pragma unroll
;     for (int i = 0; i < NT; ++i) { const int g = lrow + 32 * i, W_ = 16 * NT, rem = g % W_; sbrow[i] = (g / W_) * W_ + (rem % NT) * 16 + rem / NT; }
;     u32x4 ra0[4], rb0[NT];
; #pragma unroll
;     for (int i = 0; i < 4; ++i) ra0[i] = *(const u32x4*)(ga + (size_t)(32 * i) * lda);
; #pragma unroll
;     for (int i = 0; i < NT; ++i) rb0[i] = *(const u32x4*)(gb + (size_t)(32 * i) * ldb);
; template <int NT>
; __device__ __forceinline__ void resid_tile(int tm, int col0, const bf16_t* A, int lda, int K, const bf16_t* W, const float* X, float* Y, float scale, bf16_t* sm) {
;     const int tid_ = tidx();
;     const int lane = tid_ & 63, wid = tid_ >> 6, wr = wid >> 1, wc = wid & 1, fr = lane & 15, fq = lane >> 4;
;     f32x4 acc[4][NT]; zero_acc<NT>(acc);
;     gemm_tile<NT>(acc, A + (size_t)tm * 128 * lda, lda, W + (size_t)col0 * K, K, K, sm);
.LBB0_35:
	v_mov_b32_e32 v118, v192
	v_mov_b32_e32 v36, v192
	s_ashr_i32 s18, s39, 3
	v_ashrrev_i32_e32 v0, 31, v36
	v_ashrrev_i32_e32 v34, 3, v36
	v_lshrrev_b32_e32 v0, 26, v0
	v_add_u32_e32 v0, v34, v0
	v_lshrrev_b32_e32 v1, 6, v0
	v_mul_i32_i24_e32 v1, 64, v1
	v_sub_u32_e32 v1, v34, v1
	v_lshrrev_b16_sdwa v2, v196, sext(v1) dst_sel:DWORD dst_unused:UNUSED_PAD src0_sel:DWORD src1_sel:BYTE_0
	v_and_b32_e32 v2, 3, v2
	v_add_u16_e32 v2, v1, v2
	v_ashrrev_i16_sdwa v3, v197, sext(v2) dst_sel:DWORD dst_unused:UNUSED_PAD src0_sel:DWORD src1_sel:BYTE_0
	v_and_b32_e32 v2, 0xfc, v2
	v_sub_u16_e32 v1, v1, v2
	v_and_b32_e32 v0, 0x7ffffc0, v0
	v_lshlrev_b32_sdwa v1, v198, sext(v1) dst_sel:DWORD dst_unused:UNUSED_PAD src0_sel:DWORD src1_sel:BYTE_0
	v_bfe_i32 v2, v3, 0, 16
	v_add3_u32 v37, v0, v2, v1
	v_add_u32_e32 v0, 32, v34
	v_ashrrev_i32_e32 v1, 31, v0
	v_lshrrev_b32_e32 v1, 26, v1
	v_add_u32_e32 v1, v0, v1
	v_lshrrev_b32_e32 v2, 6, v1
	v_mul_i32_i24_e32 v2, 64, v2
	v_sub_u32_e32 v0, v0, v2
	v_lshrrev_b16_sdwa v2, v196, sext(v0) dst_sel:DWORD dst_unused:UNUSED_PAD src0_sel:DWORD src1_sel:BYTE_0
	v_and_b32_e32 v2, 3, v2
	v_add_u16_e32 v2, v0, v2
	v_ashrrev_i16_sdwa v3, v197, sext(v2) dst_sel:DWORD dst_unused:UNUSED_PAD src0_sel:DWORD src1_sel:BYTE_0
	v_and_b32_e32 v2, 0xfc, v2
	v_sub_u16_e32 v0, v0, v2
	v_and_b32_e32 v1, 0x7ffffc0, v1
	v_lshlrev_b32_sdwa v0, v198, sext(v0) dst_sel:DWORD dst_unused:UNUSED_PAD src0_sel:DWORD src1_sel:BYTE_0
	v_bfe_i32 v2, v3, 0, 16
	v_add3_u32 v38, v1, v2, v0
	v_add_u32_e32 v0, 64, v34
	v_ashrrev_i32_e32 v1, 31, v0
	v_lshrrev_b32_e32 v1, 26, v1
	v_add_u32_e32 v1, v0, v1
	v_lshrrev_b32_e32 v2, 6, v1
	v_mul_i32_i24_e32 v2, 64, v2
	v_sub_u32_e32 v0, v0, v2
	v_lshrrev_b16_sdwa v2, v196, sext(v0) dst_sel:DWORD dst_unused:UNUSED_PAD src0_sel:DWORD src1_sel:BYTE_0
	v_and_b32_e32 v2, 3, v2
	v_add_u16_e32 v2, v0, v2
	v_ashrrev_i16_sdwa v3, v197, sext(v2) dst_sel:DWORD dst_unused:UNUSED_PAD src0_sel:DWORD src1_sel:BYTE_0
	v_and_b32_e32 v2, 0xfc, v2
	v_sub_u16_e32 v0, v0, v2
	v_and_b32_e32 v1, 0x7ffffc0, v1
	v_lshlrev_b32_sdwa v0, v198, sext(v0) dst_sel:DWORD dst_unused:UNUSED_PAD src0_sel:DWORD src1_sel:BYTE_0
	v_bfe_i32 v2, v3, 0, 16
	v_add3_u32 v39, v1, v2, v0
	v_add_u32_e32 v0, 0x60, v34
	v_ashrrev_i32_e32 v1, 31, v0
	v_lshrrev_b32_e32 v1, 26, v1
	v_add_u32_e32 v1, v0, v1
	v_lshrrev_b32_e32 v2, 6, v1
	v_mul_i32_i24_e32 v2, 64, v2
	v_sub_u32_e32 v0, v0, v2
	s_ashr_i32 s19, s18, 31
	v_lshrrev_b16_sdwa v2, v196, sext(v0) dst_sel:DWORD dst_unused:UNUSED_PAD src0_sel:DWORD src1_sel:BYTE_0
	s_lshl_b32 s2, s39, 7
	s_lshl_b64 s[76:77], s[18:19], s97
	v_and_b32_e32 v2, 3, v2
	s_and_b32 s2, s2, 0x380
	s_lshl_b64 s[78:79], s[76:77], 1
	v_add_u16_e32 v2, v0, v2
	s_add_u32 s84, s12, s78
	v_ashrrev_i16_sdwa v3, v197, sext(v2) dst_sel:DWORD dst_unused:UNUSED_PAD src0_sel:DWORD src1_sel:BYTE_0
	v_and_b32_e32 v2, 0xfc, v2
	s_addc_u32 s85, s11, s79
	s_lshl_b32 s19, s2, vcc_lo
	v_sub_u16_e32 v0, v0, v2
	s_lshl_b32 s19, s19, 1
	v_and_b32_e32 v1, 0x7ffffc0, v1
	v_lshlrev_b32_sdwa v0, v198, sext(v0) dst_sel:DWORD dst_unused:UNUSED_PAD src0_sel:DWORD src1_sel:BYTE_0
	v_bfe_i32 v2, v3, 0, 16
	v_ashrrev_i32_e32 v35, 31, v34
	s_add_u32 s76, s13, s19
	v_add3_u32 v40, v1, v2, v0
	v_lshlrev_b64 v[0:1], vcc_lo, v[34:35]
	s_addc_u32 s77, s94, 0
	v_lshlrev_b64 v[100:101], 1, v[0:1]
	v_lshlrev_b32_e32 v2, 4, v36
	v_lshl_add_u64 v[0:1], s[76:77], 0, v[100:101]
	v_and_b32_e32 v12, 0x70, v2
	v_lshl_add_u64 v[18:19], s[84:85], 0, v[100:101]
	v_lshl_add_u64 v[4:5], v[0:1], 0, v[12:13]
	s_mov_b32 s75, s87
	s_mov_b32 s83, s87
	v_lshl_add_u64 v[18:19], v[18:19], 0, v[12:13]
	v_lshl_add_u64 v[0:1], v[4:5], 0, s[86:87]
	v_lshl_add_u64 v[6:7], v[4:5], 0, s[74:75]
	v_lshl_add_u64 v[14:15], v[4:5], 0, s[82:83]
	v_lshl_add_u64 v[20:21], v[18:19], 0, s[86:87]
	v_mov_b32_e32 v250, v4
	v_mov_b32_e32 v251, v5
	s_nop 0
	s_nop 0
	s_nop 0
	s_nop 0
	v_mov_b32_e32 v248, v18
	v_mov_b32_e32 v249, v19
	v_lshl_add_u64 v[20:21], v[18:19], 0, s[74:75]
	v_lshl_add_u64 v[26:27], v[18:19], 0, s[82:83]
	s_nop 0
	v_and_b32_e32 v35, 15, v36
	v_lshrrev_b32_e32 v42, 1, v36
	v_and_or_b32 v35, v42, s3, v35
	v_mul_lo_u32 v42, v35, s89
	v_mul_lo_u32 v43, v34, s89
	v_lshl_add_u64 v[34:35], v[12:13], 0, s[78:79]
	v_and_b32_e32 v41, 48, v36
	v_and_b32_e32 v36, 0x4f, v36
	v_lshl_add_u64 v[102:103], s[42:43], 0, v[34:35]
	v_lshl_add_u64 v[104:105], s[44:45], 0, v[34:35]
	v_lshl_add_u64 v[106:107], s[46:47], 0, v[34:35]
	v_lshl_add_u64 v[108:109], s[40:41], 0, v[34:35]
	v_or_b32_e32 v34, s19, v12
	v_mov_b32_e32 v35, v13
	v_mul_u32_u24_e32 v36, 0xa0, v36
	v_mul_lo_u32 v37, v37, s89
	v_mul_lo_u32 v38, v38, s89
	v_mul_lo_u32 v39, v39, s89
	v_mul_lo_u32 v40, v40, s89
	v_lshl_add_u64 v[110:111], s[48:49], 0, v[34:35]
	v_lshl_add_u64 v[112:113], s[50:51], 0, v[34:35]
	v_lshl_add_u64 v[114:115], s[52:53], 0, v[34:35]
	v_lshl_add_u64 v[116:117], s[54:55], 0, v[34:35]
	v_mov_b32_e32 v34, 0
	v_add_u32_e32 v120, v12, v43
	v_add_u32_e32 v121, v12, v37
	v_add_u32_e32 v122, v12, v38
	v_add_u32_e32 v123, v12, v39
	v_add_u32_e32 v124, v12, v40
	v_add_u32_e32 v119, v41, v42
	v_add_u32_e32 v12, v41, v36
	s_mov_b32 s19, vcc_hi
	v_mov_b32_e32 v35, v34
	v_mov_b32_e32 v36, v34
	v_mov_b32_e32 v37, v34
	v_mov_b32_e32 v38, v34
	v_mov_b32_e32 v39, v34
	v_mov_b32_e32 v40, v34
	v_mov_b32_e32 v41, v34
	v_mov_b32_e32 v42, v34
	v_mov_b32_e32 v43, v34
	v_mov_b32_e32 v44, v34
	v_mov_b32_e32 v45, v34
	v_mov_b32_e32 v46, v34
	v_mov_b32_e32 v47, v34
	v_mov_b32_e32 v48, v34
	v_mov_b32_e32 v49, v34
	v_mov_b32_e32 v50, v34
	v_mov_b32_e32 v51, v34
	v_mov_b32_e32 v52, v34
	v_mov_b32_e32 v53, v34
	v_mov_b32_e32 v54, v34
	v_mov_b32_e32 v55, v34
; template <int NT>
; __device__ __forceinline__ void gemm_tile(f32x4 (&acc)[4][NT], const bf16_t* A, int lda, const bf16_t* B, int ldb, int K, bf16_t* sm) {
;     ...
;     for (int kt = 0; kt < nk; ++kt) {
;         lds_barrier();
; #pragma unroll
;         for (int i = 0; i < 4; ++i) *(u32x4*)(sA + (lrow + 32 * i) * LDT + lkc * 8) = ra0[i];
; #pragma unroll
;         for (int i = 0; i < NT; ++i) *(u32x4*)(sB + sbrow[i] * LDT + lkc * 8) = rb0[i];
;         lds_barrier();
;         if (kt + 1 < nk) {
;             ga += 64; gb += 64;
; #pragma unroll
;             for (int i = 0; i < 4; ++i) ra0[i] = *(const u32x4*)(ga + (size_t)(32 * i) * lda);
; #pragma unroll
;             for (int i = 0; i < NT; ++i) rb0[i] = *(const u32x4*)(gb + (size_t)(32 * i) * ldb);
;         }
;         __builtin_amdgcn_sched_barrier(0);
;         gemm_compute<NT>(acc, sA, sB, wr, wc, fr, fq);
	v_mov_b32_e32 v56, v34
	v_mov_b32_e32 v57, v34
	v_mov_b32_e32 v58, v34
	v_mov_b32_e32 v59, v34
	v_mov_b32_e32 v60, v34
	v_mov_b32_e32 v61, v34
	v_mov_b32_e32 v62, v34
	v_mov_b32_e32 v63, v34
	v_mov_b32_e32 v64, v34
	v_mov_b32_e32 v65, v34
	v_mov_b32_e32 v66, v34
	v_mov_b32_e32 v67, v34
	v_mov_b32_e32 v68, v34
	v_mov_b32_e32 v69, v34
	v_mov_b32_e32 v70, v34
	v_mov_b32_e32 v71, v34
	v_mov_b32_e32 v72, v34
	v_mov_b32_e32 v73, v34
	v_mov_b32_e32 v74, v34
	v_mov_b32_e32 v75, v34
	v_mov_b32_e32 v76, v34
	v_mov_b32_e32 v77, v34
	v_mov_b32_e32 v78, v34
	v_mov_b32_e32 v79, v34
	v_mov_b32_e32 v80, v34
	v_mov_b32_e32 v81, v34
	v_mov_b32_e32 v82, v34
	v_mov_b32_e32 v83, v34
	v_mov_b32_e32 v84, v34
	v_mov_b32_e32 v85, v34
	v_mov_b32_e32 v86, v34
	v_mov_b32_e32 v87, v34
	v_mov_b32_e32 v88, v34
	v_mov_b32_e32 v89, v34
	v_mov_b32_e32 v90, v34
	v_mov_b32_e32 v91, v34
	v_mov_b32_e32 v92, v34
	v_mov_b32_e32 v93, v34
	v_mov_b32_e32 v94, v34
	v_mov_b32_e32 v95, v34
	v_mov_b32_e32 v96, v34
	v_mov_b32_e32 v97, v34
	v_writelane_b32 v234, s90, 0
	v_writelane_b32 v234, s91, 1
	v_writelane_b32 v234, s92, 2
	v_writelane_b32 v234, s93, 3
	v_writelane_b32 v234, s94, 4
	v_writelane_b32 v234, s95, 5
	v_bfe_u32 v160, v192, 3, 3
	v_and_b32_e32 v161, 7, v192
	v_xor_b32_e32 v161, v160, v161
	v_lshlrev_b32_e32 v161, 4, v161
	v_lshrrev_b32_e32 v162, 6, v192
	v_lshl_add_u32 v163, v162, 5, v160
	s_lshl_b32 s95, s96, 1
	v_mul_u32_u24_e32 v163, s95, v163
	v_add_u32_e32 v236, v163, v161
	s_lshl_b32 s95, s96, 4
	s_sub_u32 s95, s95, 0x400
	v_add_u32_e32 v237, s95, v236
	v_add_u32_e32 v238, s95, v237
	v_add_u32_e32 v239, s95, v238
	v_lshrrev_b32_e32 v163, 7, v192
	v_bfe_u32 v162, v192, 6, 1
	v_lshlrev_b32_e32 v163, 6, v163
	v_lshl_add_u32 v163, v160, 2, v163
	v_lshl_add_u32 v163, v162, 1, v163
	s_lshl_b32 s95, s96, 1
	v_mul_u32_u24_e32 v163, s95, v163
	v_add_u32_e32 v240, v163, v161
	s_mul_i32 s95, s96, 64
	s_sub_u32 s95, s95, 0x400
	v_add_u32_e32 v241, s95, v240
	s_mul_i32 s95, s96, 62
	s_add_u32 s95, s95, 0x400
	v_subrev_u32_e32 v242, s95, v241
	s_mul_i32 s95, s96, 64
	s_sub_u32 s95, s95, 0x400
	v_add_u32_e32 v243, s95, v242
	v_and_b32_e32 v160, 15, v192
	v_bfe_u32 v161, v192, 4, 2
	v_and_b32_e32 v162, 7, v160
	v_xor_b32_e32 v161, v161, v162
	v_lshlrev_b32_e32 v161, 4, v161
	v_lshl_add_u32 v161, v160, 7, v161
	v_lshrrev_b32_e32 v162, 7, v192
	v_lshl_add_u32 v244, v162, 13, v161
	v_bfe_u32 v162, v192, 6, 1
	v_lshl_add_u32 v246, v162, 13, v161
	v_add_u32_e32 v246, 0x4000, v246
	v_xor_b32_e32 v245, 64, v244
	v_xor_b32_e32 v247, 64, v246
	v_lshrrev_b32_e32 v160, 6, v192
	s_nop 0
	v_readfirstlane_b32 s94, v160
	v_readfirstlane_b32 s90, v248
	v_readfirstlane_b32 s91, v249
	v_readfirstlane_b32 s92, v250
	v_readfirstlane_b32 s93, v251
	s_lshl_b32 s95, s96, 4
	s_mul_i32 s95, s94, s95
	s_sub_u32 s90, s90, s95
	s_subb_u32 s91, s91, 0
	s_lshl_b32 s95, s96, 4
	s_mul_i32 s95, s94, s95
	s_sub_u32 s92, s92, s95
	s_subb_u32 s93, s93, 0
	s_lshl_b32 s94, s94, 10
	s_waitcnt lgkmcnt(0)
	s_barrier
	s_lshl_b32 s95, s94, 2
	s_add_u32 m0, s95, 0x0
	s_nop 0
	global_load_lds_dwordx4 v236, s[90:91]
	global_load_lds_dwordx4 v237, s[90:91] offset:1024
	global_load_lds_dwordx4 v238, s[90:91] offset:2048
	global_load_lds_dwordx4 v239, s[90:91] offset:3072
	s_mul_i32 s95, s94, 4
	s_add_u32 m0, s95, 0x4000
	s_nop 0
	global_load_lds_dwordx4 v240, s[92:93]
	global_load_lds_dwordx4 v241, s[92:93] offset:1024
	global_load_lds_dwordx4 v242, s[92:93] offset:2048
	global_load_lds_dwordx4 v243, s[92:93] offset:3072
	s_add_u32 s90, s90, 0x80
	s_addc_u32 s91, s91, 0
	s_add_u32 s92, s92, 0x80
	s_addc_u32 s93, s93, 0
	s_waitcnt vmcnt(0)
	s_barrier
	s_lshl_b32 s95, s94, 2
	s_add_u32 m0, s95, 0x8000
	s_nop 0
	global_load_lds_dwordx4 v236, s[90:91]
	global_load_lds_dwordx4 v237, s[90:91] offset:1024
	global_load_lds_dwordx4 v238, s[90:91] offset:2048
	global_load_lds_dwordx4 v239, s[90:91] offset:3072
	s_mul_i32 s95, s94, 4
	s_add_u32 m0, s95, 0xc000
	s_nop 0
	global_load_lds_dwordx4 v240, s[92:93]
	global_load_lds_dwordx4 v241, s[92:93] offset:1024
	global_load_lds_dwordx4 v242, s[92:93] offset:2048
	global_load_lds_dwordx4 v243, s[92:93] offset:3072
	s_add_u32 s90, s90, 0x80
	s_addc_u32 s91, s91, 0
	s_add_u32 s92, s92, 0x80
	s_addc_u32 s93, s93, 0
	ds_read_b128 v[126:129], v244 offset:0
	ds_read_b128 v[130:133], v244 offset:2048
	ds_read_b128 v[134:137], v244 offset:4096
	ds_read_b128 v[138:141], v244 offset:6144
	ds_read_b128 v[142:145], v246 offset:0
	ds_read_b128 v[146:149], v246 offset:2048
	ds_read_b128 v[152:155], v246 offset:4096
	ds_read_b128 v[156:159], v246 offset:6144
	s_lshr_b32 s95, s96, 7
	s_add_i32 s95, s95, -2
	s_cmp_eq_u32 s95, 0
	s_cbranch_scc1 .Lgemm_x36
; template <int NT>
; __device__ __forceinline__ void gemm_compute(f32x4 (&acc)[4][NT], const bf16_t* sA, const bf16_t* sB, int wr, int wc, int fr, int fq) {
; #pragma unroll
;     for (int ks = 0; ks < 2; ++ks) {
;         bf16x8 a[4], b[NT];
; #pragma unroll
;         for (int mt = 0; mt < 4; ++mt) a[mt] = *(const bf16x8*)(sA + (wr * 64 + mt * 16 + fr) * LDT + ks * 32 + fq * 8);
; #pragma unroll
;         for (int nt = 0; nt < NT; ++nt) b[nt] = *(const bf16x8*)(sB + (wc * 16 * NT + nt * 16 + fr) * LDT + ks * 32 + fq * 8);
;         __builtin_amdgcn_s_setprio(1);
; #pragma unroll
;         for (int mt = 0; mt < 4; ++mt)
; #pragma unroll
;             for (int nt = 0; nt < NT; ++nt)
;                 acc[mt][nt] = __builtin_amdgcn_mfma_f32_16x16x32_bf16(b[nt], a[mt], acc[mt][nt], 0, 0, 0);
;         __builtin_amdgcn_s_setprio(0);
;     }
; template <int NT>
; __device__ __forceinline__ void gemm_tile(f32x4 (&acc)[4][NT], const bf16_t* A, int lda, const bf16_t* B, int ldb, int K, bf16_t* sm) {
;     ...
;     for (int kt = 0; kt < nk; ++kt) {
;         lds_barrier();
; #pragma unroll
;         for (int i = 0; i < 4; ++i) *(u32x4*)(sA + (lrow + 32 * i) * LDT + lkc * 8) = ra0[i];
; #pragma unroll
;         for (int i = 0; i < NT; ++i) *(u32x4*)(sB + sbrow[i] * LDT + lkc * 8) = rb0[i];
;         lds_barrier();
;         if (kt + 1 < nk) {
;             ga += 64; gb += 64;
; #pragma unroll
;             for (int i = 0; i < 4; ++i) ra0[i] = *(const u32x4*)(ga + (size_t)(32 * i) * lda);
; #pragma unroll
;             for (int i = 0; i < NT; ++i) rb0[i] = *(const u32x4*)(gb + (size_t)(32 * i) * ldb);
;         }
;         __builtin_amdgcn_sched_barrier(0);
;         gemm_compute<NT>(acc, sA, sB, wr, wc, fr, fq);
;         __builtin_amdgcn_sched_barrier(0);
;     }
.Lgemm_k36:
	v_writelane_b32 v234, s95, 6
	ds_read_b128 v[160:163], v245 offset:0
	ds_read_b128 v[164:167], v245 offset:2048
	ds_read_b128 v[168:171], v245 offset:4096
	ds_read_b128 v[172:175], v245 offset:6144
	ds_read_b128 v[176:179], v247 offset:0
	ds_read_b128 v[180:183], v247 offset:2048
	ds_read_b128 v[184:187], v247 offset:4096
	ds_read_b128 v[188:191], v247 offset:6144
	s_setprio 1
	s_waitcnt lgkmcnt(11)
	v_mfma_f32_16x16x32_bf16 v[94:97], v[142:145], v[126:129], v[94:97]
	s_waitcnt lgkmcnt(10)
	v_mfma_f32_16x16x32_bf16 v[90:93], v[146:149], v[126:129], v[90:93]
	s_waitcnt lgkmcnt(9)
	v_mfma_f32_16x16x32_bf16 v[86:89], v[152:155], v[126:129], v[86:89]
	s_waitcnt lgkmcnt(8)
	v_mfma_f32_16x16x32_bf16 v[82:85], v[156:159], v[126:129], v[82:85]
	v_mfma_f32_16x16x32_bf16 v[78:81], v[142:145], v[130:133], v[78:81]
	v_mfma_f32_16x16x32_bf16 v[74:77], v[146:149], v[130:133], v[74:77]
	v_mfma_f32_16x16x32_bf16 v[70:73], v[152:155], v[130:133], v[70:73]
	v_mfma_f32_16x16x32_bf16 v[66:69], v[156:159], v[130:133], v[66:69]
	v_mfma_f32_16x16x32_bf16 v[62:65], v[142:145], v[134:137], v[62:65]
	v_mfma_f32_16x16x32_bf16 v[58:61], v[146:149], v[134:137], v[58:61]
	v_mfma_f32_16x16x32_bf16 v[54:57], v[152:155], v[134:137], v[54:57]
	v_mfma_f32_16x16x32_bf16 v[50:53], v[156:159], v[134:137], v[50:53]
	v_mfma_f32_16x16x32_bf16 v[46:49], v[142:145], v[138:141], v[46:49]
	v_mfma_f32_16x16x32_bf16 v[42:45], v[146:149], v[138:141], v[42:45]
	v_mfma_f32_16x16x32_bf16 v[38:41], v[152:155], v[138:141], v[38:41]
	v_mfma_f32_16x16x32_bf16 v[34:37], v[156:159], v[138:141], v[34:37]
	s_setprio 0
	s_waitcnt vmcnt(0) lgkmcnt(0)
	s_barrier
	ds_read_b128 v[126:129], v244 offset:32768
	ds_read_b128 v[130:133], v244 offset:34816
	ds_read_b128 v[134:137], v244 offset:36864
	ds_read_b128 v[138:141], v244 offset:38912
	ds_read_b128 v[142:145], v246 offset:32768
	ds_read_b128 v[146:149], v246 offset:34816
	ds_read_b128 v[152:155], v246 offset:36864
	ds_read_b128 v[156:159], v246 offset:38912
	s_setprio 1
	v_mfma_f32_16x16x32_bf16 v[94:97], v[176:179], v[160:163], v[94:97]
	s_lshl_b32 s95, s94, 2
	s_add_u32 m0, s95, 0x0
	s_nop 0
	global_load_lds_dwordx4 v236, s[90:91]
	v_mfma_f32_16x16x32_bf16 v[90:93], v[180:183], v[160:163], v[90:93]
	v_mfma_f32_16x16x32_bf16 v[86:89], v[184:187], v[160:163], v[86:89]
	global_load_lds_dwordx4 v237, s[90:91] offset:1024
	v_mfma_f32_16x16x32_bf16 v[82:85], v[188:191], v[160:163], v[82:85]
	v_mfma_f32_16x16x32_bf16 v[78:81], v[176:179], v[164:167], v[78:81]
	global_load_lds_dwordx4 v238, s[90:91] offset:2048
	v_mfma_f32_16x16x32_bf16 v[74:77], v[180:183], v[164:167], v[74:77]
	v_mfma_f32_16x16x32_bf16 v[70:73], v[184:187], v[164:167], v[70:73]
	global_load_lds_dwordx4 v239, s[90:91] offset:3072
	v_mfma_f32_16x16x32_bf16 v[66:69], v[188:191], v[164:167], v[66:69]
	v_mfma_f32_16x16x32_bf16 v[62:65], v[176:179], v[168:171], v[62:65]
	s_mul_i32 s95, s94, 4
	s_add_u32 m0, s95, 0x4000
	s_nop 0
	global_load_lds_dwordx4 v240, s[92:93]
	v_mfma_f32_16x16x32_bf16 v[58:61], v[180:183], v[168:171], v[58:61]
	v_mfma_f32_16x16x32_bf16 v[54:57], v[184:187], v[168:171], v[54:57]
	global_load_lds_dwordx4 v241, s[92:93] offset:1024
	v_mfma_f32_16x16x32_bf16 v[50:53], v[188:191], v[168:171], v[50:53]
	v_mfma_f32_16x16x32_bf16 v[46:49], v[176:179], v[172:175], v[46:49]
	global_load_lds_dwordx4 v242, s[92:93] offset:2048
	v_mfma_f32_16x16x32_bf16 v[42:45], v[180:183], v[172:175], v[42:45]
	v_mfma_f32_16x16x32_bf16 v[38:41], v[184:187], v[172:175], v[38:41]
	global_load_lds_dwordx4 v243, s[92:93] offset:3072
	v_mfma_f32_16x16x32_bf16 v[34:37], v[188:191], v[172:175], v[34:37]
	s_add_u32 s90, s90, 0x80
	s_addc_u32 s91, s91, 0
	s_add_u32 s92, s92, 0x80
	s_addc_u32 s93, s93, 0
	s_setprio 0
	ds_read_b128 v[160:163], v245 offset:32768
	ds_read_b128 v[164:167], v245 offset:34816
	ds_read_b128 v[168:171], v245 offset:36864
	ds_read_b128 v[172:175], v245 offset:38912
	ds_read_b128 v[176:179], v247 offset:32768
	ds_read_b128 v[180:183], v247 offset:34816
	ds_read_b128 v[184:187], v247 offset:36864
	ds_read_b128 v[188:191], v247 offset:38912
	s_setprio 1
	s_waitcnt lgkmcnt(11)
	v_mfma_f32_16x16x32_bf16 v[94:97], v[142:145], v[126:129], v[94:97]
	s_waitcnt lgkmcnt(10)
	v_mfma_f32_16x16x32_bf16 v[90:93], v[146:149], v[126:129], v[90:93]
	s_waitcnt lgkmcnt(9)
	v_mfma_f32_16x16x32_bf16 v[86:89], v[152:155], v[126:129], v[86:89]
	s_waitcnt lgkmcnt(8)
	v_mfma_f32_16x16x32_bf16 v[82:85], v[156:159], v[126:129], v[82:85]
	v_mfma_f32_16x16x32_bf16 v[78:81], v[142:145], v[130:133], v[78:81]
	v_mfma_f32_16x16x32_bf16 v[74:77], v[146:149], v[130:133], v[74:77]
	v_mfma_f32_16x16x32_bf16 v[70:73], v[152:155], v[130:133], v[70:73]
	v_mfma_f32_16x16x32_bf16 v[66:69], v[156:159], v[130:133], v[66:69]
	v_mfma_f32_16x16x32_bf16 v[62:65], v[142:145], v[134:137], v[62:65]
	v_mfma_f32_16x16x32_bf16 v[58:61], v[146:149], v[134:137], v[58:61]
	v_mfma_f32_16x16x32_bf16 v[54:57], v[152:155], v[134:137], v[54:57]
	v_mfma_f32_16x16x32_bf16 v[50:53], v[156:159], v[134:137], v[50:53]
	v_mfma_f32_16x16x32_bf16 v[46:49], v[142:145], v[138:141], v[46:49]
	v_mfma_f32_16x16x32_bf16 v[42:45], v[146:149], v[138:141], v[42:45]
	v_mfma_f32_16x16x32_bf16 v[38:41], v[152:155], v[138:141], v[38:41]
	v_mfma_f32_16x16x32_bf16 v[34:37], v[156:159], v[138:141], v[34:37]
	s_setprio 0
	s_waitcnt vmcnt(0) lgkmcnt(0)
	s_barrier
; template <int NT>
; __device__ __forceinline__ void gemm_compute(f32x4 (&acc)[4][NT], const bf16_t* sA, const bf16_t* sB, int wr, int wc, int fr, int fq) {
; #pragma unroll
;     for (int ks = 0; ks < 2; ++ks) {
;         bf16x8 a[4], b[NT];
; #pragma unroll
;         for (int mt = 0; mt < 4; ++mt) a[mt] = *(const bf16x8*)(sA + (wr * 64 + mt * 16 + fr) * LDT + ks * 32 + fq * 8);
; #pragma unroll
;         for (int nt = 0; nt < NT; ++nt) b[nt] = *(const bf16x8*)(sB + (wc * 16 * NT + nt * 16 + fr) * LDT + ks * 32 + fq * 8);
;         __builtin_amdgcn_s_setprio(1);
; #pragma unroll
;         for (int mt = 0; mt < 4; ++mt)
; #pragma unroll
;             for (int nt = 0; nt < NT; ++nt)
;                 acc[mt][nt] = __builtin_amdgcn_mfma_f32_16x16x32_bf16(b[nt], a[mt], acc[mt][nt], 0, 0, 0);
;         __builtin_amdgcn_s_setprio(0);
;     }
; template <int NT>
; __device__ __forceinline__ void gemm_tile(f32x4 (&acc)[4][NT], const bf16_t* A, int lda, const bf16_t* B, int ldb, int K, bf16_t* sm) {
;     ...
;     for (int kt = 0; kt < nk; ++kt) {
;         lds_barrier();
; #pragma unroll
;         for (int i = 0; i < 4; ++i) *(u32x4*)(sA + (lrow + 32 * i) * LDT + lkc * 8) = ra0[i];
; #pragma unroll
;         for (int i = 0; i < NT; ++i) *(u32x4*)(sB + sbrow[i] * LDT + lkc * 8) = rb0[i];
;         lds_barrier();
;         if (kt + 1 < nk) {
;             ga += 64; gb += 64;
; #pragma unroll
;             for (int i = 0; i < 4; ++i) ra0[i] = *(const u32x4*)(ga + (size_t)(32 * i) * lda);
; #pragma unroll
;             for (int i = 0; i < NT; ++i) rb0[i] = *(const u32x4*)(gb + (size_t)(32 * i) * ldb);
;         }
;         __builtin_amdgcn_sched_barrier(0);
;         gemm_compute<NT>(acc, sA, sB, wr, wc, fr, fq);
;         __builtin_amdgcn_sched_barrier(0);
;     }
	ds_read_b128 v[126:129], v244 offset:0
	ds_read_b128 v[130:133], v244 offset:2048
	ds_read_b128 v[134:137], v244 offset:4096
	ds_read_b128 v[138:141], v244 offset:6144
	ds_read_b128 v[142:145], v246 offset:0
	ds_read_b128 v[146:149], v246 offset:2048
	ds_read_b128 v[152:155], v246 offset:4096
	ds_read_b128 v[156:159], v246 offset:6144
	s_setprio 1
	v_mfma_f32_16x16x32_bf16 v[94:97], v[176:179], v[160:163], v[94:97]
	s_lshl_b32 s95, s94, 2
	s_add_u32 m0, s95, 0x8000
	s_nop 0
	global_load_lds_dwordx4 v236, s[90:91]
	v_mfma_f32_16x16x32_bf16 v[90:93], v[180:183], v[160:163], v[90:93]
	v_mfma_f32_16x16x32_bf16 v[86:89], v[184:187], v[160:163], v[86:89]
	global_load_lds_dwordx4 v237, s[90:91] offset:1024
	v_mfma_f32_16x16x32_bf16 v[82:85], v[188:191], v[160:163], v[82:85]
	v_mfma_f32_16x16x32_bf16 v[78:81], v[176:179], v[164:167], v[78:81]
	global_load_lds_dwordx4 v238, s[90:91] offset:2048
	v_mfma_f32_16x16x32_bf16 v[74:77], v[180:183], v[164:167], v[74:77]
	v_mfma_f32_16x16x32_bf16 v[70:73], v[184:187], v[164:167], v[70:73]
	global_load_lds_dwordx4 v239, s[90:91] offset:3072
	v_mfma_f32_16x16x32_bf16 v[66:69], v[188:191], v[164:167], v[66:69]
	v_mfma_f32_16x16x32_bf16 v[62:65], v[176:179], v[168:171], v[62:65]
	s_mul_i32 s95, s94, 4
	s_add_u32 m0, s95, 0xc000
	s_nop 0
	global_load_lds_dwordx4 v240, s[92:93]
	v_mfma_f32_16x16x32_bf16 v[58:61], v[180:183], v[168:171], v[58:61]
	v_mfma_f32_16x16x32_bf16 v[54:57], v[184:187], v[168:171], v[54:57]
	global_load_lds_dwordx4 v241, s[92:93] offset:1024
	v_mfma_f32_16x16x32_bf16 v[50:53], v[188:191], v[168:171], v[50:53]
	v_mfma_f32_16x16x32_bf16 v[46:49], v[176:179], v[172:175], v[46:49]
	global_load_lds_dwordx4 v242, s[92:93] offset:2048
	v_mfma_f32_16x16x32_bf16 v[42:45], v[180:183], v[172:175], v[42:45]
	v_mfma_f32_16x16x32_bf16 v[38:41], v[184:187], v[172:175], v[38:41]
	global_load_lds_dwordx4 v243, s[92:93] offset:3072
	v_mfma_f32_16x16x32_bf16 v[34:37], v[188:191], v[172:175], v[34:37]
	s_add_u32 s90, s90, 0x80
	s_addc_u32 s91, s91, 0
	s_add_u32 s92, s92, 0x80
	s_addc_u32 s93, s93, 0
	s_setprio 0
	v_readlane_b32 s95, v234, 6
	s_add_i32 s95, s95, -1
	s_cmp_lg_u32 s95, 0
	s_cbranch_scc1 .Lgemm_k36
.Lgemm_x36:
	ds_read_b128 v[160:163], v245 offset:0
	ds_read_b128 v[164:167], v245 offset:2048
	ds_read_b128 v[168:171], v245 offset:4096
	ds_read_b128 v[172:175], v245 offset:6144
	ds_read_b128 v[176:179], v247 offset:0
	ds_read_b128 v[180:183], v247 offset:2048
	ds_read_b128 v[184:187], v247 offset:4096
	ds_read_b128 v[188:191], v247 offset:6144
	s_setprio 1
	s_waitcnt lgkmcnt(11)
	v_mfma_f32_16x16x32_bf16 v[94:97], v[142:145], v[126:129], v[94:97]
	s_waitcnt lgkmcnt(10)
	v_mfma_f32_16x16x32_bf16 v[90:93], v[146:149], v[126:129], v[90:93]
	s_waitcnt lgkmcnt(9)
	v_mfma_f32_16x16x32_bf16 v[86:89], v[152:155], v[126:129], v[86:89]
	s_waitcnt lgkmcnt(8)
	v_mfma_f32_16x16x32_bf16 v[82:85], v[156:159], v[126:129], v[82:85]
	v_mfma_f32_16x16x32_bf16 v[78:81], v[142:145], v[130:133], v[78:81]
	v_mfma_f32_16x16x32_bf16 v[74:77], v[146:149], v[130:133], v[74:77]
	v_mfma_f32_16x16x32_bf16 v[70:73], v[152:155], v[130:133], v[70:73]
	v_mfma_f32_16x16x32_bf16 v[66:69], v[156:159], v[130:133], v[66:69]
	v_mfma_f32_16x16x32_bf16 v[62:65], v[142:145], v[134:137], v[62:65]
	v_mfma_f32_16x16x32_bf16 v[58:61], v[146:149], v[134:137], v[58:61]
	v_mfma_f32_16x16x32_bf16 v[54:57], v[152:155], v[134:137], v[54:57]
	v_mfma_f32_16x16x32_bf16 v[50:53], v[156:159], v[134:137], v[50:53]
	v_mfma_f32_16x16x32_bf16 v[46:49], v[142:145], v[138:141], v[46:49]
	v_mfma_f32_16x16x32_bf16 v[42:45], v[146:149], v[138:141], v[42:45]
	v_mfma_f32_16x16x32_bf16 v[38:41], v[152:155], v[138:141], v[38:41]
	v_mfma_f32_16x16x32_bf16 v[34:37], v[156:159], v[138:141], v[34:37]
	s_setprio 0
	s_waitcnt vmcnt(0) lgkmcnt(0)
	s_barrier
	ds_read_b128 v[126:129], v244 offset:32768
	ds_read_b128 v[130:133], v244 offset:34816
	ds_read_b128 v[134:137], v244 offset:36864
	ds_read_b128 v[138:141], v244 offset:38912
	ds_read_b128 v[142:145], v246 offset:32768
	ds_read_b128 v[146:149], v246 offset:34816
	ds_read_b128 v[152:155], v246 offset:36864
	ds_read_b128 v[156:159], v246 offset:38912
	s_setprio 1
	v_mfma_f32_16x16x32_bf16 v[94:97], v[176:179], v[160:163], v[94:97]
	s_lshl_b32 s95, s94, 2
	s_add_u32 m0, s95, 0x0
	s_nop 0
	global_load_lds_dwordx4 v236, s[90:91]
	v_mfma_f32_16x16x32_bf16 v[90:93], v[180:183], v[160:163], v[90:93]
	v_mfma_f32_16x16x32_bf16 v[86:89], v[184:187], v[160:163], v[86:89]
	global_load_lds_dwordx4 v237, s[90:91] offset:1024
	v_mfma_f32_16x16x32_bf16 v[82:85], v[188:191], v[160:163], v[82:85]
	v_mfma_f32_16x16x32_bf16 v[78:81], v[176:179], v[164:167], v[78:81]
	global_load_lds_dwordx4 v238, s[90:91] offset:2048
	v_mfma_f32_16x16x32_bf16 v[74:77], v[180:183], v[164:167], v[74:77]
	v_mfma_f32_16x16x32_bf16 v[70:73], v[184:187], v[164:167], v[70:73]
	global_load_lds_dwordx4 v239, s[90:91] offset:3072
	v_mfma_f32_16x16x32_bf16 v[66:69], v[188:191], v[164:167], v[66:69]
	v_mfma_f32_16x16x32_bf16 v[62:65], v[176:179], v[168:171], v[62:65]
	s_mul_i32 s95, s94, 4
	s_add_u32 m0, s95, 0x4000
	s_nop 0
	global_load_lds_dwordx4 v240, s[92:93]
	v_mfma_f32_16x16x32_bf16 v[58:61], v[180:183], v[168:171], v[58:61]
	v_mfma_f32_16x16x32_bf16 v[54:57], v[184:187], v[168:171], v[54:57]
	global_load_lds_dwordx4 v241, s[92:93] offset:1024
	v_mfma_f32_16x16x32_bf16 v[50:53], v[188:191], v[168:171], v[50:53]
	v_mfma_f32_16x16x32_bf16 v[46:49], v[176:179], v[172:175], v[46:49]
	global_load_lds_dwordx4 v242, s[92:93] offset:2048
	v_mfma_f32_16x16x32_bf16 v[42:45], v[180:183], v[172:175], v[42:45]
	v_mfma_f32_16x16x32_bf16 v[38:41], v[184:187], v[172:175], v[38:41]
	global_load_lds_dwordx4 v243, s[92:93] offset:3072
	v_mfma_f32_16x16x32_bf16 v[34:37], v[188:191], v[172:175], v[34:37]
	s_add_u32 s90, s90, 0x80
	s_addc_u32 s91, s91, 0
	s_add_u32 s92, s92, 0x80
	s_addc_u32 s93, s93, 0
	s_setprio 0
	ds_read_b128 v[160:163], v245 offset:32768
	ds_read_b128 v[164:167], v245 offset:34816
	ds_read_b128 v[168:171], v245 offset:36864
	ds_read_b128 v[172:175], v245 offset:38912
	ds_read_b128 v[176:179], v247 offset:32768
	ds_read_b128 v[180:183], v247 offset:34816
	ds_read_b128 v[184:187], v247 offset:36864
	ds_read_b128 v[188:191], v247 offset:38912
	s_setprio 1
	s_waitcnt lgkmcnt(11)
; template <int NT>
; __device__ __forceinline__ void gemm_compute(f32x4 (&acc)[4][NT], const bf16_t* sA, const bf16_t* sB, int wr, int wc, int fr, int fq) {
; #pragma unroll
;     for (int ks = 0; ks < 2; ++ks) {
;         bf16x8 a[4], b[NT];
; #pragma unroll
;         for (int mt = 0; mt < 4; ++mt) a[mt] = *(const bf16x8*)(sA + (wr * 64 + mt * 16 + fr) * LDT + ks * 32 + fq * 8);
; #pragma unroll
;         for (int nt = 0; nt < NT; ++nt) b[nt] = *(const bf16x8*)(sB + (wc * 16 * NT + nt * 16 + fr) * LDT + ks * 32 + fq * 8);
;         __builtin_amdgcn_s_setprio(1);
; #pragma unroll
;         for (int mt = 0; mt < 4; ++mt)
; #pragma unroll
;             for (int nt = 0; nt < NT; ++nt)
;                 acc[mt][nt] = __builtin_amdgcn_mfma_f32_16x16x32_bf16(b[nt], a[mt], acc[mt][nt], 0, 0, 0);
;         __builtin_amdgcn_s_setprio(0);
;     }
; template <int NT>
; __device__ __forceinline__ void gemm_tile(f32x4 (&acc)[4][NT], const bf16_t* A, int lda, const bf16_t* B, int ldb, int K, bf16_t* sm) {
;     ...
;     for (int kt = 0; kt < nk; ++kt) {
;         lds_barrier();
; #pragma unroll
;         for (int i = 0; i < 4; ++i) *(u32x4*)(sA + (lrow + 32 * i) * LDT + lkc * 8) = ra0[i];
; #pragma unroll
;         for (int i = 0; i < NT; ++i) *(u32x4*)(sB + sbrow[i] * LDT + lkc * 8) = rb0[i];
;         lds_barrier();
;         if (kt + 1 < nk) {
;             ga += 64; gb += 64;
; #pragma unroll
;             for (int i = 0; i < 4; ++i) ra0[i] = *(const u32x4*)(ga + (size_t)(32 * i) * lda);
; #pragma unroll
;             for (int i = 0; i < NT; ++i) rb0[i] = *(const u32x4*)(gb + (size_t)(32 * i) * ldb);
;         }
;         __builtin_amdgcn_sched_barrier(0);
;         gemm_compute<NT>(acc, sA, sB, wr, wc, fr, fq);
;         __builtin_amdgcn_sched_barrier(0);
;     }
	v_mfma_f32_16x16x32_bf16 v[94:97], v[142:145], v[126:129], v[94:97]
	s_waitcnt lgkmcnt(10)
	v_mfma_f32_16x16x32_bf16 v[90:93], v[146:149], v[126:129], v[90:93]
	s_waitcnt lgkmcnt(9)
	v_mfma_f32_16x16x32_bf16 v[86:89], v[152:155], v[126:129], v[86:89]
	s_waitcnt lgkmcnt(8)
	v_mfma_f32_16x16x32_bf16 v[82:85], v[156:159], v[126:129], v[82:85]
	v_mfma_f32_16x16x32_bf16 v[78:81], v[142:145], v[130:133], v[78:81]
	v_mfma_f32_16x16x32_bf16 v[74:77], v[146:149], v[130:133], v[74:77]
	v_mfma_f32_16x16x32_bf16 v[70:73], v[152:155], v[130:133], v[70:73]
	v_mfma_f32_16x16x32_bf16 v[66:69], v[156:159], v[130:133], v[66:69]
	v_mfma_f32_16x16x32_bf16 v[62:65], v[142:145], v[134:137], v[62:65]
	v_mfma_f32_16x16x32_bf16 v[58:61], v[146:149], v[134:137], v[58:61]
	v_mfma_f32_16x16x32_bf16 v[54:57], v[152:155], v[134:137], v[54:57]
	v_mfma_f32_16x16x32_bf16 v[50:53], v[156:159], v[134:137], v[50:53]
	v_mfma_f32_16x16x32_bf16 v[46:49], v[142:145], v[138:141], v[46:49]
	v_mfma_f32_16x16x32_bf16 v[42:45], v[146:149], v[138:141], v[42:45]
	v_mfma_f32_16x16x32_bf16 v[38:41], v[152:155], v[138:141], v[38:41]
	v_mfma_f32_16x16x32_bf16 v[34:37], v[156:159], v[138:141], v[34:37]
	s_setprio 0
	s_waitcnt vmcnt(0) lgkmcnt(0)
	s_barrier
	ds_read_b128 v[126:129], v244 offset:0
	ds_read_b128 v[130:133], v244 offset:2048
	ds_read_b128 v[134:137], v244 offset:4096
	ds_read_b128 v[138:141], v244 offset:6144
	ds_read_b128 v[142:145], v246 offset:0
	ds_read_b128 v[146:149], v246 offset:2048
	ds_read_b128 v[152:155], v246 offset:4096
	ds_read_b128 v[156:159], v246 offset:6144
	s_setprio 1
	v_mfma_f32_16x16x32_bf16 v[94:97], v[176:179], v[160:163], v[94:97]
	s_lshl_b32 s92, s96, 1
	s_sub_u32 s92, s92, 0x100
	s_mov_b32 s93, 0
	v_lshl_add_u64 v[102:103], v[102:103], 0, s[92:93]
	v_lshl_add_u64 v[104:105], v[104:105], 0, s[92:93]
	v_lshl_add_u64 v[106:107], v[106:107], 0, s[92:93]
	v_lshl_add_u64 v[108:109], v[108:109], 0, s[92:93]
	v_lshl_add_u64 v[110:111], v[110:111], 0, s[92:93]
	v_lshl_add_u64 v[112:113], v[112:113], 0, s[92:93]
	v_lshl_add_u64 v[114:115], v[114:115], 0, s[92:93]
	v_lshl_add_u64 v[116:117], v[116:117], 0, s[92:93]
	v_readlane_b32 s90, v234, 0
	v_readlane_b32 s91, v234, 1
	v_readlane_b32 s92, v234, 2
	v_readlane_b32 s93, v234, 3
	v_readlane_b32 s94, v234, 4
	v_readlane_b32 s95, v234, 5
	s_mov_b32 s19, 0
	s_nop 3
	v_mfma_f32_16x16x32_bf16 v[90:93], v[180:183], v[160:163], v[90:93]
	v_mfma_f32_16x16x32_bf16 v[86:89], v[184:187], v[160:163], v[86:89]
	v_lshl_add_u64 v[0:1], v[108:109], 0, v[100:101]
	v_mfma_f32_16x16x32_bf16 v[82:85], v[188:191], v[160:163], v[82:85]
	v_mfma_f32_16x16x32_bf16 v[78:81], v[176:179], v[164:167], v[78:81]
	global_load_dwordx4 v[30:33], v[0:1], off
	v_mfma_f32_16x16x32_bf16 v[74:77], v[180:183], v[164:167], v[74:77]
	v_mfma_f32_16x16x32_bf16 v[70:73], v[184:187], v[164:167], v[70:73]
	v_lshl_add_u64 v[0:1], v[106:107], 0, v[100:101]
	v_mfma_f32_16x16x32_bf16 v[66:69], v[188:191], v[164:167], v[66:69]
	v_mfma_f32_16x16x32_bf16 v[62:65], v[176:179], v[168:171], v[62:65]
	global_load_dwordx4 v[22:25], v[0:1], off
	v_mfma_f32_16x16x32_bf16 v[58:61], v[180:183], v[168:171], v[58:61]
	v_mfma_f32_16x16x32_bf16 v[54:57], v[184:187], v[168:171], v[54:57]
	v_lshl_add_u64 v[0:1], v[104:105], 0, v[100:101]
	v_mfma_f32_16x16x32_bf16 v[50:53], v[188:191], v[168:171], v[50:53]
	v_mfma_f32_16x16x32_bf16 v[46:49], v[176:179], v[172:175], v[46:49]
	global_load_dwordx4 v[18:21], v[0:1], off
	v_mfma_f32_16x16x32_bf16 v[42:45], v[180:183], v[172:175], v[42:45]
	v_mfma_f32_16x16x32_bf16 v[38:41], v[184:187], v[172:175], v[38:41]
	v_lshl_add_u64 v[0:1], v[102:103], 0, v[100:101]
	v_mfma_f32_16x16x32_bf16 v[34:37], v[188:191], v[172:175], v[34:37]
	global_load_dwordx4 v[26:29], v[0:1], off
	v_lshl_add_u64 v[0:1], v[116:117], 0, v[100:101]
	global_load_dwordx4 v[8:11], v[0:1], off
	v_lshl_add_u64 v[0:1], v[114:115], 0, v[100:101]
	v_lshl_add_u64 v[4:5], v[112:113], 0, v[100:101]
	v_lshl_add_u64 v[14:15], v[110:111], 0, v[100:101]
	global_load_dwordx4 v[0:3], v[0:1], off
	s_nop 0
	global_load_dwordx4 v[4:7], v[4:5], off
	s_nop 0
	global_load_dwordx4 v[14:17], v[14:15], off
	s_setprio 0
	ds_read_b128 v[160:163], v245 offset:0
	ds_read_b128 v[164:167], v245 offset:2048
	ds_read_b128 v[168:171], v245 offset:4096
	ds_read_b128 v[172:175], v245 offset:6144
	ds_read_b128 v[176:179], v247 offset:0
	ds_read_b128 v[180:183], v247 offset:2048
	ds_read_b128 v[184:187], v247 offset:4096
	ds_read_b128 v[188:191], v247 offset:6144
	s_setprio 1
	s_waitcnt lgkmcnt(11)
	v_mfma_f32_16x16x32_bf16 v[94:97], v[142:145], v[126:129], v[94:97]
	s_waitcnt lgkmcnt(10)
	v_mfma_f32_16x16x32_bf16 v[90:93], v[146:149], v[126:129], v[90:93]
	s_waitcnt lgkmcnt(9)
	v_mfma_f32_16x16x32_bf16 v[86:89], v[152:155], v[126:129], v[86:89]
	s_waitcnt lgkmcnt(8)
	v_mfma_f32_16x16x32_bf16 v[82:85], v[156:159], v[126:129], v[82:85]
	v_mfma_f32_16x16x32_bf16 v[78:81], v[142:145], v[130:133], v[78:81]
	v_mfma_f32_16x16x32_bf16 v[74:77], v[146:149], v[130:133], v[74:77]
	v_mfma_f32_16x16x32_bf16 v[70:73], v[152:155], v[130:133], v[70:73]
	v_mfma_f32_16x16x32_bf16 v[66:69], v[156:159], v[130:133], v[66:69]
	v_mfma_f32_16x16x32_bf16 v[62:65], v[142:145], v[134:137], v[62:65]
	v_mfma_f32_16x16x32_bf16 v[58:61], v[146:149], v[134:137], v[58:61]
	v_mfma_f32_16x16x32_bf16 v[54:57], v[152:155], v[134:137], v[54:57]
	v_mfma_f32_16x16x32_bf16 v[50:53], v[156:159], v[134:137], v[50:53]
	v_mfma_f32_16x16x32_bf16 v[46:49], v[142:145], v[138:141], v[46:49]
	v_mfma_f32_16x16x32_bf16 v[42:45], v[146:149], v[138:141], v[42:45]
	v_mfma_f32_16x16x32_bf16 v[38:41], v[152:155], v[138:141], v[38:41]
	v_mfma_f32_16x16x32_bf16 v[34:37], v[156:159], v[138:141], v[34:37]
	s_setprio 0
	s_waitcnt lgkmcnt(0)
	s_setprio 1
	v_mfma_f32_16x16x32_bf16 v[94:97], v[176:179], v[160:163], v[94:97]
	v_mfma_f32_16x16x32_bf16 v[90:93], v[180:183], v[160:163], v[90:93]
	v_mfma_f32_16x16x32_bf16 v[86:89], v[184:187], v[160:163], v[86:89]
	v_mfma_f32_16x16x32_bf16 v[82:85], v[188:191], v[160:163], v[82:85]
	v_mfma_f32_16x16x32_bf16 v[78:81], v[176:179], v[164:167], v[78:81]
	v_mfma_f32_16x16x32_bf16 v[74:77], v[180:183], v[164:167], v[74:77]
	v_mfma_f32_16x16x32_bf16 v[70:73], v[184:187], v[164:167], v[70:73]
	v_mfma_f32_16x16x32_bf16 v[66:69], v[188:191], v[164:167], v[66:69]
	v_mfma_f32_16x16x32_bf16 v[62:65], v[176:179], v[168:171], v[62:65]
	v_mfma_f32_16x16x32_bf16 v[58:61], v[180:183], v[168:171], v[58:61]
	v_mfma_f32_16x16x32_bf16 v[54:57], v[184:187], v[168:171], v[54:57]
	v_mfma_f32_16x16x32_bf16 v[50:53], v[188:191], v[168:171], v[50:53]
	v_mfma_f32_16x16x32_bf16 v[46:49], v[176:179], v[172:175], v[46:49]
	v_mfma_f32_16x16x32_bf16 v[42:45], v[180:183], v[172:175], v[42:45]
	v_mfma_f32_16x16x32_bf16 v[38:41], v[184:187], v[172:175], v[38:41]
	v_mfma_f32_16x16x32_bf16 v[34:37], v[188:191], v[172:175], v[34:37]
	s_setprio 0
	s_waitcnt lgkmcnt(0)
	s_barrier
; template <int NT>
; __device__ __forceinline__ void gemm_tile(f32x4 (&acc)[4][NT], const bf16_t* A, int lda, const bf16_t* B, int ldb, int K, bf16_t* sm) {
;     ...
;         lds_barrier();
; #pragma unroll
;         for (int i = 0; i < 4; ++i) *(u32x4*)(sA + (lrow + 32 * i) * LDT + lkc * 8) = ra0[i];
; #pragma unroll
;         for (int i = 0; i < NT; ++i) *(u32x4*)(sB + sbrow[i] * LDT + lkc * 8) = rb0[i];
;         lds_barrier();
;         if (kt + 1 < nk) {
;             ga += 64; gb += 64;
; #pragma unroll
;             for (int i = 0; i < 4; ++i) ra0[i] = *(const u32x4*)(ga + (size_t)(32 * i) * lda);
; #pragma unroll
;             for (int i = 0; i < NT; ++i) rb0[i] = *(const u32x4*)(gb + (size_t)(32 * i) * ldb);
;         }
;         __builtin_amdgcn_sched_barrier(0);
;         gemm_compute<NT>(acc, sA, sB, wr, wc, fr, fq);
; template <int NT>
; __device__ __forceinline__ void resid_tile(int tm, int col0, const bf16_t* A, int lda, int K, const bf16_t* W, const float* X, float* Y, float scale, bf16_t* sm) {
;     ...
; #pragma unroll
;     for (int mt = 0; mt < 4; ++mt) {
;         const int row = tm * 128 + wr * 64 + mt * 16 + fr;
;         const int cbase = col0 + wc * 16 * NT + fq * 4 * NT;
;         const size_t o = (size_t)row * 1024 + cbase;
;         float v[4 * NT]; gather_cols<NT>(acc, mt, v);
;         float4 xv[NT];
; #pragma unroll
;         for (int q = 0; q < NT; ++q) xv[q] = *(const float4*)(X + o + 4 * q);
; #pragma unroll
;         for (int q = 0; q < NT; ++q)
;             *(float4*)(Y + o + 4 * q) = make_float4(ALPHA * xv[q].x + scale * v[4 * q], ALPHA * xv[q].y + scale * v[4 * q + 1],
;                                                     ALPHA * xv[q].z + scale * v[4 * q + 2], ALPHA * xv[q].w + scale * v[4 * q + 3]);
;     }
	s_waitcnt vmcnt(7)
	ds_write_b128 v120, v[30:33]
	s_waitcnt vmcnt(6)
	ds_write_b128 v120, v[22:25] offset:5120
	s_waitcnt vmcnt(5)
	ds_write_b128 v120, v[18:21] offset:10240
	s_waitcnt vmcnt(4)
	ds_write_b128 v120, v[26:29] offset:15360
	s_waitcnt vmcnt(3)
	ds_write_b128 v121, v[8:11] offset:20480
	s_waitcnt vmcnt(2)
	ds_write_b128 v122, v[0:3] offset:20480
	s_waitcnt vmcnt(1)
	ds_write_b128 v123, v[4:7] offset:20480
	s_waitcnt vmcnt(0)
	ds_write_b128 v124, v[14:17] offset:20480
	s_waitcnt lgkmcnt(0)
	s_barrier
	ds_read_b128 v[0:3], v119
	ds_read_b128 v[4:7], v119 offset:2560
	ds_read_b128 v[8:11], v119 offset:5120
	ds_read_b128 v[14:17], v119 offset:7680
	ds_read_b128 v[18:21], v12 offset:20480
	ds_read_b128 v[22:25], v12 offset:23040
	ds_read_b128 v[26:29], v12 offset:25600
	ds_read_b128 v[30:33], v12 offset:28160
	s_setprio 1
	s_waitcnt lgkmcnt(3)
	v_mfma_f32_16x16x32_bf16 v[94:97], v[18:21], v[0:3], v[94:97]
	s_waitcnt lgkmcnt(2)
	v_mfma_f32_16x16x32_bf16 v[90:93], v[22:25], v[0:3], v[90:93]
	s_waitcnt lgkmcnt(1)
	v_mfma_f32_16x16x32_bf16 v[86:89], v[26:29], v[0:3], v[86:89]
	s_waitcnt lgkmcnt(0)
	v_mfma_f32_16x16x32_bf16 v[0:3], v[30:33], v[0:3], v[82:85]
	v_mfma_f32_16x16x32_bf16 v[78:81], v[18:21], v[4:7], v[78:81]
	v_mfma_f32_16x16x32_bf16 v[74:77], v[22:25], v[4:7], v[74:77]
	v_mfma_f32_16x16x32_bf16 v[70:73], v[26:29], v[4:7], v[70:73]
	v_mfma_f32_16x16x32_bf16 v[4:7], v[30:33], v[4:7], v[66:69]
	v_mfma_f32_16x16x32_bf16 v[62:65], v[18:21], v[8:11], v[62:65]
	v_mfma_f32_16x16x32_bf16 v[58:61], v[22:25], v[8:11], v[58:61]
	v_mfma_f32_16x16x32_bf16 v[54:57], v[26:29], v[8:11], v[54:57]
	v_mfma_f32_16x16x32_bf16 v[8:11], v[30:33], v[8:11], v[50:53]
	v_mfma_f32_16x16x32_bf16 v[50:53], v[18:21], v[14:17], v[46:49]
	v_mfma_f32_16x16x32_bf16 v[66:69], v[22:25], v[14:17], v[42:45]
	v_mfma_f32_16x16x32_bf16 v[82:85], v[26:29], v[14:17], v[38:41]
	v_mfma_f32_16x16x32_bf16 v[100:103], v[30:33], v[14:17], v[34:37]
	s_setprio 0
	ds_read_b128 v[14:17], v119 offset:64
	ds_read_b128 v[18:21], v119 offset:2624
	ds_read_b128 v[22:25], v119 offset:5184
	ds_read_b128 v[104:107], v119 offset:7744
	ds_read_b128 v[108:111], v12 offset:20544
	ds_read_b128 v[112:115], v12 offset:23104
	ds_read_b128 v[120:123], v12 offset:25664
	ds_read_b128 v[124:127], v12 offset:28224
	s_setprio 1
	s_waitcnt lgkmcnt(3)
	v_mfma_f32_16x16x32_bf16 v[94:97], v[108:111], v[14:17], v[94:97]
	s_waitcnt lgkmcnt(2)
	v_mfma_f32_16x16x32_bf16 v[90:93], v[112:115], v[14:17], v[90:93]
	s_waitcnt lgkmcnt(1)
	v_mfma_f32_16x16x32_bf16 v[86:89], v[120:123], v[14:17], v[86:89]
	s_waitcnt lgkmcnt(0)
	v_mfma_f32_16x16x32_bf16 v[128:131], v[124:127], v[14:17], v[0:3]
	v_mfma_f32_16x16x32_bf16 v[42:45], v[108:111], v[18:21], v[78:81]
	v_mfma_f32_16x16x32_bf16 v[46:49], v[112:115], v[18:21], v[74:77]
	v_mfma_f32_16x16x32_bf16 v[34:37], v[120:123], v[18:21], v[70:73]
	v_mfma_f32_16x16x32_bf16 v[38:41], v[124:127], v[18:21], v[4:7]
	v_mfma_f32_16x16x32_bf16 v[26:29], v[108:111], v[22:25], v[62:65]
	v_mfma_f32_16x16x32_bf16 v[30:33], v[112:115], v[22:25], v[58:61]
	v_mfma_f32_16x16x32_bf16 v[18:21], v[120:123], v[22:25], v[54:57]
	v_mfma_f32_16x16x32_bf16 v[22:25], v[124:127], v[22:25], v[8:11]
	v_mfma_f32_16x16x32_bf16 v[8:11], v[108:111], v[104:107], v[50:53]
	v_mfma_f32_16x16x32_bf16 v[14:17], v[112:115], v[104:107], v[66:69]
	v_mfma_f32_16x16x32_bf16 v[0:3], v[120:123], v[104:107], v[82:85]
	v_mfma_f32_16x16x32_bf16 v[4:7], v[124:127], v[104:107], v[100:103]
	s_setprio 0
	v_ashrrev_i32_e32 v12, 1, v118
	v_and_b32_e32 v12, 0xffffffc0, v12
	v_lshl_add_u32 v12, s18, 7, v12
	v_and_or_b32 v50, v118, 15, v12
	v_and_b32_e32 v12, 0x70, v118
	v_or_b32_e32 v12, s2, v12
	v_ashrrev_i32_e32 v51, 31, v50
	v_lshlrev_b64 v[52:53], 12, v[50:51]
	v_lshlrev_b32_e32 v12, 2, v12
	v_or_b32_e32 v52, v52, v12
	v_lshl_add_u64 v[64:65], s[56:57], 0, v[52:53]
	v_lshl_add_u64 v[68:69], s[90:91], 0, v[52:53]
	global_load_dwordx4 v[52:55], v[64:65], off offset:48
	global_load_dwordx4 v[56:59], v[64:65], off offset:32
	global_load_dwordx4 v[60:63], v[64:65], off offset:16
	s_nop 0
	global_load_dwordx4 v[64:67], v[64:65], off
	v_mov_b32_e32 v70, v94
	v_mov_b32_e32 v71, v90
	v_mov_b32_e32 v90, v95
	s_add_i32 s39, s39, s62
	s_cmp_ge_i32 s39, s1
	s_waitcnt vmcnt(3)
	v_pk_mul_f32 v[52:53], v[52:53], s[88:89] op_sel_hi:[1,0]
	s_waitcnt vmcnt(2)
	v_pk_mul_f32 v[56:57], v[56:57], s[88:89] op_sel_hi:[1,0]
	s_waitcnt vmcnt(1)
	v_pk_mul_f32 v[60:61], v[60:61], s[88:89] op_sel_hi:[1,0]
	s_waitcnt vmcnt(0)
	v_pk_mul_f32 v[64:65], v[64:65], s[88:89] op_sel_hi:[1,0]
	v_pk_mul_f32 v[66:67], v[66:67], s[88:89] op_sel_hi:[1,0]
	v_pk_fma_f32 v[64:65], v[98:99], v[70:71], v[64:65]
	v_mov_b32_e32 v70, v86
	v_mov_b32_e32 v71, v128
	v_pk_fma_f32 v[66:67], v[98:99], v[70:71], v[66:67]
	v_mov_b32_e32 v70, v96
	v_mov_b32_e32 v71, v92
	v_mov_b32_e32 v92, v97
	v_pk_mul_f32 v[62:63], v[62:63], s[88:89] op_sel_hi:[1,0]
	v_mov_b32_e32 v128, v87
	v_pk_fma_f32 v[56:57], v[98:99], v[70:71], v[56:57]
	v_pk_mul_f32 v[58:59], v[58:59], s[88:89] op_sel_hi:[1,0]
	v_mov_b32_e32 v70, v88
	v_mov_b32_e32 v71, v130
	v_pk_fma_f32 v[52:53], v[98:99], v[92:93], v[52:53]
	v_pk_mul_f32 v[54:55], v[54:55], s[88:89] op_sel_hi:[1,0]
	v_mov_b32_e32 v130, v89
	v_pk_fma_f32 v[60:61], v[98:99], v[90:91], v[60:61]
	v_pk_fma_f32 v[62:63], v[98:99], v[128:129], v[62:63]
	v_pk_fma_f32 v[58:59], v[98:99], v[70:71], v[58:59]
	v_pk_fma_f32 v[54:55], v[98:99], v[130:131], v[54:55]
	global_store_dwordx4 v[68:69], v[64:67], off
	global_store_dwordx4 v[68:69], v[60:63], off offset:16
	global_store_dwordx4 v[68:69], v[56:59], off offset:32
	global_store_dwordx4 v[68:69], v[52:55], off offset:48
	v_mov_b32_e32 v70, v42
	v_mov_b32_e32 v71, v46
	v_or_b32_e32 v52, 16, v50
	v_ashrrev_i32_e32 v53, 31, v52
	v_lshlrev_b64 v[52:53], 12, v[52:53]
	v_or_b32_e32 v52, v52, v12
	v_lshl_add_u64 v[64:65], s[56:57], 0, v[52:53]
	v_lshl_add_u64 v[68:69], s[90:91], 0, v[52:53]
	global_load_dwordx4 v[52:55], v[64:65], off offset:48
	global_load_dwordx4 v[56:59], v[64:65], off offset:32
	global_load_dwordx4 v[60:63], v[64:65], off offset:16
	s_nop 0
	global_load_dwordx4 v[64:67], v[64:65], off
	v_mov_b32_e32 v46, v43
	s_waitcnt vmcnt(1)
; template <int NT>
; __device__ __forceinline__ void resid_tile(int tm, int col0, const bf16_t* A, int lda, int K, const bf16_t* W, const float* X, float* Y, float scale, bf16_t* sm) {
;     ...
; #pragma unroll
;     for (int mt = 0; mt < 4; ++mt) {
;         const int row = tm * 128 + wr * 64 + mt * 16 + fr;
;         const int cbase = col0 + wc * 16 * NT + fq * 4 * NT;
;         const size_t o = (size_t)row * 1024 + cbase;
;         float v[4 * NT]; gather_cols<NT>(acc, mt, v);
;         float4 xv[NT];
; #pragma unroll
;         for (int q = 0; q < NT; ++q) xv[q] = *(const float4*)(X + o + 4 * q);
; #pragma unroll
;         for (int q = 0; q < NT; ++q)
;             *(float4*)(Y + o + 4 * q) = make_float4(ALPHA * xv[q].x + scale * v[4 * q], ALPHA * xv[q].y + scale * v[4 * q + 1],
;                                                     ALPHA * xv[q].z + scale * v[4 * q + 2], ALPHA * xv[q].w + scale * v[4 * q + 3]);
;     }
; }
; __device__ __forceinline__ void phase_gemm_resid(const bf16_t* A, int lda, int K, const bf16_t* W, const float* X, float* Y, float scale, bf16_t* sm) {
;     const int G = gridDim.x, NTILES = 136 * 8;
;     const int nfull = (NTILES / G) * G;
;     for (int t = blockIdx.x; t < nfull; t += G) resid_tile<4>(t >> 3, (t & 7) * 128, A, lda, K, W, X, Y, scale, sm);
	v_pk_mul_f32 v[42:43], v[62:63], s[88:89] op_sel_hi:[1,0]
	s_waitcnt vmcnt(0)
	v_pk_mul_f32 v[64:65], v[64:65], s[88:89] op_sel_hi:[1,0]
	v_pk_mul_f32 v[66:67], v[66:67], s[88:89] op_sel_hi:[1,0]
	v_pk_fma_f32 v[64:65], v[98:99], v[70:71], v[64:65]
	v_mov_b32_e32 v71, v38
	v_mov_b32_e32 v38, v35
	v_mov_b32_e32 v70, v34
	v_pk_fma_f32 v[62:63], v[98:99], v[38:39], v[42:43]
	v_pk_mul_f32 v[34:35], v[56:57], s[88:89] op_sel_hi:[1,0]
	v_mov_b32_e32 v38, v44
	v_mov_b32_e32 v39, v48
	v_pk_fma_f32 v[56:57], v[98:99], v[38:39], v[34:35]
	v_pk_mul_f32 v[34:35], v[58:59], s[88:89] op_sel_hi:[1,0]
	v_mov_b32_e32 v38, v36
	v_mov_b32_e32 v39, v40
	v_pk_fma_f32 v[58:59], v[98:99], v[38:39], v[34:35]
	v_pk_mul_f32 v[34:35], v[52:53], s[88:89] op_sel_hi:[1,0]
	v_mov_b32_e32 v48, v45
	v_pk_fma_f32 v[66:67], v[98:99], v[70:71], v[66:67]
	v_pk_mul_f32 v[60:61], v[60:61], s[88:89] op_sel_hi:[1,0]
	v_pk_fma_f32 v[34:35], v[98:99], v[48:49], v[34:35]
	v_pk_mul_f32 v[38:39], v[54:55], s[88:89] op_sel_hi:[1,0]
	v_mov_b32_e32 v40, v37
	v_pk_fma_f32 v[60:61], v[98:99], v[46:47], v[60:61]
	v_pk_fma_f32 v[36:37], v[98:99], v[40:41], v[38:39]
	global_store_dwordx4 v[68:69], v[64:67], off
	global_store_dwordx4 v[68:69], v[60:63], off offset:16
	global_store_dwordx4 v[68:69], v[56:59], off offset:32
	global_store_dwordx4 v[68:69], v[34:37], off offset:48
	v_mov_b32_e32 v54, v26
	v_mov_b32_e32 v55, v30
	v_or_b32_e32 v34, 32, v50
	v_ashrrev_i32_e32 v35, 31, v34
	v_lshlrev_b64 v[34:35], 12, v[34:35]
	v_or_b32_e32 v34, v34, v12
	v_lshl_add_u64 v[46:47], s[56:57], 0, v[34:35]
	v_lshl_add_u64 v[52:53], s[90:91], 0, v[34:35]
	global_load_dwordx4 v[34:37], v[46:47], off offset:48
	global_load_dwordx4 v[38:41], v[46:47], off offset:32
	global_load_dwordx4 v[42:45], v[46:47], off offset:16
	s_nop 0
	global_load_dwordx4 v[46:49], v[46:47], off
	v_mov_b32_e32 v30, v27
	s_waitcnt vmcnt(1)
	v_pk_mul_f32 v[26:27], v[44:45], s[88:89] op_sel_hi:[1,0]
	s_waitcnt vmcnt(0)
	v_pk_mul_f32 v[46:47], v[46:47], s[88:89] op_sel_hi:[1,0]
	v_pk_mul_f32 v[48:49], v[48:49], s[88:89] op_sel_hi:[1,0]
	v_pk_fma_f32 v[46:47], v[98:99], v[54:55], v[46:47]
	v_mov_b32_e32 v55, v22
	v_mov_b32_e32 v22, v19
	v_mov_b32_e32 v54, v18
	v_pk_fma_f32 v[44:45], v[98:99], v[22:23], v[26:27]
	v_pk_mul_f32 v[18:19], v[38:39], s[88:89] op_sel_hi:[1,0]
	v_mov_b32_e32 v22, v28
	v_mov_b32_e32 v23, v32
	v_pk_fma_f32 v[38:39], v[98:99], v[22:23], v[18:19]
	v_pk_mul_f32 v[18:19], v[40:41], s[88:89] op_sel_hi:[1,0]
	v_mov_b32_e32 v22, v20
	v_mov_b32_e32 v23, v24
	v_pk_fma_f32 v[40:41], v[98:99], v[22:23], v[18:19]
	v_pk_mul_f32 v[18:19], v[34:35], s[88:89] op_sel_hi:[1,0]
	v_mov_b32_e32 v32, v29
	v_pk_fma_f32 v[48:49], v[98:99], v[54:55], v[48:49]
	v_pk_mul_f32 v[42:43], v[42:43], s[88:89] op_sel_hi:[1,0]
	v_pk_fma_f32 v[18:19], v[98:99], v[32:33], v[18:19]
	v_pk_mul_f32 v[22:23], v[36:37], s[88:89] op_sel_hi:[1,0]
	v_mov_b32_e32 v24, v21
	v_pk_fma_f32 v[42:43], v[98:99], v[30:31], v[42:43]
	v_pk_fma_f32 v[20:21], v[98:99], v[24:25], v[22:23]
	global_store_dwordx4 v[52:53], v[46:49], off
	global_store_dwordx4 v[52:53], v[42:45], off offset:16
	global_store_dwordx4 v[52:53], v[38:41], off offset:32
	global_store_dwordx4 v[52:53], v[18:21], off offset:48
	v_mov_b32_e32 v36, v8
	v_mov_b32_e32 v37, v14
	v_or_b32_e32 v18, 48, v50
	v_ashrrev_i32_e32 v19, 31, v18
	v_lshlrev_b64 v[18:19], 12, v[18:19]
	v_or_b32_e32 v18, v18, v12
	v_lshl_add_u64 v[30:31], s[56:57], 0, v[18:19]
	v_lshl_add_u64 v[34:35], s[90:91], 0, v[18:19]
	global_load_dwordx4 v[18:21], v[30:31], off offset:48
	global_load_dwordx4 v[22:25], v[30:31], off offset:32
	global_load_dwordx4 v[26:29], v[30:31], off offset:16
	s_nop 0
	global_load_dwordx4 v[30:33], v[30:31], off
	v_mov_b32_e32 v14, v9
	s_waitcnt vmcnt(1)
	v_pk_mul_f32 v[8:9], v[28:29], s[88:89] op_sel_hi:[1,0]
	s_waitcnt vmcnt(0)
	v_pk_mul_f32 v[30:31], v[30:31], s[88:89] op_sel_hi:[1,0]
	v_pk_mul_f32 v[32:33], v[32:33], s[88:89] op_sel_hi:[1,0]
	v_pk_fma_f32 v[30:31], v[98:99], v[36:37], v[30:31]
	v_mov_b32_e32 v37, v4
	v_mov_b32_e32 v4, v1
	v_mov_b32_e32 v36, v0
	v_pk_fma_f32 v[28:29], v[98:99], v[4:5], v[8:9]
	v_pk_mul_f32 v[0:1], v[22:23], s[88:89] op_sel_hi:[1,0]
	v_mov_b32_e32 v4, v10
	v_mov_b32_e32 v5, v16
	v_pk_fma_f32 v[22:23], v[98:99], v[4:5], v[0:1]
	v_pk_mul_f32 v[0:1], v[24:25], s[88:89] op_sel_hi:[1,0]
	v_mov_b32_e32 v4, v2
	v_mov_b32_e32 v5, v6
	v_pk_fma_f32 v[32:33], v[98:99], v[36:37], v[32:33]
	v_pk_mul_f32 v[26:27], v[26:27], s[88:89] op_sel_hi:[1,0]
	v_pk_fma_f32 v[24:25], v[98:99], v[4:5], v[0:1]
	v_pk_mul_f32 v[0:1], v[18:19], s[88:89] op_sel_hi:[1,0]
	v_mov_b32_e32 v16, v11
	v_pk_mul_f32 v[4:5], v[20:21], s[88:89] op_sel_hi:[1,0]
	v_mov_b32_e32 v6, v3
	v_pk_fma_f32 v[26:27], v[98:99], v[14:15], v[26:27]
	v_pk_fma_f32 v[0:1], v[98:99], v[16:17], v[0:1]
	v_pk_fma_f32 v[2:3], v[98:99], v[6:7], v[4:5]
	global_store_dwordx4 v[34:35], v[30:33], off
	global_store_dwordx4 v[34:35], v[26:29], off offset:16
	global_store_dwordx4 v[34:35], v[22:25], off offset:32
	global_store_dwordx4 v[34:35], v[0:3], off offset:48
	s_cbranch_scc0 .LBB0_35

; __device__ __forceinline__ int tidx() { int t = threadIdx.x; asm volatile("" : "+v"(t)); return t; }
; template <int NT>
; __device__ __forceinline__ void gemm_tile(f32x4 (&acc)[4][NT], const bf16_t* A, int lda, const bf16_t* B, int ldb, int K, bf16_t* sm) {
;     const int tid_ = tidx();
;     bf16_t* sA = sm; bf16_t* sB = sm + 128 * LDT;
;     const int tid = tid_, lane = tid & 63, wid = tid >> 6, wr = wid >> 1, wc = wid & 1;
;     const int fr = lane & 15, fq = lane >> 4;
;     const int lrow = tid >> 3, lkc = tid & 7;
;     const bf16_t* ga = A + (size_t)lrow * lda + lkc * 8;
;     const bf16_t* gb = B + (size_t)lrow * ldb + lkc * 8;
;     int sbrow[NT];
; #pragma unroll
;     for (int i = 0; i < NT; ++i) { const int g = lrow + 32 * i, W_ = 16 * NT, rem = g % W_; sbrow[i] = (g / W_) * W_ + (rem % NT) * 16 + rem / NT; }
;     u32x4 ra0[4], rb0[NT];
; #pragma unroll
;     for (int i = 0; i < 4; ++i) ra0[i] = *(const u32x4*)(ga + (size_t)(32 * i) * lda);
; #pragma unroll
;     for (int i = 0; i < NT; ++i) rb0[i] = *(const u32x4*)(gb + (size_t)(32 * i) * ldb);
; __device__ __forceinline__ void phase_scan(KP p, int l, unsigned char* smem) {
;     ...
;     for (;;) {
;         __syncthreads();
;         if (tid_ == 0) s_q = (int)atomicAdd(cnt, 1u);
;         __syncthreads();
;         const int t = s_q;
;         const int NGT = 136 * 32, NAT = 1152, NMV = 256;
;         if (t >= NGT + NAT + NMV) break;
;         if (t < NMV) misc_vblock(p, l, t, NMV);
;         else if (t < NMV + NAT) attn_block_task(p, l, t - NMV);
;         else gate_tile(t - NMV - NAT, (const bf16_t*)(p->ws + OFF_XB), (const bf16_t*)(p->ws + OFF_WG), (bf16_t*)(p->ws + OFF_G), (bf16_t*)smem);
.LBB0_174:
	s_or_b64 exec, exec, s[14:15]
	s_waitcnt lgkmcnt(0)
	s_barrier
	ds_read_b32 v0, v235 offset:16
	s_movk_i32 s2, 0x167f
	s_mov_b64 s[12:13], -1
	s_waitcnt lgkmcnt(0)
	v_cmp_lt_i32_e32 vcc, s2, v0
	v_readfirstlane_b32 s74, v0
	s_cbranch_vccnz .LBB0_169
	s_cmpk_gt_i32 s74, 0xff
	s_cbranch_scc0 .LBB0_189
	s_cmpk_gt_u32 s74, 0x57f
	s_cbranch_scc0 .LBB0_180
	v_mov_b32_e32 v12, v192
	v_mov_b32_e32 v40, v192
	s_add_i32 s2, s74, 0xfffffa80
	v_ashrrev_i32_e32 v0, 31, v40
	s_waitcnt vmcnt(6)
	v_ashrrev_i32_e32 v30, 3, v40
	v_lshrrev_b32_e32 v0, 26, v0
	v_add_u32_e32 v0, v30, v0
	v_lshrrev_b32_e32 v1, 6, v0
	v_mul_i32_i24_e32 v1, 64, v1
	v_sub_u32_e32 v1, v30, v1
	v_lshrrev_b16_sdwa v2, v196, sext(v1) dst_sel:DWORD dst_unused:UNUSED_PAD src0_sel:DWORD src1_sel:BYTE_0
	v_and_b32_e32 v2, 3, v2
	v_add_u16_e32 v2, v1, v2
	v_ashrrev_i16_sdwa v3, v197, sext(v2) dst_sel:DWORD dst_unused:UNUSED_PAD src0_sel:DWORD src1_sel:BYTE_0
	v_and_b32_e32 v2, 0xfc, v2
	v_sub_u16_e32 v1, v1, v2
	v_and_b32_e32 v0, 0x7ffffc0, v0
	v_lshlrev_b32_sdwa v1, v198, sext(v1) dst_sel:DWORD dst_unused:UNUSED_PAD src0_sel:DWORD src1_sel:BYTE_0
	v_bfe_i32 v2, v3, 0, 16
	v_add3_u32 v41, v0, v2, v1
	v_add_u32_e32 v0, 32, v30
	v_ashrrev_i32_e32 v1, 31, v0
	v_lshrrev_b32_e32 v1, 26, v1
	v_add_u32_e32 v1, v0, v1
	v_lshrrev_b32_e32 v2, 6, v1
	v_mul_i32_i24_e32 v2, 64, v2
	v_sub_u32_e32 v0, v0, v2
	v_lshrrev_b16_sdwa v2, v196, sext(v0) dst_sel:DWORD dst_unused:UNUSED_PAD src0_sel:DWORD src1_sel:BYTE_0
	v_and_b32_e32 v2, 3, v2
	v_add_u16_e32 v2, v0, v2
	v_ashrrev_i16_sdwa v3, v197, sext(v2) dst_sel:DWORD dst_unused:UNUSED_PAD src0_sel:DWORD src1_sel:BYTE_0
	v_and_b32_e32 v2, 0xfc, v2
	v_sub_u16_e32 v0, v0, v2
	v_and_b32_e32 v1, 0x7ffffc0, v1
	v_lshlrev_b32_sdwa v0, v198, sext(v0) dst_sel:DWORD dst_unused:UNUSED_PAD src0_sel:DWORD src1_sel:BYTE_0
	v_bfe_i32 v2, v3, 0, 16
	v_add3_u32 v42, v1, v2, v0
	v_add_u32_e32 v0, 64, v30
	v_ashrrev_i32_e32 v1, 31, v0
	v_lshrrev_b32_e32 v1, 26, v1
	v_add_u32_e32 v1, v0, v1
	v_lshrrev_b32_e32 v2, 6, v1
	v_mul_i32_i24_e32 v2, 64, v2
	v_sub_u32_e32 v0, v0, v2
	v_lshrrev_b16_sdwa v2, v196, sext(v0) dst_sel:DWORD dst_unused:UNUSED_PAD src0_sel:DWORD src1_sel:BYTE_0
	v_and_b32_e32 v2, 3, v2
	v_add_u16_e32 v2, v0, v2
	v_ashrrev_i16_sdwa v3, v197, sext(v2) dst_sel:DWORD dst_unused:UNUSED_PAD src0_sel:DWORD src1_sel:BYTE_0
	v_and_b32_e32 v2, 0xfc, v2
	v_sub_u16_e32 v0, v0, v2
	v_and_b32_e32 v1, 0x7ffffc0, v1
	v_lshlrev_b32_sdwa v0, v198, sext(v0) dst_sel:DWORD dst_unused:UNUSED_PAD src0_sel:DWORD src1_sel:BYTE_0
	v_bfe_i32 v2, v3, 0, 16
	v_add3_u32 v43, v1, v2, v0
	v_add_u32_e32 v0, 0x60, v30
	v_ashrrev_i32_e32 v1, 31, v0
	v_lshrrev_b32_e32 v1, 26, v1
	v_add_u32_e32 v1, v0, v1
	v_lshrrev_b32_e32 v2, 6, v1
	v_mul_i32_i24_e32 v2, 64, v2
	v_sub_u32_e32 v0, v0, v2
	s_lshr_b32 s13, s2, 5
	v_lshrrev_b16_sdwa v2, v196, sext(v0) dst_sel:DWORD dst_unused:UNUSED_PAD src0_sel:DWORD src1_sel:BYTE_0
	s_lshl_b32 s86, s13, 17
	v_and_b32_e32 v2, 3, v2
	s_and_b32 s12, s74, 31
	s_lshl_b64 s[14:15], s[86:87], 1
	v_add_u16_e32 v2, v0, v2
	s_add_u32 s18, s80, s14
	v_ashrrev_i16_sdwa v3, v197, sext(v2) dst_sel:DWORD dst_unused:UNUSED_PAD src0_sel:DWORD src1_sel:BYTE_0
	v_and_b32_e32 v2, 0xfc, v2
	s_addc_u32 s19, s81, s15
	s_lshl_b32 s2, s12, 18
	v_sub_u16_e32 v0, v0, v2
	s_add_u32 s22, s11, s2
	v_and_b32_e32 v1, 0x7ffffc0, v1
	v_lshlrev_b32_sdwa v0, v198, sext(v0) dst_sel:DWORD dst_unused:UNUSED_PAD src0_sel:DWORD src1_sel:BYTE_0
	v_bfe_i32 v2, v3, 0, 16
	v_ashrrev_i32_e32 v31, 31, v30
	s_addc_u32 s23, s39, 0
	v_add3_u32 v44, v1, v2, v0
	v_lshlrev_b64 v[32:33], 11, v[30:31]
	v_lshlrev_b32_e32 v2, 4, v40
	v_lshl_add_u64 v[0:1], s[22:23], 0, v[32:33]
	v_and_b32_e32 v38, 0x70, v2
	v_mov_b32_e32 v39, v13
	v_lshl_add_u64 v[8:9], v[0:1], 0, v[38:39]
	v_add_co_u32_e32 v0, vcc, s7, v8
	v_mul_lo_u32 v46, v30, s89
	s_nop 0
	v_addc_co_u32_e32 v1, vcc, 0, v9, vcc
	v_add_co_u32_e32 v10, vcc, s37, v8
	v_mov_b32_e32 v250, v8
	v_mov_b32_e32 v251, v9
	s_nop 0
	v_addc_co_u32_e32 v11, vcc, 0, v9, vcc
	v_add_co_u32_e32 v14, vcc, s73, v8
	v_and_b32_e32 v30, 7, v40
	s_nop 0
	v_addc_co_u32_e32 v15, vcc, 0, v9, vcc
	s_nop 0
	v_lshl_add_u64 v[14:15], s[18:19], 0, v[32:33]
	v_lshl_add_u64 v[26:27], v[14:15], 0, v[38:39]
	v_add_co_u32_e32 v14, vcc, s7, v26
	s_add_u32 s14, s58, s14
	s_nop 0
	v_addc_co_u32_e32 v15, vcc, 0, v27, vcc
	v_add_co_u32_e32 v28, vcc, s37, v26
	v_mov_b32_e32 v248, v26
	v_mov_b32_e32 v249, v27
	s_nop 0
	v_addc_co_u32_e32 v29, vcc, 0, v27, vcc
	v_add_co_u32_e32 v34, vcc, s73, v26
	v_and_b32_e32 v31, 15, v40
	s_nop 0
	v_addc_co_u32_e32 v35, vcc, 0, v27, vcc
	s_nop 0
	v_lshrrev_b32_e32 v39, 1, v40
	v_lshl_or_b32 v32, v30, 4, v32
	s_addc_u32 s15, s59, s15
	v_and_or_b32 v31, v39, s3, v31
	v_and_b32_e32 v39, 0x4f, v40
	v_lshl_add_u64 v[98:99], s[14:15], 0, v[32:33]
	s_add_u32 s14, s58, s2
	v_and_b32_e32 v45, 48, v40
	v_mul_lo_u32 v31, v31, s89
	v_mul_u32_u24_e32 v39, 0xa0, v39
	v_mul_lo_u32 v41, v41, s89
	v_mul_lo_u32 v42, v42, s89
	v_mul_lo_u32 v43, v43, s89
	v_mul_lo_u32 v44, v44, s89
	s_addc_u32 s15, s59, 0
	v_mov_b32_e32 v30, 0
	v_lshl_add_u64 v[100:101], s[14:15], 0, v[32:33]
	s_mov_b64 s[14:15], 0
	v_add_u32_e32 v104, v38, v46
	v_add_u32_e32 v105, v38, v41
	v_add_u32_e32 v106, v38, v42
	v_add_u32_e32 v107, v38, v43
	v_add_u32_e32 v108, v38, v44
	v_add_u32_e32 v103, v45, v31
	v_add_u32_e32 v102, v45, v39
	v_mov_b32_e32 v31, v30
	v_mov_b32_e32 v32, v30
	v_mov_b32_e32 v33, v30
	v_mov_b32_e32 v38, v30
	v_mov_b32_e32 v39, v30
	v_mov_b32_e32 v40, v30
	v_mov_b32_e32 v41, v30
	v_mov_b32_e32 v42, v30
	v_mov_b32_e32 v43, v30
	v_mov_b32_e32 v44, v30
	v_mov_b32_e32 v45, v30
	v_mov_b32_e32 v46, v30
; template <int NT>
; __device__ __forceinline__ void gemm_tile(f32x4 (&acc)[4][NT], const bf16_t* A, int lda, const bf16_t* B, int ldb, int K, bf16_t* sm) {
;     ...
;     for (int kt = 0; kt < nk; ++kt) {
;         lds_barrier();
; #pragma unroll
;         for (int i = 0; i < 4; ++i) *(u32x4*)(sA + (lrow + 32 * i) * LDT + lkc * 8) = ra0[i];
; #pragma unroll
;         for (int i = 0; i < NT; ++i) *(u32x4*)(sB + sbrow[i] * LDT + lkc * 8) = rb0[i];
;         lds_barrier();
;         if (kt + 1 < nk) {
;             ga += 64; gb += 64;
; #pragma unroll
;             for (int i = 0; i < 4; ++i) ra0[i] = *(const u32x4*)(ga + (size_t)(32 * i) * lda);
; #pragma unroll
;             for (int i = 0; i < NT; ++i) rb0[i] = *(const u32x4*)(gb + (size_t)(32 * i) * ldb);
;         }
;         __builtin_amdgcn_sched_barrier(0);
;         gemm_compute<NT>(acc, sA, sB, wr, wc, fr, fq);
	v_mov_b32_e32 v47, v30
	v_mov_b32_e32 v48, v30
	v_mov_b32_e32 v49, v30
	v_mov_b32_e32 v50, v30
	v_mov_b32_e32 v51, v30
	v_mov_b32_e32 v52, v30
	v_mov_b32_e32 v53, v30
	v_mov_b32_e32 v54, v30
	v_mov_b32_e32 v55, v30
	v_mov_b32_e32 v56, v30
	v_mov_b32_e32 v57, v30
	v_mov_b32_e32 v58, v30
	v_mov_b32_e32 v59, v30
	v_mov_b32_e32 v60, v30
	v_mov_b32_e32 v61, v30
	v_mov_b32_e32 v62, v30
	v_mov_b32_e32 v63, v30
	v_mov_b32_e32 v64, v30
	v_mov_b32_e32 v65, v30
	v_mov_b32_e32 v66, v30
	v_mov_b32_e32 v67, v30
	v_mov_b32_e32 v68, v30
	v_mov_b32_e32 v69, v30
	v_mov_b32_e32 v70, v30
	v_mov_b32_e32 v71, v30
	v_mov_b32_e32 v72, v30
	v_mov_b32_e32 v73, v30
	v_mov_b32_e32 v74, v30
	v_mov_b32_e32 v75, v30
	v_mov_b32_e32 v76, v30
	v_mov_b32_e32 v77, v30
	v_mov_b32_e32 v78, v30
	v_mov_b32_e32 v79, v30
	v_mov_b32_e32 v80, v30
	v_mov_b32_e32 v81, v30
	v_mov_b32_e32 v82, v30
	v_mov_b32_e32 v83, v30
	v_mov_b32_e32 v84, v30
	v_mov_b32_e32 v85, v30
	v_mov_b32_e32 v86, v30
	v_mov_b32_e32 v87, v30
	v_mov_b32_e32 v88, v30
	v_mov_b32_e32 v89, v30
	v_mov_b32_e32 v90, v30
	v_mov_b32_e32 v91, v30
	v_mov_b32_e32 v92, v30
	v_mov_b32_e32 v93, v30
	v_mov_b32_e32 v94, v30
	v_mov_b32_e32 v95, v30
	v_mov_b32_e32 v96, v30
	v_mov_b32_e32 v97, v30
	v_writelane_b32 v234, s90, 0
	v_writelane_b32 v234, s91, 1
	v_writelane_b32 v234, s92, 2
	v_writelane_b32 v234, s93, 3
	v_writelane_b32 v234, s94, 4
	v_writelane_b32 v234, s95, 5
	v_bfe_u32 v160, v192, 3, 3
	v_and_b32_e32 v161, 7, v192
	v_xor_b32_e32 v161, v160, v161
	v_lshlrev_b32_e32 v161, 4, v161
	v_lshrrev_b32_e32 v162, 6, v192
	v_lshl_add_u32 v163, v162, 5, v160
	v_mul_u32_u24_e32 v163, 0x800, v163
	v_add_u32_e32 v236, v163, v161
	v_add_u32_e32 v237, 0x3c00, v236
	v_add_u32_e32 v238, 0x3c00, v237
	v_add_u32_e32 v239, 0x3c00, v238
	v_lshrrev_b32_e32 v163, 7, v192
	v_bfe_u32 v162, v192, 6, 1
	v_lshlrev_b32_e32 v163, 6, v163
	v_lshl_add_u32 v163, v160, 2, v163
	v_lshl_add_u32 v163, v162, 1, v163
	v_mul_u32_u24_e32 v163, 0x800, v163
	v_add_u32_e32 v240, v163, v161
	v_add_u32_e32 v241, 0xfc00, v240
	v_subrev_u32_e32 v242, 0xfc00, v241
	v_add_u32_e32 v243, 0xfc00, v242
	v_and_b32_e32 v160, 15, v192
	v_bfe_u32 v161, v192, 4, 2
	v_and_b32_e32 v162, 7, v160
	v_xor_b32_e32 v161, v161, v162
	v_lshlrev_b32_e32 v161, 4, v161
	v_lshl_add_u32 v161, v160, 7, v161
	v_lshrrev_b32_e32 v162, 7, v192
	v_lshl_add_u32 v244, v162, 13, v161
	v_bfe_u32 v162, v192, 6, 1
	v_lshl_add_u32 v246, v162, 13, v161
	v_add_u32_e32 v246, 0x4000, v246
	v_xor_b32_e32 v245, 64, v244
	v_xor_b32_e32 v247, 64, v246
	v_lshrrev_b32_e32 v160, 6, v192
	s_nop 0
	v_readfirstlane_b32 s94, v160
	v_readfirstlane_b32 s90, v248
	v_readfirstlane_b32 s91, v249
	v_readfirstlane_b32 s92, v250
	v_readfirstlane_b32 s93, v251
	s_mul_i32 s95, s94, 0x4000
	s_sub_u32 s90, s90, s95
	s_subb_u32 s91, s91, 0
	s_mul_i32 s95, s94, 0x4000
	s_sub_u32 s92, s92, s95
	s_subb_u32 s93, s93, 0
	s_lshl_b32 s94, s94, 10
	s_waitcnt lgkmcnt(0)
	s_barrier
	s_lshl_b32 s95, s94, 2
	s_add_u32 m0, s95, 0x0
	s_nop 0
	global_load_lds_dwordx4 v236, s[90:91]
	global_load_lds_dwordx4 v237, s[90:91] offset:1024
	global_load_lds_dwordx4 v238, s[90:91] offset:2048
	global_load_lds_dwordx4 v239, s[90:91] offset:3072
	s_mul_i32 s95, s94, 4
	s_add_u32 m0, s95, 0x4000
	s_nop 0
	global_load_lds_dwordx4 v240, s[92:93]
	global_load_lds_dwordx4 v241, s[92:93] offset:1024
	global_load_lds_dwordx4 v242, s[92:93] offset:2048
	global_load_lds_dwordx4 v243, s[92:93] offset:3072
	s_add_u32 s90, s90, 0x80
	s_addc_u32 s91, s91, 0
	s_add_u32 s92, s92, 0x80
	s_addc_u32 s93, s93, 0
	s_waitcnt vmcnt(0)
	s_barrier
	s_lshl_b32 s95, s94, 2
	s_add_u32 m0, s95, 0x8000
	s_nop 0
	global_load_lds_dwordx4 v236, s[90:91]
	global_load_lds_dwordx4 v237, s[90:91] offset:1024
	global_load_lds_dwordx4 v238, s[90:91] offset:2048
	global_load_lds_dwordx4 v239, s[90:91] offset:3072
	s_mul_i32 s95, s94, 4
	s_add_u32 m0, s95, 0xc000
	s_nop 0
	global_load_lds_dwordx4 v240, s[92:93]
	global_load_lds_dwordx4 v241, s[92:93] offset:1024
	global_load_lds_dwordx4 v242, s[92:93] offset:2048
	global_load_lds_dwordx4 v243, s[92:93] offset:3072
	s_add_u32 s90, s90, 0x80
	s_addc_u32 s91, s91, 0
	s_add_u32 s92, s92, 0x80
	s_addc_u32 s93, s93, 0
	ds_read_b128 v[110:113], v244 offset:0
	ds_read_b128 v[114:117], v244 offset:2048
	ds_read_b128 v[118:121], v244 offset:4096
	ds_read_b128 v[122:125], v244 offset:6144
	ds_read_b128 v[126:129], v246 offset:0
	ds_read_b128 v[130:133], v246 offset:2048
	ds_read_b128 v[134:137], v246 offset:4096
	ds_read_b128 v[138:141], v246 offset:6144
	s_movk_i32 s95, 0x6
	s_cmp_eq_u32 s95, 0
	s_cbranch_scc1 .Lgemm_x178
; template <int NT>
; __device__ __forceinline__ void gemm_compute(f32x4 (&acc)[4][NT], const bf16_t* sA, const bf16_t* sB, int wr, int wc, int fr, int fq) {
; #pragma unroll
;     for (int ks = 0; ks < 2; ++ks) {
;         bf16x8 a[4], b[NT];
; #pragma unroll
;         for (int mt = 0; mt < 4; ++mt) a[mt] = *(const bf16x8*)(sA + (wr * 64 + mt * 16 + fr) * LDT + ks * 32 + fq * 8);
; #pragma unroll
;         for (int nt = 0; nt < NT; ++nt) b[nt] = *(const bf16x8*)(sB + (wc * 16 * NT + nt * 16 + fr) * LDT + ks * 32 + fq * 8);
;         __builtin_amdgcn_s_setprio(1);
; #pragma unroll
;         for (int mt = 0; mt < 4; ++mt)
; #pragma unroll
;             for (int nt = 0; nt < NT; ++nt)
;                 acc[mt][nt] = __builtin_amdgcn_mfma_f32_16x16x32_bf16(b[nt], a[mt], acc[mt][nt], 0, 0, 0);
;         __builtin_amdgcn_s_setprio(0);
;     }
; template <int NT>
; __device__ __forceinline__ void gemm_tile(f32x4 (&acc)[4][NT], const bf16_t* A, int lda, const bf16_t* B, int ldb, int K, bf16_t* sm) {
;     ...
;     for (int kt = 0; kt < nk; ++kt) {
;         lds_barrier();
; #pragma unroll
;         for (int i = 0; i < 4; ++i) *(u32x4*)(sA + (lrow + 32 * i) * LDT + lkc * 8) = ra0[i];
; #pragma unroll
;         for (int i = 0; i < NT; ++i) *(u32x4*)(sB + sbrow[i] * LDT + lkc * 8) = rb0[i];
;         lds_barrier();
;         if (kt + 1 < nk) {
;             ga += 64; gb += 64;
; #pragma unroll
;             for (int i = 0; i < 4; ++i) ra0[i] = *(const u32x4*)(ga + (size_t)(32 * i) * lda);
; #pragma unroll
;             for (int i = 0; i < NT; ++i) rb0[i] = *(const u32x4*)(gb + (size_t)(32 * i) * ldb);
;         }
;         __builtin_amdgcn_sched_barrier(0);
;         gemm_compute<NT>(acc, sA, sB, wr, wc, fr, fq);
;         __builtin_amdgcn_sched_barrier(0);
;     }
.Lgemm_k178:
	v_writelane_b32 v234, s95, 6
	ds_read_b128 v[160:163], v245 offset:0
	ds_read_b128 v[164:167], v245 offset:2048
	ds_read_b128 v[168:171], v245 offset:4096
	ds_read_b128 v[172:175], v245 offset:6144
	ds_read_b128 v[176:179], v247 offset:0
	ds_read_b128 v[180:183], v247 offset:2048
	ds_read_b128 v[184:187], v247 offset:4096
	ds_read_b128 v[188:191], v247 offset:6144
	s_setprio 1
	s_waitcnt lgkmcnt(11)
	v_mfma_f32_16x16x32_bf16 v[94:97], v[126:129], v[110:113], v[94:97]
	s_waitcnt lgkmcnt(10)
	v_mfma_f32_16x16x32_bf16 v[90:93], v[130:133], v[110:113], v[90:93]
	s_waitcnt lgkmcnt(9)
	v_mfma_f32_16x16x32_bf16 v[86:89], v[134:137], v[110:113], v[86:89]
	s_waitcnt lgkmcnt(8)
	v_mfma_f32_16x16x32_bf16 v[82:85], v[138:141], v[110:113], v[82:85]
	v_mfma_f32_16x16x32_bf16 v[78:81], v[126:129], v[114:117], v[78:81]
	v_mfma_f32_16x16x32_bf16 v[74:77], v[130:133], v[114:117], v[74:77]
	v_mfma_f32_16x16x32_bf16 v[70:73], v[134:137], v[114:117], v[70:73]
	v_mfma_f32_16x16x32_bf16 v[66:69], v[138:141], v[114:117], v[66:69]
	v_mfma_f32_16x16x32_bf16 v[62:65], v[126:129], v[118:121], v[62:65]
	v_mfma_f32_16x16x32_bf16 v[58:61], v[130:133], v[118:121], v[58:61]
	v_mfma_f32_16x16x32_bf16 v[54:57], v[134:137], v[118:121], v[54:57]
	v_mfma_f32_16x16x32_bf16 v[50:53], v[138:141], v[118:121], v[50:53]
	v_mfma_f32_16x16x32_bf16 v[46:49], v[126:129], v[122:125], v[46:49]
	v_mfma_f32_16x16x32_bf16 v[42:45], v[130:133], v[122:125], v[42:45]
	v_mfma_f32_16x16x32_bf16 v[38:41], v[134:137], v[122:125], v[38:41]
	v_mfma_f32_16x16x32_bf16 v[30:33], v[138:141], v[122:125], v[30:33]
	s_setprio 0
	s_waitcnt vmcnt(0) lgkmcnt(0)
	s_barrier
	ds_read_b128 v[110:113], v244 offset:32768
	ds_read_b128 v[114:117], v244 offset:34816
	ds_read_b128 v[118:121], v244 offset:36864
	ds_read_b128 v[122:125], v244 offset:38912
	ds_read_b128 v[126:129], v246 offset:32768
	ds_read_b128 v[130:133], v246 offset:34816
	ds_read_b128 v[134:137], v246 offset:36864
	ds_read_b128 v[138:141], v246 offset:38912
	s_setprio 1
	v_mfma_f32_16x16x32_bf16 v[94:97], v[176:179], v[160:163], v[94:97]
	s_lshl_b32 s95, s94, 2
	s_add_u32 m0, s95, 0x0
	s_nop 0
	global_load_lds_dwordx4 v236, s[90:91]
	v_mfma_f32_16x16x32_bf16 v[90:93], v[180:183], v[160:163], v[90:93]
	v_mfma_f32_16x16x32_bf16 v[86:89], v[184:187], v[160:163], v[86:89]
	global_load_lds_dwordx4 v237, s[90:91] offset:1024
	v_mfma_f32_16x16x32_bf16 v[82:85], v[188:191], v[160:163], v[82:85]
	v_mfma_f32_16x16x32_bf16 v[78:81], v[176:179], v[164:167], v[78:81]
	global_load_lds_dwordx4 v238, s[90:91] offset:2048
	v_mfma_f32_16x16x32_bf16 v[74:77], v[180:183], v[164:167], v[74:77]
	v_mfma_f32_16x16x32_bf16 v[70:73], v[184:187], v[164:167], v[70:73]
	global_load_lds_dwordx4 v239, s[90:91] offset:3072
	v_mfma_f32_16x16x32_bf16 v[66:69], v[188:191], v[164:167], v[66:69]
	v_mfma_f32_16x16x32_bf16 v[62:65], v[176:179], v[168:171], v[62:65]
	s_mul_i32 s95, s94, 4
	s_add_u32 m0, s95, 0x4000
	s_nop 0
	global_load_lds_dwordx4 v240, s[92:93]
	v_mfma_f32_16x16x32_bf16 v[58:61], v[180:183], v[168:171], v[58:61]
	v_mfma_f32_16x16x32_bf16 v[54:57], v[184:187], v[168:171], v[54:57]
	global_load_lds_dwordx4 v241, s[92:93] offset:1024
	v_mfma_f32_16x16x32_bf16 v[50:53], v[188:191], v[168:171], v[50:53]
	v_mfma_f32_16x16x32_bf16 v[46:49], v[176:179], v[172:175], v[46:49]
	global_load_lds_dwordx4 v242, s[92:93] offset:2048
	v_mfma_f32_16x16x32_bf16 v[42:45], v[180:183], v[172:175], v[42:45]
	v_mfma_f32_16x16x32_bf16 v[38:41], v[184:187], v[172:175], v[38:41]
	global_load_lds_dwordx4 v243, s[92:93] offset:3072
	v_mfma_f32_16x16x32_bf16 v[30:33], v[188:191], v[172:175], v[30:33]
	s_add_u32 s90, s90, 0x80
	s_addc_u32 s91, s91, 0
	s_add_u32 s92, s92, 0x80
	s_addc_u32 s93, s93, 0
	s_setprio 0
	ds_read_b128 v[160:163], v245 offset:32768
	ds_read_b128 v[164:167], v245 offset:34816
	ds_read_b128 v[168:171], v245 offset:36864
	ds_read_b128 v[172:175], v245 offset:38912
	ds_read_b128 v[176:179], v247 offset:32768
	ds_read_b128 v[180:183], v247 offset:34816
	ds_read_b128 v[184:187], v247 offset:36864
	ds_read_b128 v[188:191], v247 offset:38912
	s_setprio 1
	s_waitcnt lgkmcnt(11)
	v_mfma_f32_16x16x32_bf16 v[94:97], v[126:129], v[110:113], v[94:97]
	s_waitcnt lgkmcnt(10)
	v_mfma_f32_16x16x32_bf16 v[90:93], v[130:133], v[110:113], v[90:93]
	s_waitcnt lgkmcnt(9)
	v_mfma_f32_16x16x32_bf16 v[86:89], v[134:137], v[110:113], v[86:89]
	s_waitcnt lgkmcnt(8)
	v_mfma_f32_16x16x32_bf16 v[82:85], v[138:141], v[110:113], v[82:85]
	v_mfma_f32_16x16x32_bf16 v[78:81], v[126:129], v[114:117], v[78:81]
	v_mfma_f32_16x16x32_bf16 v[74:77], v[130:133], v[114:117], v[74:77]
	v_mfma_f32_16x16x32_bf16 v[70:73], v[134:137], v[114:117], v[70:73]
	v_mfma_f32_16x16x32_bf16 v[66:69], v[138:141], v[114:117], v[66:69]
	v_mfma_f32_16x16x32_bf16 v[62:65], v[126:129], v[118:121], v[62:65]
	v_mfma_f32_16x16x32_bf16 v[58:61], v[130:133], v[118:121], v[58:61]
	v_mfma_f32_16x16x32_bf16 v[54:57], v[134:137], v[118:121], v[54:57]
	v_mfma_f32_16x16x32_bf16 v[50:53], v[138:141], v[118:121], v[50:53]
	v_mfma_f32_16x16x32_bf16 v[46:49], v[126:129], v[122:125], v[46:49]
	v_mfma_f32_16x16x32_bf16 v[42:45], v[130:133], v[122:125], v[42:45]
	v_mfma_f32_16x16x32_bf16 v[38:41], v[134:137], v[122:125], v[38:41]
	v_mfma_f32_16x16x32_bf16 v[30:33], v[138:141], v[122:125], v[30:33]
	s_setprio 0
	s_waitcnt vmcnt(0) lgkmcnt(0)
	s_barrier
; template <int NT>
; __device__ __forceinline__ void gemm_compute(f32x4 (&acc)[4][NT], const bf16_t* sA, const bf16_t* sB, int wr, int wc, int fr, int fq) {
; #pragma unroll
;     for (int ks = 0; ks < 2; ++ks) {
;         bf16x8 a[4], b[NT];
; #pragma unroll
;         for (int mt = 0; mt < 4; ++mt) a[mt] = *(const bf16x8*)(sA + (wr * 64 + mt * 16 + fr) * LDT + ks * 32 + fq * 8);
; #pragma unroll
;         for (int nt = 0; nt < NT; ++nt) b[nt] = *(const bf16x8*)(sB + (wc * 16 * NT + nt * 16 + fr) * LDT + ks * 32 + fq * 8);
;         __builtin_amdgcn_s_setprio(1);
; #pragma unroll
;         for (int mt = 0; mt < 4; ++mt)
; #pragma unroll
;             for (int nt = 0; nt < NT; ++nt)
;                 acc[mt][nt] = __builtin_amdgcn_mfma_f32_16x16x32_bf16(b[nt], a[mt], acc[mt][nt], 0, 0, 0);
;         __builtin_amdgcn_s_setprio(0);
;     }
; template <int NT>
; __device__ __forceinline__ void gemm_tile(f32x4 (&acc)[4][NT], const bf16_t* A, int lda, const bf16_t* B, int ldb, int K, bf16_t* sm) {
;     ...
;     for (int kt = 0; kt < nk; ++kt) {
;         lds_barrier();
; #pragma unroll
;         for (int i = 0; i < 4; ++i) *(u32x4*)(sA + (lrow + 32 * i) * LDT + lkc * 8) = ra0[i];
; #pragma unroll
;         for (int i = 0; i < NT; ++i) *(u32x4*)(sB + sbrow[i] * LDT + lkc * 8) = rb0[i];
;         lds_barrier();
;         if (kt + 1 < nk) {
;             ga += 64; gb += 64;
; #pragma unroll
;             for (int i = 0; i < 4; ++i) ra0[i] = *(const u32x4*)(ga + (size_t)(32 * i) * lda);
; #pragma unroll
;             for (int i = 0; i < NT; ++i) rb0[i] = *(const u32x4*)(gb + (size_t)(32 * i) * ldb);
;         }
;         __builtin_amdgcn_sched_barrier(0);
;         gemm_compute<NT>(acc, sA, sB, wr, wc, fr, fq);
;         __builtin_amdgcn_sched_barrier(0);
;     }
	ds_read_b128 v[110:113], v244 offset:0
	ds_read_b128 v[114:117], v244 offset:2048
	ds_read_b128 v[118:121], v244 offset:4096
	ds_read_b128 v[122:125], v244 offset:6144
	ds_read_b128 v[126:129], v246 offset:0
	ds_read_b128 v[130:133], v246 offset:2048
	ds_read_b128 v[134:137], v246 offset:4096
	ds_read_b128 v[138:141], v246 offset:6144
	s_setprio 1
	v_mfma_f32_16x16x32_bf16 v[94:97], v[176:179], v[160:163], v[94:97]
	s_lshl_b32 s95, s94, 2
	s_add_u32 m0, s95, 0x8000
	s_nop 0
	global_load_lds_dwordx4 v236, s[90:91]
	v_mfma_f32_16x16x32_bf16 v[90:93], v[180:183], v[160:163], v[90:93]
	v_mfma_f32_16x16x32_bf16 v[86:89], v[184:187], v[160:163], v[86:89]
	global_load_lds_dwordx4 v237, s[90:91] offset:1024
	v_mfma_f32_16x16x32_bf16 v[82:85], v[188:191], v[160:163], v[82:85]
	v_mfma_f32_16x16x32_bf16 v[78:81], v[176:179], v[164:167], v[78:81]
	global_load_lds_dwordx4 v238, s[90:91] offset:2048
	v_mfma_f32_16x16x32_bf16 v[74:77], v[180:183], v[164:167], v[74:77]
	v_mfma_f32_16x16x32_bf16 v[70:73], v[184:187], v[164:167], v[70:73]
	global_load_lds_dwordx4 v239, s[90:91] offset:3072
	v_mfma_f32_16x16x32_bf16 v[66:69], v[188:191], v[164:167], v[66:69]
	v_mfma_f32_16x16x32_bf16 v[62:65], v[176:179], v[168:171], v[62:65]
	s_mul_i32 s95, s94, 4
	s_add_u32 m0, s95, 0xc000
	s_nop 0
	global_load_lds_dwordx4 v240, s[92:93]
	v_mfma_f32_16x16x32_bf16 v[58:61], v[180:183], v[168:171], v[58:61]
	v_mfma_f32_16x16x32_bf16 v[54:57], v[184:187], v[168:171], v[54:57]
	global_load_lds_dwordx4 v241, s[92:93] offset:1024
	v_mfma_f32_16x16x32_bf16 v[50:53], v[188:191], v[168:171], v[50:53]
	v_mfma_f32_16x16x32_bf16 v[46:49], v[176:179], v[172:175], v[46:49]
	global_load_lds_dwordx4 v242, s[92:93] offset:2048
	v_mfma_f32_16x16x32_bf16 v[42:45], v[180:183], v[172:175], v[42:45]
	v_mfma_f32_16x16x32_bf16 v[38:41], v[184:187], v[172:175], v[38:41]
	global_load_lds_dwordx4 v243, s[92:93] offset:3072
	v_mfma_f32_16x16x32_bf16 v[30:33], v[188:191], v[172:175], v[30:33]
	s_add_u32 s90, s90, 0x80
	s_addc_u32 s91, s91, 0
	s_add_u32 s92, s92, 0x80
	s_addc_u32 s93, s93, 0
	s_setprio 0
	v_readlane_b32 s95, v234, 6
	s_add_i32 s95, s95, -1
	s_cmp_lg_u32 s95, 0
	s_cbranch_scc1 .Lgemm_k178
.Lgemm_x178:
	ds_read_b128 v[160:163], v245 offset:0
	ds_read_b128 v[164:167], v245 offset:2048
	ds_read_b128 v[168:171], v245 offset:4096
	ds_read_b128 v[172:175], v245 offset:6144
	ds_read_b128 v[176:179], v247 offset:0
	ds_read_b128 v[180:183], v247 offset:2048
	ds_read_b128 v[184:187], v247 offset:4096
	ds_read_b128 v[188:191], v247 offset:6144
	s_setprio 1
	s_waitcnt lgkmcnt(11)
	v_mfma_f32_16x16x32_bf16 v[94:97], v[126:129], v[110:113], v[94:97]
	s_waitcnt lgkmcnt(10)
	v_mfma_f32_16x16x32_bf16 v[90:93], v[130:133], v[110:113], v[90:93]
	s_waitcnt lgkmcnt(9)
	v_mfma_f32_16x16x32_bf16 v[86:89], v[134:137], v[110:113], v[86:89]
	s_waitcnt lgkmcnt(8)
	v_mfma_f32_16x16x32_bf16 v[82:85], v[138:141], v[110:113], v[82:85]
	v_mfma_f32_16x16x32_bf16 v[78:81], v[126:129], v[114:117], v[78:81]
	v_mfma_f32_16x16x32_bf16 v[74:77], v[130:133], v[114:117], v[74:77]
	v_mfma_f32_16x16x32_bf16 v[70:73], v[134:137], v[114:117], v[70:73]
	v_mfma_f32_16x16x32_bf16 v[66:69], v[138:141], v[114:117], v[66:69]
	v_mfma_f32_16x16x32_bf16 v[62:65], v[126:129], v[118:121], v[62:65]
	v_mfma_f32_16x16x32_bf16 v[58:61], v[130:133], v[118:121], v[58:61]
	v_mfma_f32_16x16x32_bf16 v[54:57], v[134:137], v[118:121], v[54:57]
	v_mfma_f32_16x16x32_bf16 v[50:53], v[138:141], v[118:121], v[50:53]
	v_mfma_f32_16x16x32_bf16 v[46:49], v[126:129], v[122:125], v[46:49]
	v_mfma_f32_16x16x32_bf16 v[42:45], v[130:133], v[122:125], v[42:45]
	v_mfma_f32_16x16x32_bf16 v[38:41], v[134:137], v[122:125], v[38:41]
	v_mfma_f32_16x16x32_bf16 v[30:33], v[138:141], v[122:125], v[30:33]
	s_setprio 0
	s_waitcnt vmcnt(0) lgkmcnt(0)
	s_barrier
	ds_read_b128 v[110:113], v244 offset:32768
	ds_read_b128 v[114:117], v244 offset:34816
	ds_read_b128 v[118:121], v244 offset:36864
	ds_read_b128 v[122:125], v244 offset:38912
	ds_read_b128 v[126:129], v246 offset:32768
	ds_read_b128 v[130:133], v246 offset:34816
	ds_read_b128 v[134:137], v246 offset:36864
	ds_read_b128 v[138:141], v246 offset:38912
	s_setprio 1
	v_mfma_f32_16x16x32_bf16 v[94:97], v[176:179], v[160:163], v[94:97]
	s_lshl_b32 s95, s94, 2
	s_add_u32 m0, s95, 0x0
	s_nop 0
	global_load_lds_dwordx4 v236, s[90:91]
	v_mfma_f32_16x16x32_bf16 v[90:93], v[180:183], v[160:163], v[90:93]
	v_mfma_f32_16x16x32_bf16 v[86:89], v[184:187], v[160:163], v[86:89]
	global_load_lds_dwordx4 v237, s[90:91] offset:1024
	v_mfma_f32_16x16x32_bf16 v[82:85], v[188:191], v[160:163], v[82:85]
	v_mfma_f32_16x16x32_bf16 v[78:81], v[176:179], v[164:167], v[78:81]
	global_load_lds_dwordx4 v238, s[90:91] offset:2048
	v_mfma_f32_16x16x32_bf16 v[74:77], v[180:183], v[164:167], v[74:77]
	v_mfma_f32_16x16x32_bf16 v[70:73], v[184:187], v[164:167], v[70:73]
	global_load_lds_dwordx4 v239, s[90:91] offset:3072
	v_mfma_f32_16x16x32_bf16 v[66:69], v[188:191], v[164:167], v[66:69]
	v_mfma_f32_16x16x32_bf16 v[62:65], v[176:179], v[168:171], v[62:65]
	s_mul_i32 s95, s94, 4
	s_add_u32 m0, s95, 0x4000
	s_nop 0
	global_load_lds_dwordx4 v240, s[92:93]
	v_mfma_f32_16x16x32_bf16 v[58:61], v[180:183], v[168:171], v[58:61]
	v_mfma_f32_16x16x32_bf16 v[54:57], v[184:187], v[168:171], v[54:57]
	global_load_lds_dwordx4 v241, s[92:93] offset:1024
	v_mfma_f32_16x16x32_bf16 v[50:53], v[188:191], v[168:171], v[50:53]
	v_mfma_f32_16x16x32_bf16 v[46:49], v[176:179], v[172:175], v[46:49]
	global_load_lds_dwordx4 v242, s[92:93] offset:2048
	v_mfma_f32_16x16x32_bf16 v[42:45], v[180:183], v[172:175], v[42:45]
	v_mfma_f32_16x16x32_bf16 v[38:41], v[184:187], v[172:175], v[38:41]
	global_load_lds_dwordx4 v243, s[92:93] offset:3072
	v_mfma_f32_16x16x32_bf16 v[30:33], v[188:191], v[172:175], v[30:33]
	s_add_u32 s90, s90, 0x80
	s_addc_u32 s91, s91, 0
	s_add_u32 s92, s92, 0x80
	s_addc_u32 s93, s93, 0
	s_setprio 0
	ds_read_b128 v[160:163], v245 offset:32768
	ds_read_b128 v[164:167], v245 offset:34816
	ds_read_b128 v[168:171], v245 offset:36864
	ds_read_b128 v[172:175], v245 offset:38912
	ds_read_b128 v[176:179], v247 offset:32768
	ds_read_b128 v[180:183], v247 offset:34816
	ds_read_b128 v[184:187], v247 offset:36864
	ds_read_b128 v[188:191], v247 offset:38912
	s_setprio 1
	s_waitcnt lgkmcnt(11)
; template <int NT>
; __device__ __forceinline__ void gemm_compute(f32x4 (&acc)[4][NT], const bf16_t* sA, const bf16_t* sB, int wr, int wc, int fr, int fq) {
; #pragma unroll
;     for (int ks = 0; ks < 2; ++ks) {
;         bf16x8 a[4], b[NT];
; #pragma unroll
;         for (int mt = 0; mt < 4; ++mt) a[mt] = *(const bf16x8*)(sA + (wr * 64 + mt * 16 + fr) * LDT + ks * 32 + fq * 8);
; #pragma unroll
;         for (int nt = 0; nt < NT; ++nt) b[nt] = *(const bf16x8*)(sB + (wc * 16 * NT + nt * 16 + fr) * LDT + ks * 32 + fq * 8);
;         __builtin_amdgcn_s_setprio(1);
; #pragma unroll
;         for (int mt = 0; mt < 4; ++mt)
; #pragma unroll
;             for (int nt = 0; nt < NT; ++nt)
;                 acc[mt][nt] = __builtin_amdgcn_mfma_f32_16x16x32_bf16(b[nt], a[mt], acc[mt][nt], 0, 0, 0);
;         __builtin_amdgcn_s_setprio(0);
;     }
; template <int NT>
; __device__ __forceinline__ void gemm_tile(f32x4 (&acc)[4][NT], const bf16_t* A, int lda, const bf16_t* B, int ldb, int K, bf16_t* sm) {
;     ...
;     for (int kt = 0; kt < nk; ++kt) {
;         lds_barrier();
; #pragma unroll
;         for (int i = 0; i < 4; ++i) *(u32x4*)(sA + (lrow + 32 * i) * LDT + lkc * 8) = ra0[i];
; #pragma unroll
;         for (int i = 0; i < NT; ++i) *(u32x4*)(sB + sbrow[i] * LDT + lkc * 8) = rb0[i];
;         lds_barrier();
;         if (kt + 1 < nk) {
;             ga += 64; gb += 64;
; #pragma unroll
;             for (int i = 0; i < 4; ++i) ra0[i] = *(const u32x4*)(ga + (size_t)(32 * i) * lda);
; #pragma unroll
;             for (int i = 0; i < NT; ++i) rb0[i] = *(const u32x4*)(gb + (size_t)(32 * i) * ldb);
;         }
;         __builtin_amdgcn_sched_barrier(0);
;         gemm_compute<NT>(acc, sA, sB, wr, wc, fr, fq);
;         __builtin_amdgcn_sched_barrier(0);
;     }
	v_mfma_f32_16x16x32_bf16 v[94:97], v[126:129], v[110:113], v[94:97]
	s_waitcnt lgkmcnt(10)
	v_mfma_f32_16x16x32_bf16 v[90:93], v[130:133], v[110:113], v[90:93]
	s_waitcnt lgkmcnt(9)
	v_mfma_f32_16x16x32_bf16 v[86:89], v[134:137], v[110:113], v[86:89]
	s_waitcnt lgkmcnt(8)
	v_mfma_f32_16x16x32_bf16 v[82:85], v[138:141], v[110:113], v[82:85]
	v_mfma_f32_16x16x32_bf16 v[78:81], v[126:129], v[114:117], v[78:81]
	v_mfma_f32_16x16x32_bf16 v[74:77], v[130:133], v[114:117], v[74:77]
	v_mfma_f32_16x16x32_bf16 v[70:73], v[134:137], v[114:117], v[70:73]
	v_mfma_f32_16x16x32_bf16 v[66:69], v[138:141], v[114:117], v[66:69]
	v_mfma_f32_16x16x32_bf16 v[62:65], v[126:129], v[118:121], v[62:65]
	v_mfma_f32_16x16x32_bf16 v[58:61], v[130:133], v[118:121], v[58:61]
	v_mfma_f32_16x16x32_bf16 v[54:57], v[134:137], v[118:121], v[54:57]
	v_mfma_f32_16x16x32_bf16 v[50:53], v[138:141], v[118:121], v[50:53]
	v_mfma_f32_16x16x32_bf16 v[46:49], v[126:129], v[122:125], v[46:49]
	v_mfma_f32_16x16x32_bf16 v[42:45], v[130:133], v[122:125], v[42:45]
	v_mfma_f32_16x16x32_bf16 v[38:41], v[134:137], v[122:125], v[38:41]
	v_mfma_f32_16x16x32_bf16 v[30:33], v[138:141], v[122:125], v[30:33]
	s_setprio 0
	s_waitcnt vmcnt(0) lgkmcnt(0)
	s_barrier
	ds_read_b128 v[110:113], v244 offset:0
	ds_read_b128 v[114:117], v244 offset:2048
	ds_read_b128 v[118:121], v244 offset:4096
	ds_read_b128 v[122:125], v244 offset:6144
	ds_read_b128 v[126:129], v246 offset:0
	ds_read_b128 v[130:133], v246 offset:2048
	ds_read_b128 v[134:137], v246 offset:4096
	ds_read_b128 v[138:141], v246 offset:6144
	s_setprio 1
	v_mfma_f32_16x16x32_bf16 v[94:97], v[176:179], v[160:163], v[94:97]
	v_readlane_b32 s90, v234, 0
	v_readlane_b32 s91, v234, 1
	v_readlane_b32 s92, v234, 2
	v_readlane_b32 s93, v234, 3
	v_readlane_b32 s94, v234, 4
	v_readlane_b32 s95, v234, 5
	s_mov_b32 s14, 0x700
	s_mov_b32 s15, 0
	s_nop 3
	v_mfma_f32_16x16x32_bf16 v[90:93], v[180:183], v[160:163], v[90:93]
	v_mfma_f32_16x16x32_bf16 v[86:89], v[184:187], v[160:163], v[86:89]
	v_lshl_add_u64 v[0:1], v[98:99], 0, s[14:15]
	v_mfma_f32_16x16x32_bf16 v[82:85], v[188:191], v[160:163], v[82:85]
	v_mfma_f32_16x16x32_bf16 v[78:81], v[176:179], v[164:167], v[78:81]
	v_add_co_u32_e32 v2, vcc, s0, v0
	v_mfma_f32_16x16x32_bf16 v[74:77], v[180:183], v[164:167], v[74:77]
	v_mfma_f32_16x16x32_bf16 v[70:73], v[184:187], v[164:167], v[70:73]
	s_nop 0
	v_mfma_f32_16x16x32_bf16 v[66:69], v[188:191], v[164:167], v[66:69]
	v_mfma_f32_16x16x32_bf16 v[62:65], v[176:179], v[168:171], v[62:65]
	s_nop 0
	v_mfma_f32_16x16x32_bf16 v[58:61], v[180:183], v[168:171], v[58:61]
	v_mfma_f32_16x16x32_bf16 v[54:57], v[184:187], v[168:171], v[54:57]
	v_addc_co_u32_e32 v3, vcc, 0, v1, vcc
	v_mfma_f32_16x16x32_bf16 v[50:53], v[188:191], v[168:171], v[50:53]
	v_mfma_f32_16x16x32_bf16 v[46:49], v[176:179], v[172:175], v[46:49]
	v_add_co_u32_e32 v4, vcc, s64, v0
	v_mfma_f32_16x16x32_bf16 v[42:45], v[180:183], v[172:175], v[42:45]
	v_mfma_f32_16x16x32_bf16 v[38:41], v[184:187], v[172:175], v[38:41]
	v_lshl_add_u64 v[8:9], v[100:101], 0, s[14:15]
	v_mfma_f32_16x16x32_bf16 v[30:33], v[188:191], v[172:175], v[30:33]
	s_nop 0
	v_addc_co_u32_e32 v5, vcc, 0, v1, vcc
	global_load_dwordx4 v[18:21], v[2:3], off offset:128
	global_load_dwordx4 v[14:17], v[4:5], off offset:128
	v_add_co_u32_e32 v2, vcc, s65, v0
	s_mov_b32 s2, 0x2140000
	s_nop 0
	v_addc_co_u32_e32 v3, vcc, 0, v1, vcc
	v_add_co_u32_e32 v0, vcc, s33, v0
	s_nop 1
	v_addc_co_u32_e32 v1, vcc, 0, v1, vcc
	global_load_dwordx4 v[26:29], v[2:3], off offset:128
	global_load_dwordx4 v[34:37], v[0:1], off offset:128
	v_add_co_u32_e32 v0, vcc, s2, v8
	s_mov_b32 s2, 0x2150000
	s_nop 0
	v_addc_co_u32_e32 v1, vcc, 0, v9, vcc
	v_add_co_u32_e32 v2, vcc, s2, v8
	s_mov_b32 s2, 0x2160000
	s_nop 0
	v_addc_co_u32_e32 v3, vcc, 0, v9, vcc
	v_add_co_u32_e32 v10, vcc, s2, v8
	s_mov_b32 s2, 0x2170000
	s_nop 0
	v_addc_co_u32_e32 v11, vcc, 0, v9, vcc
	v_add_co_u32_e32 v22, vcc, s2, v8
	global_load_dwordx4 v[4:7], v[0:1], off offset:128
	s_nop 0
	global_load_dwordx4 v[0:3], v[2:3], off offset:128
	v_addc_co_u32_e32 v23, vcc, 0, v9, vcc
	global_load_dwordx4 v[8:11], v[10:11], off offset:128
	s_nop 0
	global_load_dwordx4 v[22:25], v[22:23], off offset:128
	s_setprio 0
	ds_read_b128 v[160:163], v245 offset:0
	ds_read_b128 v[164:167], v245 offset:2048
	ds_read_b128 v[168:171], v245 offset:4096
	ds_read_b128 v[172:175], v245 offset:6144
	ds_read_b128 v[176:179], v247 offset:0
	ds_read_b128 v[180:183], v247 offset:2048
	ds_read_b128 v[184:187], v247 offset:4096
	ds_read_b128 v[188:191], v247 offset:6144
	s_setprio 1
	s_waitcnt lgkmcnt(11)
	v_mfma_f32_16x16x32_bf16 v[94:97], v[126:129], v[110:113], v[94:97]
	s_waitcnt lgkmcnt(10)
	v_mfma_f32_16x16x32_bf16 v[90:93], v[130:133], v[110:113], v[90:93]
	s_waitcnt lgkmcnt(9)
	v_mfma_f32_16x16x32_bf16 v[86:89], v[134:137], v[110:113], v[86:89]
	s_waitcnt lgkmcnt(8)
	v_mfma_f32_16x16x32_bf16 v[82:85], v[138:141], v[110:113], v[82:85]
	v_mfma_f32_16x16x32_bf16 v[78:81], v[126:129], v[114:117], v[78:81]
	v_mfma_f32_16x16x32_bf16 v[74:77], v[130:133], v[114:117], v[74:77]
	v_mfma_f32_16x16x32_bf16 v[70:73], v[134:137], v[114:117], v[70:73]
	v_mfma_f32_16x16x32_bf16 v[66:69], v[138:141], v[114:117], v[66:69]
	v_mfma_f32_16x16x32_bf16 v[62:65], v[126:129], v[118:121], v[62:65]
	v_mfma_f32_16x16x32_bf16 v[58:61], v[130:133], v[118:121], v[58:61]
	v_mfma_f32_16x16x32_bf16 v[54:57], v[134:137], v[118:121], v[54:57]
	v_mfma_f32_16x16x32_bf16 v[50:53], v[138:141], v[118:121], v[50:53]
	v_mfma_f32_16x16x32_bf16 v[46:49], v[126:129], v[122:125], v[46:49]
	v_mfma_f32_16x16x32_bf16 v[42:45], v[130:133], v[122:125], v[42:45]
	v_mfma_f32_16x16x32_bf16 v[38:41], v[134:137], v[122:125], v[38:41]
	v_mfma_f32_16x16x32_bf16 v[30:33], v[138:141], v[122:125], v[30:33]
	s_setprio 0
	s_waitcnt lgkmcnt(0)
	s_setprio 1
	v_mfma_f32_16x16x32_bf16 v[94:97], v[176:179], v[160:163], v[94:97]
	v_mfma_f32_16x16x32_bf16 v[90:93], v[180:183], v[160:163], v[90:93]
	v_mfma_f32_16x16x32_bf16 v[86:89], v[184:187], v[160:163], v[86:89]
	v_mfma_f32_16x16x32_bf16 v[82:85], v[188:191], v[160:163], v[82:85]
	v_mfma_f32_16x16x32_bf16 v[78:81], v[176:179], v[164:167], v[78:81]
	v_mfma_f32_16x16x32_bf16 v[74:77], v[180:183], v[164:167], v[74:77]
	v_mfma_f32_16x16x32_bf16 v[70:73], v[184:187], v[164:167], v[70:73]
	v_mfma_f32_16x16x32_bf16 v[66:69], v[188:191], v[164:167], v[66:69]
	v_mfma_f32_16x16x32_bf16 v[62:65], v[176:179], v[168:171], v[62:65]
	v_mfma_f32_16x16x32_bf16 v[58:61], v[180:183], v[168:171], v[58:61]
	v_mfma_f32_16x16x32_bf16 v[54:57], v[184:187], v[168:171], v[54:57]
	v_mfma_f32_16x16x32_bf16 v[50:53], v[188:191], v[168:171], v[50:53]
	v_mfma_f32_16x16x32_bf16 v[46:49], v[176:179], v[172:175], v[46:49]
	v_mfma_f32_16x16x32_bf16 v[42:45], v[180:183], v[172:175], v[42:45]
	v_mfma_f32_16x16x32_bf16 v[38:41], v[184:187], v[172:175], v[38:41]
	v_mfma_f32_16x16x32_bf16 v[30:33], v[188:191], v[172:175], v[30:33]
	s_setprio 0
	s_waitcnt lgkmcnt(0)
	s_barrier
; __device__ __forceinline__ float sigmoid_(float x) { return __builtin_amdgcn_rcpf(1.f + __expf(-x)); }
; template <int NT>
; __device__ __forceinline__ void gemm_tile(f32x4 (&acc)[4][NT], const bf16_t* A, int lda, const bf16_t* B, int ldb, int K, bf16_t* sm) {
;     ...
;         lds_barrier();
; #pragma unroll
;         for (int i = 0; i < 4; ++i) *(u32x4*)(sA + (lrow + 32 * i) * LDT + lkc * 8) = ra0[i];
; #pragma unroll
;         for (int i = 0; i < NT; ++i) *(u32x4*)(sB + sbrow[i] * LDT + lkc * 8) = rb0[i];
;         lds_barrier();
;         if (kt + 1 < nk) {
;             ga += 64; gb += 64;
; #pragma unroll
;             for (int i = 0; i < 4; ++i) ra0[i] = *(const u32x4*)(ga + (size_t)(32 * i) * lda);
; #pragma unroll
;             for (int i = 0; i < NT; ++i) rb0[i] = *(const u32x4*)(gb + (size_t)(32 * i) * ldb);
;         }
;         __builtin_amdgcn_sched_barrier(0);
;         gemm_compute<NT>(acc, sA, sB, wr, wc, fr, fq);
; __device__ __forceinline__ void gate_tile(int t, const bf16_t* xb, const bf16_t* Wg, bf16_t* G, bf16_t* sm) {
;     ...
; #pragma unroll
;     for (int mt = 0; mt < 4; ++mt) {
;         const int row = tm * 128 + wr * 64 + mt * 16 + fr;
;         const int cbase = tn * 128 + wc * 64 + fq * 16;
;         float v[16]; gather_cols<4>(acc, mt, v);
;         u32x4 o0, o1;
; #pragma unroll
;         for (int q = 0; q < 4; ++q) {
;             o0[q] = pack2(sigmoid_(v[2 * q]), sigmoid_(v[2 * q + 1]));
;             o1[q] = pack2(sigmoid_(v[8 + 2 * q]), sigmoid_(v[8 + 2 * q + 1]));
;         }
;         *(u32x4*)(G + (size_t)row * 4096 + cbase) = o0;
;         *(u32x4*)(G + (size_t)row * 4096 + cbase + 8) = o1;
;     }
	s_waitcnt vmcnt(7)
	ds_write_b128 v104, v[18:21]
	s_waitcnt vmcnt(6)
	ds_write_b128 v104, v[14:17] offset:5120
	s_waitcnt vmcnt(5)
	ds_write_b128 v104, v[26:29] offset:10240
	s_waitcnt vmcnt(4)
	ds_write_b128 v104, v[34:37] offset:15360
	s_waitcnt vmcnt(3)
	ds_write_b128 v105, v[4:7] offset:20480
	s_waitcnt vmcnt(2)
	ds_write_b128 v106, v[0:3] offset:20480
	s_waitcnt vmcnt(1)
	ds_write_b128 v107, v[8:11] offset:20480
	s_waitcnt vmcnt(0)
	ds_write_b128 v108, v[22:25] offset:20480
	s_waitcnt lgkmcnt(0)
	s_barrier
	ds_read_b128 v[0:3], v103
	ds_read_b128 v[4:7], v103 offset:2560
	ds_read_b128 v[8:11], v103 offset:5120
	ds_read_b128 v[14:17], v103 offset:7680
	ds_read_b128 v[18:21], v102 offset:20480
	ds_read_b128 v[22:25], v102 offset:23040
	ds_read_b128 v[26:29], v102 offset:25600
	ds_read_b128 v[34:37], v102 offset:28160
	s_setprio 1
	s_waitcnt lgkmcnt(3)
	v_mfma_f32_16x16x32_bf16 v[94:97], v[18:21], v[0:3], v[94:97]
	s_waitcnt lgkmcnt(2)
	v_mfma_f32_16x16x32_bf16 v[90:93], v[22:25], v[0:3], v[90:93]
	s_waitcnt lgkmcnt(1)
	v_mfma_f32_16x16x32_bf16 v[86:89], v[26:29], v[0:3], v[86:89]
	s_waitcnt lgkmcnt(0)
	v_mfma_f32_16x16x32_bf16 v[0:3], v[34:37], v[0:3], v[82:85]
	v_mfma_f32_16x16x32_bf16 v[78:81], v[18:21], v[4:7], v[78:81]
	v_mfma_f32_16x16x32_bf16 v[74:77], v[22:25], v[4:7], v[74:77]
	v_mfma_f32_16x16x32_bf16 v[70:73], v[26:29], v[4:7], v[70:73]
	v_mfma_f32_16x16x32_bf16 v[4:7], v[34:37], v[4:7], v[66:69]
	v_mfma_f32_16x16x32_bf16 v[62:65], v[18:21], v[8:11], v[62:65]
	v_mfma_f32_16x16x32_bf16 v[58:61], v[22:25], v[8:11], v[58:61]
	v_mfma_f32_16x16x32_bf16 v[54:57], v[26:29], v[8:11], v[54:57]
	v_mfma_f32_16x16x32_bf16 v[8:11], v[34:37], v[8:11], v[50:53]
	v_mfma_f32_16x16x32_bf16 v[46:49], v[18:21], v[14:17], v[46:49]
	v_mfma_f32_16x16x32_bf16 v[42:45], v[22:25], v[14:17], v[42:45]
	v_mfma_f32_16x16x32_bf16 v[38:41], v[26:29], v[14:17], v[38:41]
	v_mfma_f32_16x16x32_bf16 v[34:37], v[34:37], v[14:17], v[30:33]
	s_setprio 0
	ds_read_b128 v[14:17], v103 offset:64
	ds_read_b128 v[18:21], v103 offset:2624
	ds_read_b128 v[50:53], v103 offset:5184
	ds_read_b128 v[66:69], v103 offset:7744
	ds_read_b128 v[82:85], v102 offset:20544
	ds_read_b128 v[98:101], v102 offset:23104
	ds_read_b128 v[104:107], v102 offset:25664
	ds_read_b128 v[108:111], v102 offset:28224
	s_setprio 1
	s_waitcnt lgkmcnt(3)
	v_mfma_f32_16x16x32_bf16 v[94:97], v[82:85], v[14:17], v[94:97]
	s_waitcnt lgkmcnt(2)
	v_mfma_f32_16x16x32_bf16 v[90:93], v[98:101], v[14:17], v[90:93]
	s_waitcnt lgkmcnt(1)
	v_mfma_f32_16x16x32_bf16 v[86:89], v[104:107], v[14:17], v[86:89]
	s_waitcnt lgkmcnt(0)
	v_mfma_f32_16x16x32_bf16 v[112:115], v[108:111], v[14:17], v[0:3]
	v_mfma_f32_16x16x32_bf16 v[78:81], v[82:85], v[18:21], v[78:81]
	v_mfma_f32_16x16x32_bf16 v[74:77], v[98:101], v[18:21], v[74:77]
	v_mfma_f32_16x16x32_bf16 v[70:73], v[104:107], v[18:21], v[70:73]
	v_mfma_f32_16x16x32_bf16 v[116:119], v[108:111], v[18:21], v[4:7]
	v_mfma_f32_16x16x32_bf16 v[30:33], v[82:85], v[50:53], v[62:65]
	v_mfma_f32_16x16x32_bf16 v[26:29], v[98:101], v[50:53], v[58:61]
	v_mfma_f32_16x16x32_bf16 v[22:25], v[104:107], v[50:53], v[54:57]
	v_mfma_f32_16x16x32_bf16 v[18:21], v[108:111], v[50:53], v[8:11]
	v_mfma_f32_16x16x32_bf16 v[14:17], v[82:85], v[66:69], v[46:49]
	v_mfma_f32_16x16x32_bf16 v[8:11], v[98:101], v[66:69], v[42:45]
	v_mfma_f32_16x16x32_bf16 v[4:7], v[104:107], v[66:69], v[38:41]
	v_mfma_f32_16x16x32_bf16 v[0:3], v[108:111], v[66:69], v[34:37]
	s_setprio 0
	s_nop 1
	v_ashrrev_i32_e32 v34, 1, v12
	v_and_b32_e32 v34, 0xffffffc0, v34
	v_lshl_add_u32 v34, s13, 7, v34
	v_and_or_b32 v34, v12, 15, v34
	v_and_b32_e32 v12, 0x70, v12
	v_lshlrev_b32_e32 v12, 1, v12
	v_lshl_or_b32 v36, s12, 8, v12
	v_mul_f32_e32 v12, 0xbfb8aa3b, v94
	v_mul_f32_e32 v35, 0xbfb8aa3b, v90
	v_exp_f32_e32 v12, v12
	v_exp_f32_e32 v35, v35
	v_mul_f32_e32 v38, 0xbfb8aa3b, v96
	v_exp_f32_e32 v39, v38
	v_add_f32_e32 v12, 1.0, v12
	v_add_f32_e32 v35, 1.0, v35
	v_mul_f32_e32 v38, 0xbfb8aa3b, v92
	v_rcp_f32_e32 v12, v12
	v_rcp_f32_e32 v35, v35
	v_exp_f32_e32 v40, v38
	v_mul_f32_e32 v45, 0xbfb8aa3b, v113
	v_exp_f32_e32 v45, v45
	v_cvt_pk_bf16_f32 v38, v12, v35
	v_add_f32_e32 v12, 1.0, v39
	v_add_f32_e32 v35, 1.0, v40
	v_mul_f32_e32 v39, 0xbfb8aa3b, v86
	v_rcp_f32_e32 v12, v12
	v_rcp_f32_e32 v35, v35
	v_exp_f32_e32 v39, v39
	v_mul_f32_e32 v40, 0xbfb8aa3b, v112
	v_exp_f32_e32 v40, v40
	v_cvt_pk_bf16_f32 v42, v12, v35
	v_add_f32_e32 v12, 1.0, v39
	v_mul_f32_e32 v39, 0xbfb8aa3b, v88
	v_add_f32_e32 v35, 1.0, v40
	v_exp_f32_e32 v40, v39
	v_mul_f32_e32 v39, 0xbfb8aa3b, v114
	v_rcp_f32_e32 v12, v12
	v_rcp_f32_e32 v35, v35
	v_exp_f32_e32 v41, v39
	v_mul_f32_e32 v47, 0xbfb8aa3b, v115
	v_exp_f32_e32 v47, v47
	v_cvt_pk_bf16_f32 v39, v12, v35
	v_add_f32_e32 v12, 1.0, v40
	v_add_f32_e32 v35, 1.0, v41
	v_mul_f32_e32 v40, 0xbfb8aa3b, v95
	v_rcp_f32_e32 v12, v12
	v_rcp_f32_e32 v35, v35
	v_exp_f32_e32 v40, v40
	v_mul_f32_e32 v41, 0xbfb8aa3b, v91
	v_exp_f32_e32 v41, v41
	v_cvt_pk_bf16_f32 v43, v12, v35
	v_add_f32_e32 v12, 1.0, v40
	v_mul_f32_e32 v40, 0xbfb8aa3b, v97
	v_add_f32_e32 v35, 1.0, v41
	v_exp_f32_e32 v40, v40
	v_mul_f32_e32 v41, 0xbfb8aa3b, v93
	v_exp_f32_e32 v41, v41
	v_rcp_f32_e32 v12, v12
	v_add_f32_e32 v40, 1.0, v40
	v_rcp_f32_e32 v44, v40
	v_add_f32_e32 v40, 1.0, v41
	v_mul_f32_e32 v41, 0xbfb8aa3b, v87
	v_exp_f32_e32 v41, v41
	v_rcp_f32_e32 v46, v40
	v_rcp_f32_e32 v35, v35
	v_readlane_b32 s12, v230, 34
	v_add_f32_e32 v40, 1.0, v41
	v_rcp_f32_e32 v41, v40
	v_add_f32_e32 v40, 1.0, v45
	v_mul_f32_e32 v45, 0xbfb8aa3b, v89
	v_exp_f32_e32 v45, v45
	v_rcp_f32_e32 v48, v40
	v_cvt_pk_bf16_f32 v44, v44, v46
	v_mov_b32_e32 v37, v13
	v_add_f32_e32 v40, 1.0, v45
; __device__ __forceinline__ float sigmoid_(float x) { return __builtin_amdgcn_rcpf(1.f + __expf(-x)); }
; __device__ __forceinline__ void gate_tile(int t, const bf16_t* xb, const bf16_t* Wg, bf16_t* G, bf16_t* sm) {
;     ...
; #pragma unroll
;     for (int mt = 0; mt < 4; ++mt) {
;         const int row = tm * 128 + wr * 64 + mt * 16 + fr;
;         const int cbase = tn * 128 + wc * 64 + fq * 16;
;         float v[16]; gather_cols<4>(acc, mt, v);
;         u32x4 o0, o1;
; #pragma unroll
;         for (int q = 0; q < 4; ++q) {
;             o0[q] = pack2(sigmoid_(v[2 * q]), sigmoid_(v[2 * q + 1]));
;             o1[q] = pack2(sigmoid_(v[8 + 2 * q]), sigmoid_(v[8 + 2 * q + 1]));
;         }
;         *(u32x4*)(G + (size_t)row * 4096 + cbase) = o0;
;         *(u32x4*)(G + (size_t)row * 4096 + cbase + 8) = o1;
;     }
	v_rcp_f32_e32 v45, v40
	v_add_f32_e32 v40, 1.0, v47
	v_rcp_f32_e32 v47, v40
	v_cvt_pk_bf16_f32 v40, v12, v35
	v_ashrrev_i32_e32 v35, 31, v34
	v_mul_f32_e32 v12, 0xbfb8aa3b, v78
	v_cvt_pk_bf16_f32 v45, v45, v47
	v_lshlrev_b64 v[46:47], 13, v[34:35]
	v_mul_f32_e32 v35, 0xbfb8aa3b, v74
	v_readlane_b32 s13, v230, 35
	v_exp_f32_e32 v12, v12
	v_exp_f32_e32 v35, v35
	v_lshl_add_u64 v[36:37], s[12:13], 0, v[36:37]
	v_cvt_pk_bf16_f32 v41, v41, v48
	v_lshl_add_u64 v[46:47], v[36:37], 0, v[46:47]
	global_store_dwordx4 v[46:47], v[38:41], off
	v_add_f32_e32 v12, 1.0, v12
	v_add_f32_e32 v35, 1.0, v35
	v_mul_f32_e32 v38, 0xbfb8aa3b, v80
	v_exp_f32_e32 v39, v38
	v_mul_f32_e32 v38, 0xbfb8aa3b, v76
	v_rcp_f32_e32 v12, v12
	v_rcp_f32_e32 v35, v35
	v_exp_f32_e32 v40, v38
	global_store_dwordx4 v[46:47], v[42:45], off offset:16
	v_mul_f32_e32 v47, 0xbfb8aa3b, v119
	v_cvt_pk_bf16_f32 v38, v12, v35
	v_add_f32_e32 v12, 1.0, v39
	v_add_f32_e32 v35, 1.0, v40
	v_mul_f32_e32 v39, 0xbfb8aa3b, v70
	v_rcp_f32_e32 v12, v12
	v_rcp_f32_e32 v35, v35
	v_exp_f32_e32 v39, v39
	v_mul_f32_e32 v40, 0xbfb8aa3b, v116
	v_exp_f32_e32 v40, v40
	v_cvt_pk_bf16_f32 v42, v12, v35
	v_add_f32_e32 v12, 1.0, v39
	v_mul_f32_e32 v39, 0xbfb8aa3b, v72
	v_add_f32_e32 v35, 1.0, v40
	v_exp_f32_e32 v40, v39
	v_mul_f32_e32 v39, 0xbfb8aa3b, v118
	v_rcp_f32_e32 v12, v12
	v_rcp_f32_e32 v35, v35
	v_exp_f32_e32 v41, v39
	v_mul_f32_e32 v45, 0xbfb8aa3b, v117
	v_exp_f32_e32 v45, v45
	v_cvt_pk_bf16_f32 v39, v12, v35
	v_add_f32_e32 v12, 1.0, v40
	v_add_f32_e32 v35, 1.0, v41
	v_mul_f32_e32 v40, 0xbfb8aa3b, v79
	v_rcp_f32_e32 v12, v12
	v_rcp_f32_e32 v35, v35
	v_exp_f32_e32 v40, v40
	v_mul_f32_e32 v41, 0xbfb8aa3b, v75
	v_exp_f32_e32 v41, v41
	v_cvt_pk_bf16_f32 v43, v12, v35
	v_add_f32_e32 v12, 1.0, v40
	v_mul_f32_e32 v40, 0xbfb8aa3b, v81
	v_add_f32_e32 v35, 1.0, v41
	v_exp_f32_e32 v40, v40
	v_mul_f32_e32 v41, 0xbfb8aa3b, v77
	v_exp_f32_e32 v41, v41
	v_exp_f32_e32 v47, v47
	v_add_f32_e32 v40, 1.0, v40
	v_rcp_f32_e32 v44, v40
	v_add_f32_e32 v40, 1.0, v41
	v_mul_f32_e32 v41, 0xbfb8aa3b, v71
	v_exp_f32_e32 v41, v41
	v_rcp_f32_e32 v46, v40
	v_rcp_f32_e32 v12, v12
	v_rcp_f32_e32 v35, v35
	v_add_f32_e32 v40, 1.0, v41
	v_rcp_f32_e32 v41, v40
	v_add_f32_e32 v40, 1.0, v45
	v_mul_f32_e32 v45, 0xbfb8aa3b, v73
	v_exp_f32_e32 v45, v45
	v_rcp_f32_e32 v48, v40
	v_mul_f32_e32 v26, 0xbfb8aa3b, v26
	v_exp_f32_e32 v26, v26
	v_add_f32_e32 v40, 1.0, v45
	v_rcp_f32_e32 v45, v40
	v_add_f32_e32 v40, 1.0, v47
	v_rcp_f32_e32 v47, v40
	v_cvt_pk_bf16_f32 v40, v12, v35
	v_mul_f32_e32 v12, 0xbfb8aa3b, v30
	v_exp_f32_e32 v12, v12
	v_add_f32_e32 v26, 1.0, v26
	v_mul_f32_e32 v30, 0xbfb8aa3b, v32
	v_mul_f32_e32 v28, 0xbfb8aa3b, v28
	v_add_f32_e32 v12, 1.0, v12
	v_cvt_pk_bf16_f32 v44, v44, v46
	v_or_b32_e32 v46, 16, v34
	v_rcp_f32_e32 v12, v12
	v_rcp_f32_e32 v26, v26
	v_exp_f32_e32 v30, v30
	v_exp_f32_e32 v28, v28
	v_cvt_pk_bf16_f32 v45, v45, v47
	v_ashrrev_i32_e32 v47, 31, v46
	v_lshlrev_b64 v[46:47], 13, v[46:47]
	v_cvt_pk_bf16_f32 v41, v41, v48
	v_lshl_add_u64 v[46:47], v[36:37], 0, v[46:47]
	global_store_dwordx4 v[46:47], v[38:41], off
	v_mul_f32_e32 v22, 0xbfb8aa3b, v22
	v_mul_f32_e32 v18, 0xbfb8aa3b, v18
	v_cvt_pk_bf16_f32 v38, v12, v26
	v_add_f32_e32 v12, 1.0, v30
	v_add_f32_e32 v26, 1.0, v28
	v_rcp_f32_e32 v12, v12
	v_rcp_f32_e32 v26, v26
	v_exp_f32_e32 v22, v22
	v_exp_f32_e32 v18, v18
	v_mul_f32_e32 v20, 0xbfb8aa3b, v20
	v_cvt_pk_bf16_f32 v26, v12, v26
	v_add_f32_e32 v12, 1.0, v22
	v_add_f32_e32 v18, 1.0, v18
	v_mul_f32_e32 v22, 0xbfb8aa3b, v24
	v_rcp_f32_e32 v12, v12
	v_rcp_f32_e32 v18, v18
	v_exp_f32_e32 v22, v22
	v_exp_f32_e32 v20, v20
	v_mul_f32_e32 v23, 0xbfb8aa3b, v23
	v_cvt_pk_bf16_f32 v39, v12, v18
; __device__ __forceinline__ float sigmoid_(float x) { return __builtin_amdgcn_rcpf(1.f + __expf(-x)); }
; __device__ __forceinline__ void gate_tile(int t, const bf16_t* xb, const bf16_t* Wg, bf16_t* G, bf16_t* sm) {
;     ...
; #pragma unroll
;     for (int mt = 0; mt < 4; ++mt) {
;         const int row = tm * 128 + wr * 64 + mt * 16 + fr;
;         const int cbase = tn * 128 + wc * 64 + fq * 16;
;         float v[16]; gather_cols<4>(acc, mt, v);
;         u32x4 o0, o1;
; #pragma unroll
;         for (int q = 0; q < 4; ++q) {
;             o0[q] = pack2(sigmoid_(v[2 * q]), sigmoid_(v[2 * q + 1]));
;             o1[q] = pack2(sigmoid_(v[8 + 2 * q]), sigmoid_(v[8 + 2 * q + 1]));
;         }
;         *(u32x4*)(G + (size_t)row * 4096 + cbase) = o0;
;         *(u32x4*)(G + (size_t)row * 4096 + cbase + 8) = o1;
;     }
	v_add_f32_e32 v12, 1.0, v22
	v_add_f32_e32 v18, 1.0, v20
	v_mul_f32_e32 v20, 0xbfb8aa3b, v31
	v_mul_f32_e32 v22, 0xbfb8aa3b, v27
	v_rcp_f32_e32 v12, v12
	v_rcp_f32_e32 v18, v18
	v_exp_f32_e32 v20, v20
	v_exp_f32_e32 v22, v22
	v_mul_f32_e32 v19, 0xbfb8aa3b, v19
	v_exp_f32_e32 v23, v23
	v_exp_f32_e32 v19, v19
	v_cvt_pk_bf16_f32 v27, v12, v18
	v_add_f32_e32 v12, 1.0, v20
	v_add_f32_e32 v18, 1.0, v22
	v_mul_f32_e32 v20, 0xbfb8aa3b, v33
	v_mul_f32_e32 v22, 0xbfb8aa3b, v29
	v_mul_f32_e32 v24, 0xbfb8aa3b, v25
	v_mul_f32_e32 v21, 0xbfb8aa3b, v21
	v_exp_f32_e32 v20, v20
	v_exp_f32_e32 v22, v22
	v_exp_f32_e32 v24, v24
	v_exp_f32_e32 v21, v21
	v_mul_f32_e32 v4, 0xbfb8aa3b, v4
	v_mul_f32_e32 v0, 0xbfb8aa3b, v0
	v_exp_f32_e32 v4, v4
	v_exp_f32_e32 v0, v0
	v_rcp_f32_e32 v12, v12
	v_rcp_f32_e32 v18, v18
	v_add_f32_e32 v23, 1.0, v23
	v_add_f32_e32 v19, 1.0, v19
	v_rcp_f32_e32 v23, v23
	v_rcp_f32_e32 v19, v19
	v_add_f32_e32 v20, 1.0, v20
	v_add_f32_e32 v22, 1.0, v22
	v_add_f32_e32 v24, 1.0, v24
	v_add_f32_e32 v21, 1.0, v21
	v_rcp_f32_e32 v20, v20
	v_rcp_f32_e32 v22, v22
	v_rcp_f32_e32 v24, v24
	v_rcp_f32_e32 v21, v21
	v_add_f32_e32 v4, 1.0, v4
	v_add_f32_e32 v0, 1.0, v0
	v_mul_f32_e32 v6, 0xbfb8aa3b, v6
	v_mul_f32_e32 v2, 0xbfb8aa3b, v2
	v_cvt_pk_bf16_f32 v40, v12, v18
	v_or_b32_e32 v18, 32, v34
	v_rcp_f32_e32 v4, v4
	v_rcp_f32_e32 v0, v0
	v_exp_f32_e32 v6, v6
	v_exp_f32_e32 v2, v2
	v_cvt_pk_bf16_f32 v41, v23, v19
	v_ashrrev_i32_e32 v19, 31, v18
	v_lshlrev_b64 v[18:19], 13, v[18:19]
	v_cvt_pk_bf16_f32 v28, v20, v22
	v_cvt_pk_bf16_f32 v29, v24, v21
	v_lshl_add_u64 v[18:19], v[36:37], 0, v[18:19]
	global_store_dwordx4 v[18:19], v[38:41], off
	v_mul_f32_e32 v12, 0xbfb8aa3b, v14
	v_mul_f32_e32 v8, 0xbfb8aa3b, v8
	global_store_dwordx4 v[18:19], v[26:29], off offset:16
	v_cvt_pk_bf16_f32 v19, v4, v0
	v_add_f32_e32 v0, 1.0, v6
	v_add_f32_e32 v2, 1.0, v2
	v_mul_f32_e32 v4, 0xbfb8aa3b, v15
	v_mul_f32_e32 v6, 0xbfb8aa3b, v9
	v_exp_f32_e32 v12, v12
	v_exp_f32_e32 v8, v8
	v_rcp_f32_e32 v0, v0
	v_rcp_f32_e32 v2, v2
	v_exp_f32_e32 v4, v4
	v_exp_f32_e32 v6, v6
	v_mul_f32_e32 v5, 0xbfb8aa3b, v5
	v_mul_f32_e32 v1, 0xbfb8aa3b, v1
	v_exp_f32_e32 v5, v5
	v_exp_f32_e32 v1, v1
	v_add_f32_e32 v12, 1.0, v12
	v_add_f32_e32 v8, 1.0, v8
	v_mul_f32_e32 v14, 0xbfb8aa3b, v16
	v_mul_f32_e32 v10, 0xbfb8aa3b, v10
	v_cvt_pk_bf16_f32 v9, v0, v2
	v_add_f32_e32 v0, 1.0, v4
	v_add_f32_e32 v2, 1.0, v6
	v_mul_f32_e32 v4, 0xbfb8aa3b, v17
	v_mul_f32_e32 v6, 0xbfb8aa3b, v11
	v_mul_f32_e32 v7, 0xbfb8aa3b, v7
	v_mul_f32_e32 v3, 0xbfb8aa3b, v3
	v_rcp_f32_e32 v12, v12
	v_rcp_f32_e32 v8, v8
	v_exp_f32_e32 v14, v14
	v_exp_f32_e32 v10, v10
	v_exp_f32_e32 v4, v4
	v_exp_f32_e32 v6, v6
	v_exp_f32_e32 v7, v7
	v_exp_f32_e32 v3, v3
	v_rcp_f32_e32 v0, v0
	v_rcp_f32_e32 v2, v2
	v_add_f32_e32 v5, 1.0, v5
	v_add_f32_e32 v1, 1.0, v1
	v_rcp_f32_e32 v5, v5
	v_rcp_f32_e32 v1, v1
	v_cvt_pk_bf16_f32 v18, v12, v8
	v_add_f32_e32 v8, 1.0, v14
	v_add_f32_e32 v10, 1.0, v10
	v_add_f32_e32 v4, 1.0, v4
	v_add_f32_e32 v6, 1.0, v6
	v_add_f32_e32 v7, 1.0, v7
	v_add_f32_e32 v3, 1.0, v3
	v_rcp_f32_e32 v8, v8
	v_rcp_f32_e32 v10, v10
	v_rcp_f32_e32 v4, v4
	v_rcp_f32_e32 v6, v6
	v_rcp_f32_e32 v7, v7
	v_rcp_f32_e32 v3, v3
	v_cvt_pk_bf16_f32 v20, v0, v2
	v_or_b32_e32 v0, 48, v34
	v_cvt_pk_bf16_f32 v21, v5, v1
	v_ashrrev_i32_e32 v1, 31, v0
	v_lshlrev_b64 v[0:1], 13, v[0:1]
	v_lshl_add_u64 v[0:1], v[36:37], 0, v[0:1]
	global_store_dwordx4 v[46:47], v[42:45], off offset:16
	v_cvt_pk_bf16_f32 v8, v8, v10
	v_cvt_pk_bf16_f32 v10, v4, v6
	v_cvt_pk_bf16_f32 v11, v7, v3
	global_store_dwordx4 v[0:1], v[18:21], off
	global_store_dwordx4 v[0:1], v[8:11], off offset:16
	s_mov_b64 s[12:13], 0

; __device__ __forceinline__ int tidx() { int t = threadIdx.x; asm volatile("" : "+v"(t)); return t; }
; template <int NT>
; __device__ __forceinline__ void gemm_tile(f32x4 (&acc)[4][NT], const bf16_t* A, int lda, const bf16_t* B, int ldb, int K, bf16_t* sm) {
;     const int tid_ = tidx();
;     bf16_t* sA = sm; bf16_t* sB = sm + 128 * LDT;
;     const int tid = tid_, lane = tid & 63, wid = tid >> 6, wr = wid >> 1, wc = wid & 1;
;     const int fr = lane & 15, fq = lane >> 4;
;     const int lrow = tid >> 3, lkc = tid & 7;
;     const bf16_t* ga = A + (size_t)lrow * lda + lkc * 8;
;     const bf16_t* gb = B + (size_t)lrow * ldb + lkc * 8;
;     int sbrow[NT];
; #pragma unroll
;     for (int i = 0; i < NT; ++i) { const int g = lrow + 32 * i, W_ = 16 * NT, rem = g % W_; sbrow[i] = (g / W_) * W_ + (rem % NT) * 16 + rem / NT; }
;     u32x4 ra0[4], rb0[NT];
; #pragma unroll
;     for (int i = 0; i < 4; ++i) ra0[i] = *(const u32x4*)(ga + (size_t)(32 * i) * lda);
; #pragma unroll
;     for (int i = 0; i < NT; ++i) rb0[i] = *(const u32x4*)(gb + (size_t)(32 * i) * ldb);
; __device__ __forceinline__ void phase_proj(const bf16_t* xb, const bf16_t* W, bf16_t* P, bf16_t* sm) {
;     ...
;     for (int t = blockIdx.x; t < 136 * 37; t += gridDim.x) {
;         const int tm = t / 37, tn = t % 37;
;         f32x4 acc[4][4]; zero_acc<4>(acc);
;         gemm_tile<4>(acc, xb + (size_t)tm * 128 * 1024, 1024, W + (size_t)tn * 128 * 1024, 1024, 1024, sm);
.LBB0_464:
	v_mov_b32_e32 v38, v192
	s_mul_hi_i32 s2, s13, 0xdd67c8a7
	v_ashrrev_i32_e32 v0, 31, v38
	s_waitcnt vmcnt(6)
	v_ashrrev_i32_e32 v30, 3, v38
	v_lshrrev_b32_e32 v0, 26, v0
	v_add_u32_e32 v0, v30, v0
	v_lshrrev_b32_e32 v1, 6, v0
	v_mul_i32_i24_e32 v1, 64, v1
	v_sub_u32_e32 v1, v30, v1
	v_lshrrev_b16_sdwa v2, v196, sext(v1) dst_sel:DWORD dst_unused:UNUSED_PAD src0_sel:DWORD src1_sel:BYTE_0
	v_and_b32_e32 v2, 3, v2
	v_add_u16_e32 v2, v1, v2
	v_ashrrev_i16_sdwa v3, v197, sext(v2) dst_sel:DWORD dst_unused:UNUSED_PAD src0_sel:DWORD src1_sel:BYTE_0
	v_and_b32_e32 v2, 0xfc, v2
	v_sub_u16_e32 v1, v1, v2
	v_and_b32_e32 v0, 0x7ffffc0, v0
	v_lshlrev_b32_sdwa v1, v198, sext(v1) dst_sel:DWORD dst_unused:UNUSED_PAD src0_sel:DWORD src1_sel:BYTE_0
	v_bfe_i32 v2, v3, 0, 16
	v_add3_u32 v39, v0, v2, v1
	v_add_u32_e32 v0, 32, v30
	v_ashrrev_i32_e32 v1, 31, v0
	v_lshrrev_b32_e32 v1, 26, v1
	v_add_u32_e32 v1, v0, v1
	v_lshrrev_b32_e32 v2, 6, v1
	v_mul_i32_i24_e32 v2, 64, v2
	v_sub_u32_e32 v0, v0, v2
	v_lshrrev_b16_sdwa v2, v196, sext(v0) dst_sel:DWORD dst_unused:UNUSED_PAD src0_sel:DWORD src1_sel:BYTE_0
	v_and_b32_e32 v2, 3, v2
	v_add_u16_e32 v2, v0, v2
	v_ashrrev_i16_sdwa v3, v197, sext(v2) dst_sel:DWORD dst_unused:UNUSED_PAD src0_sel:DWORD src1_sel:BYTE_0
	v_and_b32_e32 v2, 0xfc, v2
	v_sub_u16_e32 v0, v0, v2
	v_and_b32_e32 v1, 0x7ffffc0, v1
	v_lshlrev_b32_sdwa v0, v198, sext(v0) dst_sel:DWORD dst_unused:UNUSED_PAD src0_sel:DWORD src1_sel:BYTE_0
	v_bfe_i32 v2, v3, 0, 16
	v_add3_u32 v40, v1, v2, v0
	v_add_u32_e32 v0, 64, v30
	v_ashrrev_i32_e32 v1, 31, v0
	v_lshrrev_b32_e32 v1, 26, v1
	v_add_u32_e32 v1, v0, v1
	v_lshrrev_b32_e32 v2, 6, v1
	v_mul_i32_i24_e32 v2, 64, v2
	v_sub_u32_e32 v0, v0, v2
	v_lshrrev_b16_sdwa v2, v196, sext(v0) dst_sel:DWORD dst_unused:UNUSED_PAD src0_sel:DWORD src1_sel:BYTE_0
	v_and_b32_e32 v2, 3, v2
	v_add_u16_e32 v2, v0, v2
	v_ashrrev_i16_sdwa v3, v197, sext(v2) dst_sel:DWORD dst_unused:UNUSED_PAD src0_sel:DWORD src1_sel:BYTE_0
	v_and_b32_e32 v2, 0xfc, v2
	v_sub_u16_e32 v0, v0, v2
	v_and_b32_e32 v1, 0x7ffffc0, v1
	v_lshlrev_b32_sdwa v0, v198, sext(v0) dst_sel:DWORD dst_unused:UNUSED_PAD src0_sel:DWORD src1_sel:BYTE_0
	v_bfe_i32 v2, v3, 0, 16
	s_waitcnt lgkmcnt(0)
	v_add3_u32 v41, v1, v2, v0
	v_add_u32_e32 v0, 0x60, v30
	v_ashrrev_i32_e32 v1, 31, v0
	v_lshrrev_b32_e32 v1, 26, v1
	v_add_u32_e32 v1, v0, v1
	s_add_i32 s2, s2, s13
	v_lshrrev_b32_e32 v2, 6, v1
	s_lshr_b32 s14, s2, 31
	s_ashr_i32 s2, s2, 5
	v_mul_i32_i24_e32 v2, 64, v2
	s_add_i32 s14, s2, s14
	v_sub_u32_e32 v0, v0, v2
	s_mul_i32 s2, s14, 37
	s_ashr_i32 s15, s14, 31
	v_lshrrev_b16_sdwa v2, v196, sext(v0) dst_sel:DWORD dst_unused:UNUSED_PAD src0_sel:DWORD src1_sel:BYTE_0
	s_sub_i32 s18, s13, s2
	s_lshl_b64 s[22:23], s[14:15], 18
	v_and_b32_e32 v2, 3, v2
	s_add_u32 s40, s80, s22
	v_add_u16_e32 v2, v0, v2
	s_addc_u32 s41, s81, s23
	s_ashr_i32 s19, s18, 31
	v_ashrrev_i16_sdwa v3, v197, sext(v2) dst_sel:DWORD dst_unused:UNUSED_PAD src0_sel:DWORD src1_sel:BYTE_0
	v_and_b32_e32 v2, 0xfc, v2
	s_lshl_b64 s[24:25], s[18:19], 18
	v_sub_u16_e32 v0, v0, v2
	s_add_u32 s42, s11, s24
	v_and_b32_e32 v1, 0x7ffffc0, v1
	v_lshlrev_b32_sdwa v0, v198, sext(v0) dst_sel:DWORD dst_unused:UNUSED_PAD src0_sel:DWORD src1_sel:BYTE_0
	v_bfe_i32 v2, v3, 0, 16
	v_ashrrev_i32_e32 v31, 31, v30
	s_addc_u32 s43, s12, s25
	v_add3_u32 v42, v1, v2, v0
	v_lshlrev_b64 v[32:33], 11, v[30:31]
	v_lshlrev_b32_e32 v2, 4, v38
	v_lshl_add_u64 v[0:1], s[42:43], 0, v[32:33]
	v_and_b32_e32 v12, 0x70, v2
	v_lshl_add_u64 v[8:9], v[0:1], 0, v[12:13]
	v_add_co_u32_e32 v0, vcc, s7, v8
	v_and_b32_e32 v31, 15, v38
	s_nop 0
	v_addc_co_u32_e32 v1, vcc, 0, v9, vcc
	v_add_co_u32_e32 v10, vcc, s37, v8
	v_mov_b32_e32 v250, v8
	v_mov_b32_e32 v251, v9
	s_nop 0
	v_addc_co_u32_e32 v11, vcc, 0, v9, vcc
	v_add_co_u32_e32 v14, vcc, s73, v8
	v_lshrrev_b32_e32 v44, 1, v38
	s_nop 0
	v_addc_co_u32_e32 v15, vcc, 0, v9, vcc
	s_nop 0
	v_lshl_add_u64 v[14:15], s[40:41], 0, v[32:33]
	v_lshl_add_u64 v[26:27], v[14:15], 0, v[12:13]
	v_add_co_u32_e32 v14, vcc, s7, v26
	v_and_or_b32 v31, v44, s3, v31
	s_nop 0
	v_addc_co_u32_e32 v15, vcc, 0, v27, vcc
	v_add_co_u32_e32 v28, vcc, s37, v26
	v_mov_b32_e32 v248, v26
	v_mov_b32_e32 v249, v27
	s_nop 0
	v_addc_co_u32_e32 v29, vcc, 0, v27, vcc
	v_add_co_u32_e32 v34, vcc, s73, v26
	v_mul_lo_u32 v44, v31, s89
	s_nop 0
	v_addc_co_u32_e32 v35, vcc, 0, v27, vcc
	s_nop 0
	v_mul_lo_u32 v45, v30, s89
	v_lshl_add_u64 v[30:31], s[22:23], 0, v[32:33]
	v_or_b32_e32 v30, v30, v12
	v_lshl_add_u64 v[98:99], s[58:59], 0, v[30:31]
	v_lshl_add_u64 v[30:31], s[24:25], 0, v[32:33]
	v_and_b32_e32 v43, 48, v38
	v_and_b32_e32 v38, 0x4f, v38
	v_or_b32_e32 v30, v30, v12
	v_mul_u32_u24_e32 v38, 0xa0, v38
	v_mul_lo_u32 v39, v39, s89
	v_mul_lo_u32 v40, v40, s89
	v_mul_lo_u32 v41, v41, s89
	v_mul_lo_u32 v42, v42, s89
	v_lshl_add_u64 v[100:101], s[58:59], 0, v[30:31]
	v_mov_b32_e32 v30, 0
	s_mov_b64 s[22:23], 0
	v_add_u32_e32 v105, v12, v45
	v_add_u32_e32 v106, v12, v39
	v_add_u32_e32 v107, v12, v40
; template <int NT>
; __device__ __forceinline__ void gemm_tile(f32x4 (&acc)[4][NT], const bf16_t* A, int lda, const bf16_t* B, int ldb, int K, bf16_t* sm) {
;     ...
;     for (int kt = 0; kt < nk; ++kt) {
;         lds_barrier();
; #pragma unroll
;         for (int i = 0; i < 4; ++i) *(u32x4*)(sA + (lrow + 32 * i) * LDT + lkc * 8) = ra0[i];
; #pragma unroll
;         for (int i = 0; i < NT; ++i) *(u32x4*)(sB + sbrow[i] * LDT + lkc * 8) = rb0[i];
;         lds_barrier();
;         if (kt + 1 < nk) {
;             ga += 64; gb += 64;
; #pragma unroll
;             for (int i = 0; i < 4; ++i) ra0[i] = *(const u32x4*)(ga + (size_t)(32 * i) * lda);
; #pragma unroll
;             for (int i = 0; i < NT; ++i) rb0[i] = *(const u32x4*)(gb + (size_t)(32 * i) * ldb);
;         }
;         __builtin_amdgcn_sched_barrier(0);
;         gemm_compute<NT>(acc, sA, sB, wr, wc, fr, fq);
	v_add_u32_e32 v108, v12, v41
	v_add_u32_e32 v109, v12, v42
	v_add_u32_e32 v104, v43, v44
	v_add_u32_e32 v12, v43, v38
	v_mov_b32_e32 v31, v30
	v_mov_b32_e32 v32, v30
	v_mov_b32_e32 v33, v30
	v_mov_b32_e32 v38, v30
	v_mov_b32_e32 v39, v30
	v_mov_b32_e32 v40, v30
	v_mov_b32_e32 v41, v30
	v_mov_b32_e32 v42, v30
	v_mov_b32_e32 v43, v30
	v_mov_b32_e32 v44, v30
	v_mov_b32_e32 v45, v30
	v_mov_b32_e32 v46, v30
	v_mov_b32_e32 v47, v30
	v_mov_b32_e32 v48, v30
	v_mov_b32_e32 v49, v30
	v_mov_b32_e32 v50, v30
	v_mov_b32_e32 v51, v30
	v_mov_b32_e32 v52, v30
	v_mov_b32_e32 v53, v30
	v_mov_b32_e32 v54, v30
	v_mov_b32_e32 v55, v30
	v_mov_b32_e32 v56, v30
	v_mov_b32_e32 v57, v30
	v_mov_b32_e32 v58, v30
	v_mov_b32_e32 v59, v30
	v_mov_b32_e32 v60, v30
	v_mov_b32_e32 v61, v30
	v_mov_b32_e32 v62, v30
	v_mov_b32_e32 v63, v30
	v_mov_b32_e32 v64, v30
	v_mov_b32_e32 v65, v30
	v_mov_b32_e32 v66, v30
	v_mov_b32_e32 v67, v30
	v_mov_b32_e32 v68, v30
	v_mov_b32_e32 v69, v30
	v_mov_b32_e32 v70, v30
	v_mov_b32_e32 v71, v30
	v_mov_b32_e32 v72, v30
	v_mov_b32_e32 v73, v30
	v_mov_b32_e32 v74, v30
	v_mov_b32_e32 v75, v30
	v_mov_b32_e32 v76, v30
	v_mov_b32_e32 v77, v30
	v_mov_b32_e32 v78, v30
	v_mov_b32_e32 v79, v30
	v_mov_b32_e32 v80, v30
	v_mov_b32_e32 v81, v30
	v_mov_b32_e32 v82, v30
	v_mov_b32_e32 v83, v30
	v_mov_b32_e32 v84, v30
	v_mov_b32_e32 v85, v30
	v_mov_b32_e32 v86, v30
	v_mov_b32_e32 v87, v30
	v_mov_b32_e32 v88, v30
	v_mov_b32_e32 v89, v30
	v_mov_b32_e32 v90, v30
	v_mov_b32_e32 v91, v30
	v_mov_b32_e32 v92, v30
	v_mov_b32_e32 v93, v30
	v_mov_b32_e32 v94, v30
	v_mov_b32_e32 v95, v30
	v_mov_b32_e32 v96, v30
	v_mov_b32_e32 v97, v30
	v_writelane_b32 v234, s90, 0
	v_writelane_b32 v234, s91, 1
	v_writelane_b32 v234, s92, 2
	v_writelane_b32 v234, s93, 3
	v_writelane_b32 v234, s94, 4
	v_writelane_b32 v234, s95, 5
	v_bfe_u32 v160, v192, 3, 3
	v_and_b32_e32 v161, 7, v192
	v_xor_b32_e32 v161, v160, v161
	v_lshlrev_b32_e32 v161, 4, v161
	v_lshrrev_b32_e32 v162, 6, v192
	v_lshl_add_u32 v163, v162, 5, v160
	v_mul_u32_u24_e32 v163, 0x800, v163
	v_add_u32_e32 v236, v163, v161
	v_add_u32_e32 v237, 0x3c00, v236
	v_add_u32_e32 v238, 0x3c00, v237
	v_add_u32_e32 v239, 0x3c00, v238
	v_lshrrev_b32_e32 v163, 7, v192
	v_bfe_u32 v162, v192, 6, 1
	v_lshlrev_b32_e32 v163, 6, v163
	v_lshl_add_u32 v163, v160, 2, v163
	v_lshl_add_u32 v163, v162, 1, v163
	v_mul_u32_u24_e32 v163, 0x800, v163
	v_add_u32_e32 v240, v163, v161
	v_add_u32_e32 v241, 0xfc00, v240
	v_subrev_u32_e32 v242, 0xfc00, v241
	v_add_u32_e32 v243, 0xfc00, v242
	v_and_b32_e32 v160, 15, v192
	v_bfe_u32 v161, v192, 4, 2
	v_and_b32_e32 v162, 7, v160
	v_xor_b32_e32 v161, v161, v162
	v_lshlrev_b32_e32 v161, 4, v161
	v_lshl_add_u32 v161, v160, 7, v161
	v_lshrrev_b32_e32 v162, 7, v192
	v_lshl_add_u32 v244, v162, 13, v161
	v_bfe_u32 v162, v192, 6, 1
	v_lshl_add_u32 v246, v162, 13, v161
	v_add_u32_e32 v246, 0x4000, v246
	v_xor_b32_e32 v245, 64, v244
	v_xor_b32_e32 v247, 64, v246
	v_lshrrev_b32_e32 v160, 6, v192
	s_nop 0
	v_readfirstlane_b32 s94, v160
	v_readfirstlane_b32 s90, v248
	v_readfirstlane_b32 s91, v249
	v_readfirstlane_b32 s92, v250
	v_readfirstlane_b32 s93, v251
	s_mul_i32 s95, s94, 0x4000
	s_sub_u32 s90, s90, s95
	s_subb_u32 s91, s91, 0
	s_mul_i32 s95, s94, 0x4000
	s_sub_u32 s92, s92, s95
	s_subb_u32 s93, s93, 0
	s_lshl_b32 s94, s94, 10
	s_waitcnt lgkmcnt(0)
	s_barrier
	s_lshl_b32 s95, s94, 2
	s_add_u32 m0, s95, 0x0
	s_nop 0
	global_load_lds_dwordx4 v236, s[90:91]
	global_load_lds_dwordx4 v237, s[90:91] offset:1024
	global_load_lds_dwordx4 v238, s[90:91] offset:2048
	global_load_lds_dwordx4 v239, s[90:91] offset:3072
	s_mul_i32 s95, s94, 4
	s_add_u32 m0, s95, 0x4000
	s_nop 0
	global_load_lds_dwordx4 v240, s[92:93]
	global_load_lds_dwordx4 v241, s[92:93] offset:1024
	global_load_lds_dwordx4 v242, s[92:93] offset:2048
	global_load_lds_dwordx4 v243, s[92:93] offset:3072
	s_add_u32 s90, s90, 0x80
	s_addc_u32 s91, s91, 0
	s_add_u32 s92, s92, 0x80
	s_addc_u32 s93, s93, 0
	s_waitcnt vmcnt(0)
	s_barrier
	s_lshl_b32 s95, s94, 2
	s_add_u32 m0, s95, 0x8000
	s_nop 0
	global_load_lds_dwordx4 v236, s[90:91]
	global_load_lds_dwordx4 v237, s[90:91] offset:1024
	global_load_lds_dwordx4 v238, s[90:91] offset:2048
	global_load_lds_dwordx4 v239, s[90:91] offset:3072
	s_mul_i32 s95, s94, 4
	s_add_u32 m0, s95, 0xc000
	s_nop 0
	global_load_lds_dwordx4 v240, s[92:93]
	global_load_lds_dwordx4 v241, s[92:93] offset:1024
	global_load_lds_dwordx4 v242, s[92:93] offset:2048
	global_load_lds_dwordx4 v243, s[92:93] offset:3072
	s_add_u32 s90, s90, 0x80
	s_addc_u32 s91, s91, 0
	s_add_u32 s92, s92, 0x80
	s_addc_u32 s93, s93, 0
	ds_read_b128 v[110:113], v244 offset:0
	ds_read_b128 v[114:117], v244 offset:2048
	ds_read_b128 v[118:121], v244 offset:4096
	ds_read_b128 v[122:125], v244 offset:6144
	ds_read_b128 v[126:129], v246 offset:0
	ds_read_b128 v[130:133], v246 offset:2048
	ds_read_b128 v[134:137], v246 offset:4096
	ds_read_b128 v[138:141], v246 offset:6144
	s_movk_i32 s95, 0x6
	s_cmp_eq_u32 s95, 0
	s_cbranch_scc1 .Lgemm_x465

; template <int NT>
; __device__ __forceinline__ void gemm_compute(f32x4 (&acc)[4][NT], const bf16_t* sA, const bf16_t* sB, int wr, int wc, int fr, int fq) {
; #pragma unroll
;     for (int ks = 0; ks < 2; ++ks) {
;         bf16x8 a[4], b[NT];
; #pragma unroll
;         for (int mt = 0; mt < 4; ++mt) a[mt] = *(const bf16x8*)(sA + (wr * 64 + mt * 16 + fr) * LDT + ks * 32 + fq * 8);
; #pragma unroll
;         for (int nt = 0; nt < NT; ++nt) b[nt] = *(const bf16x8*)(sB + (wc * 16 * NT + nt * 16 + fr) * LDT + ks * 32 + fq * 8);
;         __builtin_amdgcn_s_setprio(1);
; #pragma unroll
;         for (int mt = 0; mt < 4; ++mt)
; #pragma unroll
;             for (int nt = 0; nt < NT; ++nt)
;                 acc[mt][nt] = __builtin_amdgcn_mfma_f32_16x16x32_bf16(b[nt], a[mt], acc[mt][nt], 0, 0, 0);
;         __builtin_amdgcn_s_setprio(0);
;     }
; template <int NT>
; __device__ __forceinline__ void gemm_tile(f32x4 (&acc)[4][NT], const bf16_t* A, int lda, const bf16_t* B, int ldb, int K, bf16_t* sm) {
;     ...
;     for (int kt = 0; kt < nk; ++kt) {
;         lds_barrier();
; #pragma unroll
;         for (int i = 0; i < 4; ++i) *(u32x4*)(sA + (lrow + 32 * i) * LDT + lkc * 8) = ra0[i];
; #pragma unroll
;         for (int i = 0; i < NT; ++i) *(u32x4*)(sB + sbrow[i] * LDT + lkc * 8) = rb0[i];
;         lds_barrier();
;         if (kt + 1 < nk) {
;             ga += 64; gb += 64;
; #pragma unroll
;             for (int i = 0; i < 4; ++i) ra0[i] = *(const u32x4*)(ga + (size_t)(32 * i) * lda);
; #pragma unroll
;             for (int i = 0; i < NT; ++i) rb0[i] = *(const u32x4*)(gb + (size_t)(32 * i) * ldb);
;         }
;         __builtin_amdgcn_sched_barrier(0);
;         gemm_compute<NT>(acc, sA, sB, wr, wc, fr, fq);
;         __builtin_amdgcn_sched_barrier(0);
;     }
.Lgemm_x465:
	ds_read_b128 v[160:163], v245 offset:0
	ds_read_b128 v[164:167], v245 offset:2048
	ds_read_b128 v[168:171], v245 offset:4096
	ds_read_b128 v[172:175], v245 offset:6144
	ds_read_b128 v[176:179], v247 offset:0
	ds_read_b128 v[180:183], v247 offset:2048
	ds_read_b128 v[184:187], v247 offset:4096
	ds_read_b128 v[188:191], v247 offset:6144
	s_setprio 1
	s_waitcnt lgkmcnt(11)
	v_mfma_f32_16x16x32_bf16 v[94:97], v[126:129], v[110:113], v[94:97]
	s_waitcnt lgkmcnt(10)
	v_mfma_f32_16x16x32_bf16 v[90:93], v[130:133], v[110:113], v[90:93]
	s_waitcnt lgkmcnt(9)
	v_mfma_f32_16x16x32_bf16 v[86:89], v[134:137], v[110:113], v[86:89]
	s_waitcnt lgkmcnt(8)
	v_mfma_f32_16x16x32_bf16 v[82:85], v[138:141], v[110:113], v[82:85]
	v_mfma_f32_16x16x32_bf16 v[78:81], v[126:129], v[114:117], v[78:81]
	v_mfma_f32_16x16x32_bf16 v[74:77], v[130:133], v[114:117], v[74:77]
	v_mfma_f32_16x16x32_bf16 v[70:73], v[134:137], v[114:117], v[70:73]
	v_mfma_f32_16x16x32_bf16 v[66:69], v[138:141], v[114:117], v[66:69]
	v_mfma_f32_16x16x32_bf16 v[62:65], v[126:129], v[118:121], v[62:65]
	v_mfma_f32_16x16x32_bf16 v[58:61], v[130:133], v[118:121], v[58:61]
	v_mfma_f32_16x16x32_bf16 v[54:57], v[134:137], v[118:121], v[54:57]
	v_mfma_f32_16x16x32_bf16 v[50:53], v[138:141], v[118:121], v[50:53]
	v_mfma_f32_16x16x32_bf16 v[46:49], v[126:129], v[122:125], v[46:49]
	v_mfma_f32_16x16x32_bf16 v[42:45], v[130:133], v[122:125], v[42:45]
	v_mfma_f32_16x16x32_bf16 v[38:41], v[134:137], v[122:125], v[38:41]
	v_mfma_f32_16x16x32_bf16 v[30:33], v[138:141], v[122:125], v[30:33]
	s_setprio 0
	s_waitcnt vmcnt(0) lgkmcnt(0)
	s_barrier
	ds_read_b128 v[110:113], v244 offset:32768
	ds_read_b128 v[114:117], v244 offset:34816
	ds_read_b128 v[118:121], v244 offset:36864
	ds_read_b128 v[122:125], v244 offset:38912
	ds_read_b128 v[126:129], v246 offset:32768
	ds_read_b128 v[130:133], v246 offset:34816
	ds_read_b128 v[134:137], v246 offset:36864
	ds_read_b128 v[138:141], v246 offset:38912
	s_setprio 1
	v_mfma_f32_16x16x32_bf16 v[94:97], v[176:179], v[160:163], v[94:97]
	s_lshl_b32 s95, s94, 2
	s_add_u32 m0, s95, 0x0
	s_nop 0
	global_load_lds_dwordx4 v236, s[90:91]
	v_mfma_f32_16x16x32_bf16 v[90:93], v[180:183], v[160:163], v[90:93]
	v_mfma_f32_16x16x32_bf16 v[86:89], v[184:187], v[160:163], v[86:89]
	global_load_lds_dwordx4 v237, s[90:91] offset:1024
	v_mfma_f32_16x16x32_bf16 v[82:85], v[188:191], v[160:163], v[82:85]
	v_mfma_f32_16x16x32_bf16 v[78:81], v[176:179], v[164:167], v[78:81]
	global_load_lds_dwordx4 v238, s[90:91] offset:2048
	v_mfma_f32_16x16x32_bf16 v[74:77], v[180:183], v[164:167], v[74:77]
	v_mfma_f32_16x16x32_bf16 v[70:73], v[184:187], v[164:167], v[70:73]
	global_load_lds_dwordx4 v239, s[90:91] offset:3072
	v_mfma_f32_16x16x32_bf16 v[66:69], v[188:191], v[164:167], v[66:69]
	v_mfma_f32_16x16x32_bf16 v[62:65], v[176:179], v[168:171], v[62:65]
	s_mul_i32 s95, s94, 4
	s_add_u32 m0, s95, 0x4000
	s_nop 0
	global_load_lds_dwordx4 v240, s[92:93]
	v_mfma_f32_16x16x32_bf16 v[58:61], v[180:183], v[168:171], v[58:61]
	v_mfma_f32_16x16x32_bf16 v[54:57], v[184:187], v[168:171], v[54:57]
	global_load_lds_dwordx4 v241, s[92:93] offset:1024
	v_mfma_f32_16x16x32_bf16 v[50:53], v[188:191], v[168:171], v[50:53]
	v_mfma_f32_16x16x32_bf16 v[46:49], v[176:179], v[172:175], v[46:49]
	global_load_lds_dwordx4 v242, s[92:93] offset:2048
	v_mfma_f32_16x16x32_bf16 v[42:45], v[180:183], v[172:175], v[42:45]
	v_mfma_f32_16x16x32_bf16 v[38:41], v[184:187], v[172:175], v[38:41]
	global_load_lds_dwordx4 v243, s[92:93] offset:3072
	v_mfma_f32_16x16x32_bf16 v[30:33], v[188:191], v[172:175], v[30:33]
	s_add_u32 s90, s90, 0x80
	s_addc_u32 s91, s91, 0
	s_add_u32 s92, s92, 0x80
	s_addc_u32 s93, s93, 0
	s_setprio 0
	ds_read_b128 v[160:163], v245 offset:32768
	ds_read_b128 v[164:167], v245 offset:34816
	ds_read_b128 v[168:171], v245 offset:36864
	ds_read_b128 v[172:175], v245 offset:38912
	ds_read_b128 v[176:179], v247 offset:32768
	ds_read_b128 v[180:183], v247 offset:34816
	ds_read_b128 v[184:187], v247 offset:36864
	ds_read_b128 v[188:191], v247 offset:38912
	s_setprio 1
	s_waitcnt lgkmcnt(11)
	v_mfma_f32_16x16x32_bf16 v[94:97], v[126:129], v[110:113], v[94:97]
	s_waitcnt lgkmcnt(10)
	v_mfma_f32_16x16x32_bf16 v[90:93], v[130:133], v[110:113], v[90:93]
	s_waitcnt lgkmcnt(9)
	v_mfma_f32_16x16x32_bf16 v[86:89], v[134:137], v[110:113], v[86:89]
	s_waitcnt lgkmcnt(8)
	v_mfma_f32_16x16x32_bf16 v[82:85], v[138:141], v[110:113], v[82:85]
	v_mfma_f32_16x16x32_bf16 v[78:81], v[126:129], v[114:117], v[78:81]
	v_mfma_f32_16x16x32_bf16 v[74:77], v[130:133], v[114:117], v[74:77]
	v_mfma_f32_16x16x32_bf16 v[70:73], v[134:137], v[114:117], v[70:73]
	v_mfma_f32_16x16x32_bf16 v[66:69], v[138:141], v[114:117], v[66:69]
	v_mfma_f32_16x16x32_bf16 v[62:65], v[126:129], v[118:121], v[62:65]
	v_mfma_f32_16x16x32_bf16 v[58:61], v[130:133], v[118:121], v[58:61]
	v_mfma_f32_16x16x32_bf16 v[54:57], v[134:137], v[118:121], v[54:57]
	v_mfma_f32_16x16x32_bf16 v[50:53], v[138:141], v[118:121], v[50:53]
	v_mfma_f32_16x16x32_bf16 v[46:49], v[126:129], v[122:125], v[46:49]
	v_mfma_f32_16x16x32_bf16 v[42:45], v[130:133], v[122:125], v[42:45]
	v_mfma_f32_16x16x32_bf16 v[38:41], v[134:137], v[122:125], v[38:41]
	v_mfma_f32_16x16x32_bf16 v[30:33], v[138:141], v[122:125], v[30:33]
	s_setprio 0
	s_waitcnt vmcnt(0) lgkmcnt(0)
	s_barrier
; template <int NT>
; __device__ __forceinline__ void gemm_compute(f32x4 (&acc)[4][NT], const bf16_t* sA, const bf16_t* sB, int wr, int wc, int fr, int fq) {
; #pragma unroll
;     for (int ks = 0; ks < 2; ++ks) {
;         bf16x8 a[4], b[NT];
; #pragma unroll
;         for (int mt = 0; mt < 4; ++mt) a[mt] = *(const bf16x8*)(sA + (wr * 64 + mt * 16 + fr) * LDT + ks * 32 + fq * 8);
; #pragma unroll
;         for (int nt = 0; nt < NT; ++nt) b[nt] = *(const bf16x8*)(sB + (wc * 16 * NT + nt * 16 + fr) * LDT + ks * 32 + fq * 8);
;         __builtin_amdgcn_s_setprio(1);
; #pragma unroll
;         for (int mt = 0; mt < 4; ++mt)
; #pragma unroll
;             for (int nt = 0; nt < NT; ++nt)
;                 acc[mt][nt] = __builtin_amdgcn_mfma_f32_16x16x32_bf16(b[nt], a[mt], acc[mt][nt], 0, 0, 0);
;         __builtin_amdgcn_s_setprio(0);
;     }
; template <int NT>
; __device__ __forceinline__ void gemm_tile(f32x4 (&acc)[4][NT], const bf16_t* A, int lda, const bf16_t* B, int ldb, int K, bf16_t* sm) {
;     ...
;     for (int kt = 0; kt < nk; ++kt) {
;         lds_barrier();
; #pragma unroll
;         for (int i = 0; i < 4; ++i) *(u32x4*)(sA + (lrow + 32 * i) * LDT + lkc * 8) = ra0[i];
; #pragma unroll
;         for (int i = 0; i < NT; ++i) *(u32x4*)(sB + sbrow[i] * LDT + lkc * 8) = rb0[i];
;         lds_barrier();
;         if (kt + 1 < nk) {
;             ga += 64; gb += 64;
; #pragma unroll
;             for (int i = 0; i < 4; ++i) ra0[i] = *(const u32x4*)(ga + (size_t)(32 * i) * lda);
; #pragma unroll
;             for (int i = 0; i < NT; ++i) rb0[i] = *(const u32x4*)(gb + (size_t)(32 * i) * ldb);
;         }
;         __builtin_amdgcn_sched_barrier(0);
;         gemm_compute<NT>(acc, sA, sB, wr, wc, fr, fq);
;         __builtin_amdgcn_sched_barrier(0);
;     }
	ds_read_b128 v[110:113], v244 offset:0
	ds_read_b128 v[114:117], v244 offset:2048
	ds_read_b128 v[118:121], v244 offset:4096
	ds_read_b128 v[122:125], v244 offset:6144
	ds_read_b128 v[126:129], v246 offset:0
	ds_read_b128 v[130:133], v246 offset:2048
	ds_read_b128 v[134:137], v246 offset:4096
	ds_read_b128 v[138:141], v246 offset:6144
	s_setprio 1
	v_mfma_f32_16x16x32_bf16 v[94:97], v[176:179], v[160:163], v[94:97]
	v_readlane_b32 s90, v234, 0
	v_readlane_b32 s91, v234, 1
	v_readlane_b32 s92, v234, 2
	v_readlane_b32 s93, v234, 3
	v_readlane_b32 s94, v234, 4
	v_readlane_b32 s95, v234, 5
	s_mov_b32 s22, 0x700
	s_mov_b32 s23, 0
	s_nop 3
	v_mfma_f32_16x16x32_bf16 v[90:93], v[180:183], v[160:163], v[90:93]
	v_mfma_f32_16x16x32_bf16 v[86:89], v[184:187], v[160:163], v[86:89]
	v_lshl_add_u64 v[0:1], v[98:99], 0, s[22:23]
	v_mfma_f32_16x16x32_bf16 v[82:85], v[188:191], v[160:163], v[82:85]
	v_mfma_f32_16x16x32_bf16 v[78:81], v[176:179], v[164:167], v[78:81]
	v_add_co_u32_e32 v2, vcc, s0, v0
	v_mfma_f32_16x16x32_bf16 v[74:77], v[180:183], v[164:167], v[74:77]
	v_mfma_f32_16x16x32_bf16 v[70:73], v[184:187], v[164:167], v[70:73]
	s_nop 0
	v_mfma_f32_16x16x32_bf16 v[66:69], v[188:191], v[164:167], v[66:69]
	v_mfma_f32_16x16x32_bf16 v[62:65], v[176:179], v[168:171], v[62:65]
	s_nop 0
	v_mfma_f32_16x16x32_bf16 v[58:61], v[180:183], v[168:171], v[58:61]
	v_mfma_f32_16x16x32_bf16 v[54:57], v[184:187], v[168:171], v[54:57]
	v_addc_co_u32_e32 v3, vcc, 0, v1, vcc
	v_mfma_f32_16x16x32_bf16 v[50:53], v[188:191], v[168:171], v[50:53]
	v_mfma_f32_16x16x32_bf16 v[46:49], v[176:179], v[172:175], v[46:49]
	v_add_co_u32_e32 v4, vcc, s64, v0
	v_mfma_f32_16x16x32_bf16 v[42:45], v[180:183], v[172:175], v[42:45]
	v_mfma_f32_16x16x32_bf16 v[38:41], v[184:187], v[172:175], v[38:41]
	v_lshl_add_u64 v[8:9], v[100:101], 0, s[22:23]
	v_mfma_f32_16x16x32_bf16 v[30:33], v[188:191], v[172:175], v[30:33]
	s_nop 0
	v_addc_co_u32_e32 v5, vcc, 0, v1, vcc
	global_load_dwordx4 v[18:21], v[2:3], off offset:128
	global_load_dwordx4 v[14:17], v[4:5], off offset:128
	v_add_co_u32_e32 v2, vcc, s65, v0
	s_mov_b32 s2, 0x1800000
	s_nop 0
	v_addc_co_u32_e32 v3, vcc, 0, v1, vcc
	v_add_co_u32_e32 v0, vcc, s33, v0
	s_nop 1
	v_addc_co_u32_e32 v1, vcc, 0, v1, vcc
	global_load_dwordx4 v[26:29], v[2:3], off offset:128
	global_load_dwordx4 v[34:37], v[0:1], off offset:128
	v_add_co_u32_e32 v0, vcc, s2, v8
	s_mov_b32 s2, 0x1810000
	s_nop 0
	v_addc_co_u32_e32 v1, vcc, 0, v9, vcc
	v_add_co_u32_e32 v2, vcc, s2, v8
	s_mov_b32 s2, 0x1820000
	s_nop 0
	v_addc_co_u32_e32 v3, vcc, 0, v9, vcc
	v_add_co_u32_e32 v10, vcc, s2, v8
	s_mov_b32 s2, 0x1830000
	s_nop 0
	v_addc_co_u32_e32 v11, vcc, 0, v9, vcc
	v_add_co_u32_e32 v22, vcc, s2, v8
	global_load_dwordx4 v[4:7], v[0:1], off offset:128
	s_nop 0
	global_load_dwordx4 v[0:3], v[2:3], off offset:128
	v_addc_co_u32_e32 v23, vcc, 0, v9, vcc
	global_load_dwordx4 v[8:11], v[10:11], off offset:128
	s_nop 0
	global_load_dwordx4 v[22:25], v[22:23], off offset:128
	s_setprio 0
	ds_read_b128 v[160:163], v245 offset:0
	ds_read_b128 v[164:167], v245 offset:2048
	ds_read_b128 v[168:171], v245 offset:4096
	ds_read_b128 v[172:175], v245 offset:6144
	ds_read_b128 v[176:179], v247 offset:0
	ds_read_b128 v[180:183], v247 offset:2048
	ds_read_b128 v[184:187], v247 offset:4096
	ds_read_b128 v[188:191], v247 offset:6144
	s_setprio 1
	s_waitcnt lgkmcnt(11)
	v_mfma_f32_16x16x32_bf16 v[94:97], v[126:129], v[110:113], v[94:97]
	s_waitcnt lgkmcnt(10)
	v_mfma_f32_16x16x32_bf16 v[90:93], v[130:133], v[110:113], v[90:93]
	s_waitcnt lgkmcnt(9)
	v_mfma_f32_16x16x32_bf16 v[86:89], v[134:137], v[110:113], v[86:89]
	s_waitcnt lgkmcnt(8)
	v_mfma_f32_16x16x32_bf16 v[82:85], v[138:141], v[110:113], v[82:85]
	v_mfma_f32_16x16x32_bf16 v[78:81], v[126:129], v[114:117], v[78:81]
	v_mfma_f32_16x16x32_bf16 v[74:77], v[130:133], v[114:117], v[74:77]
	v_mfma_f32_16x16x32_bf16 v[70:73], v[134:137], v[114:117], v[70:73]
	v_mfma_f32_16x16x32_bf16 v[66:69], v[138:141], v[114:117], v[66:69]
	v_mfma_f32_16x16x32_bf16 v[62:65], v[126:129], v[118:121], v[62:65]
	v_mfma_f32_16x16x32_bf16 v[58:61], v[130:133], v[118:121], v[58:61]
	v_mfma_f32_16x16x32_bf16 v[54:57], v[134:137], v[118:121], v[54:57]
	v_mfma_f32_16x16x32_bf16 v[50:53], v[138:141], v[118:121], v[50:53]
	v_mfma_f32_16x16x32_bf16 v[46:49], v[126:129], v[122:125], v[46:49]
	v_mfma_f32_16x16x32_bf16 v[42:45], v[130:133], v[122:125], v[42:45]
	v_mfma_f32_16x16x32_bf16 v[38:41], v[134:137], v[122:125], v[38:41]
	v_mfma_f32_16x16x32_bf16 v[30:33], v[138:141], v[122:125], v[30:33]
	s_setprio 0
	s_waitcnt lgkmcnt(0)
	s_setprio 1
	v_mfma_f32_16x16x32_bf16 v[94:97], v[176:179], v[160:163], v[94:97]
	v_mfma_f32_16x16x32_bf16 v[90:93], v[180:183], v[160:163], v[90:93]
	v_mfma_f32_16x16x32_bf16 v[86:89], v[184:187], v[160:163], v[86:89]
	v_mfma_f32_16x16x32_bf16 v[82:85], v[188:191], v[160:163], v[82:85]
	v_mfma_f32_16x16x32_bf16 v[78:81], v[176:179], v[164:167], v[78:81]
	v_mfma_f32_16x16x32_bf16 v[74:77], v[180:183], v[164:167], v[74:77]
	v_mfma_f32_16x16x32_bf16 v[70:73], v[184:187], v[164:167], v[70:73]
	v_mfma_f32_16x16x32_bf16 v[66:69], v[188:191], v[164:167], v[66:69]
	v_mfma_f32_16x16x32_bf16 v[62:65], v[176:179], v[168:171], v[62:65]
	v_mfma_f32_16x16x32_bf16 v[58:61], v[180:183], v[168:171], v[58:61]
	v_mfma_f32_16x16x32_bf16 v[54:57], v[184:187], v[168:171], v[54:57]
	v_mfma_f32_16x16x32_bf16 v[50:53], v[188:191], v[168:171], v[50:53]
	v_mfma_f32_16x16x32_bf16 v[46:49], v[176:179], v[172:175], v[46:49]
	v_mfma_f32_16x16x32_bf16 v[42:45], v[180:183], v[172:175], v[42:45]
	v_mfma_f32_16x16x32_bf16 v[38:41], v[184:187], v[172:175], v[38:41]
	v_mfma_f32_16x16x32_bf16 v[30:33], v[188:191], v[172:175], v[30:33]
	s_setprio 0
	s_waitcnt lgkmcnt(0)
	s_barrier
; template <int NT>
; __device__ __forceinline__ void gemm_tile(f32x4 (&acc)[4][NT], const bf16_t* A, int lda, const bf16_t* B, int ldb, int K, bf16_t* sm) {
;     ...
;         lds_barrier();
; #pragma unroll
;         for (int i = 0; i < 4; ++i) *(u32x4*)(sA + (lrow + 32 * i) * LDT + lkc * 8) = ra0[i];
; #pragma unroll
;         for (int i = 0; i < NT; ++i) *(u32x4*)(sB + sbrow[i] * LDT + lkc * 8) = rb0[i];
;         lds_barrier();
;         if (kt + 1 < nk) {
;             ga += 64; gb += 64;
; #pragma unroll
;             for (int i = 0; i < 4; ++i) ra0[i] = *(const u32x4*)(ga + (size_t)(32 * i) * lda);
; #pragma unroll
;             for (int i = 0; i < NT; ++i) rb0[i] = *(const u32x4*)(gb + (size_t)(32 * i) * ldb);
;         }
;         __builtin_amdgcn_sched_barrier(0);
;         gemm_compute<NT>(acc, sA, sB, wr, wc, fr, fq);
; __device__ __forceinline__ void phase_proj(const bf16_t* xb, const bf16_t* W, bf16_t* P, bf16_t* sm) {
;     ...
; #pragma unroll
;         for (int mt = 0; mt < 4; ++mt) {
;             const int row = tm * 128 + wr * 64 + mt * 16 + fr;
;             const int cbase = tn * 128 + wc * 64 + fq * 16;
;             float v[16]; gather_cols<4>(acc, mt, v);
;             u32x4 o0, o1;
; #pragma unroll
;             for (int q = 0; q < 4; ++q) { o0[q] = pack2(v[2 * q], v[2 * q + 1]); o1[q] = pack2(v[8 + 2 * q], v[8 + 2 * q + 1]); }
;             *(u32x4*)(P + (size_t)row * PW + cbase) = o0;
;             *(u32x4*)(P + (size_t)row * PW + cbase + 8) = o1;
;         }
	s_waitcnt vmcnt(7)
	ds_write_b128 v105, v[18:21]
	s_waitcnt vmcnt(6)
	ds_write_b128 v105, v[14:17] offset:5120
	s_waitcnt vmcnt(5)
	ds_write_b128 v105, v[26:29] offset:10240
	s_waitcnt vmcnt(4)
	ds_write_b128 v105, v[34:37] offset:15360
	s_waitcnt vmcnt(3)
	ds_write_b128 v106, v[4:7] offset:20480
	s_waitcnt vmcnt(2)
	ds_write_b128 v107, v[0:3] offset:20480
	s_waitcnt vmcnt(1)
	ds_write_b128 v108, v[8:11] offset:20480
	s_waitcnt vmcnt(0)
	ds_write_b128 v109, v[22:25] offset:20480
	s_waitcnt lgkmcnt(0)
	s_barrier
	ds_read_b128 v[0:3], v104
	ds_read_b128 v[4:7], v104 offset:2560
	ds_read_b128 v[8:11], v104 offset:5120
	ds_read_b128 v[14:17], v104 offset:7680
	ds_read_b128 v[18:21], v12 offset:20480
	ds_read_b128 v[22:25], v12 offset:23040
	ds_read_b128 v[26:29], v12 offset:25600
	ds_read_b128 v[34:37], v12 offset:28160
	s_setprio 1
	s_waitcnt lgkmcnt(3)
	v_mfma_f32_16x16x32_bf16 v[94:97], v[18:21], v[0:3], v[94:97]
	s_waitcnt lgkmcnt(2)
	v_mfma_f32_16x16x32_bf16 v[90:93], v[22:25], v[0:3], v[90:93]
	s_waitcnt lgkmcnt(1)
	v_mfma_f32_16x16x32_bf16 v[86:89], v[26:29], v[0:3], v[86:89]
	s_waitcnt lgkmcnt(0)
	v_mfma_f32_16x16x32_bf16 v[0:3], v[34:37], v[0:3], v[82:85]
	v_mfma_f32_16x16x32_bf16 v[78:81], v[18:21], v[4:7], v[78:81]
	v_mfma_f32_16x16x32_bf16 v[74:77], v[22:25], v[4:7], v[74:77]
	v_mfma_f32_16x16x32_bf16 v[70:73], v[26:29], v[4:7], v[70:73]
	v_mfma_f32_16x16x32_bf16 v[4:7], v[34:37], v[4:7], v[66:69]
	v_mfma_f32_16x16x32_bf16 v[62:65], v[18:21], v[8:11], v[62:65]
	v_mfma_f32_16x16x32_bf16 v[58:61], v[22:25], v[8:11], v[58:61]
	v_mfma_f32_16x16x32_bf16 v[54:57], v[26:29], v[8:11], v[54:57]
	v_mfma_f32_16x16x32_bf16 v[8:11], v[34:37], v[8:11], v[50:53]
	v_mfma_f32_16x16x32_bf16 v[18:21], v[18:21], v[14:17], v[46:49]
	v_mfma_f32_16x16x32_bf16 v[22:25], v[22:25], v[14:17], v[42:45]
	v_mfma_f32_16x16x32_bf16 v[26:29], v[26:29], v[14:17], v[38:41]
	v_mfma_f32_16x16x32_bf16 v[14:17], v[34:37], v[14:17], v[30:33]
	s_setprio 0
	s_nop 1
	ds_read_b128 v[30:33], v104 offset:64
	ds_read_b128 v[34:37], v104 offset:2624
	ds_read_b128 v[38:41], v104 offset:5184
	ds_read_b128 v[42:45], v104 offset:7744
	ds_read_b128 v[46:49], v12 offset:20544
	ds_read_b128 v[50:53], v12 offset:23104
	ds_read_b128 v[66:69], v12 offset:25664
	ds_read_b128 v[82:85], v12 offset:28224
	s_setprio 1
	s_waitcnt lgkmcnt(3)
	v_mfma_f32_16x16x32_bf16 v[94:97], v[46:49], v[30:33], v[94:97]
	s_waitcnt lgkmcnt(2)
	v_mfma_f32_16x16x32_bf16 v[90:93], v[50:53], v[30:33], v[90:93]
	s_waitcnt lgkmcnt(1)
	v_mfma_f32_16x16x32_bf16 v[86:89], v[66:69], v[30:33], v[86:89]
	s_waitcnt lgkmcnt(0)
	v_mfma_f32_16x16x32_bf16 v[0:3], v[82:85], v[30:33], v[0:3]
	v_mfma_f32_16x16x32_bf16 v[30:33], v[46:49], v[34:37], v[78:81]
	v_mfma_f32_16x16x32_bf16 v[74:77], v[50:53], v[34:37], v[74:77]
	v_mfma_f32_16x16x32_bf16 v[70:73], v[66:69], v[34:37], v[70:73]
	v_mfma_f32_16x16x32_bf16 v[4:7], v[82:85], v[34:37], v[4:7]
	v_mfma_f32_16x16x32_bf16 v[34:37], v[46:49], v[38:41], v[62:65]
	v_mfma_f32_16x16x32_bf16 v[58:61], v[50:53], v[38:41], v[58:61]
	v_mfma_f32_16x16x32_bf16 v[54:57], v[66:69], v[38:41], v[54:57]
	v_mfma_f32_16x16x32_bf16 v[8:11], v[82:85], v[38:41], v[8:11]
	v_mfma_f32_16x16x32_bf16 v[18:21], v[46:49], v[42:45], v[18:21]
	v_mfma_f32_16x16x32_bf16 v[22:25], v[50:53], v[42:45], v[22:25]
	v_mfma_f32_16x16x32_bf16 v[26:29], v[66:69], v[42:45], v[26:29]
	v_mfma_f32_16x16x32_bf16 v[14:17], v[82:85], v[42:45], v[14:17]
	s_setprio 0
	v_lshl_or_b32 v38, s18, 7, v103
	v_ashrrev_i32_e32 v39, 31, v38
	v_lshl_add_u32 v12, s14, 7, v102
	v_lshl_add_u64 v[46:47], v[38:39], 1, s[8:9]
	v_cvt_pk_bf16_f32 v38, v94, v90
	v_cvt_pk_bf16_f32 v39, v86, v0
	v_cvt_pk_bf16_f32 v40, v95, v91
	v_cvt_pk_bf16_f32 v41, v87, v1
	v_mad_i64_i32 v[0:1], s[14:15], v12, s92, v[46:47]
	v_cvt_pk_bf16_f32 v42, v96, v92
	v_cvt_pk_bf16_f32 v43, v88, v2
	v_cvt_pk_bf16_f32 v44, v97, v93
	v_cvt_pk_bf16_f32 v45, v89, v3
	global_store_dwordx4 v[0:1], v[38:41], off
	global_store_dwordx4 v[0:1], v[42:45], off offset:16
	v_cvt_pk_bf16_f32 v1, v70, v4
	v_or_b32_e32 v4, 16, v12
	v_cvt_pk_bf16_f32 v0, v30, v74
	v_cvt_pk_bf16_f32 v2, v31, v75
	v_cvt_pk_bf16_f32 v3, v71, v5
	v_mad_i64_i32 v[4:5], s[14:15], v4, s92, v[46:47]
	v_cvt_pk_bf16_f32 v38, v32, v76
	v_cvt_pk_bf16_f32 v39, v72, v6
	v_cvt_pk_bf16_f32 v40, v33, v77
	v_cvt_pk_bf16_f32 v41, v73, v7
	global_store_dwordx4 v[4:5], v[0:3], off
	global_store_dwordx4 v[4:5], v[38:41], off offset:16
	v_cvt_pk_bf16_f32 v4, v36, v60
	v_cvt_pk_bf16_f32 v1, v54, v8
	v_or_b32_e32 v8, 32, v12
	v_cvt_pk_bf16_f32 v0, v34, v58
	v_cvt_pk_bf16_f32 v2, v35, v59
	v_cvt_pk_bf16_f32 v3, v55, v9
	v_mad_i64_i32 v[8:9], s[14:15], v8, s92, v[46:47]
	v_cvt_pk_bf16_f32 v5, v56, v10
	v_cvt_pk_bf16_f32 v6, v37, v61
	v_cvt_pk_bf16_f32 v7, v57, v11
	global_store_dwordx4 v[8:9], v[0:3], off
	global_store_dwordx4 v[8:9], v[4:7], off offset:16
	v_or_b32_e32 v8, 48, v12
	s_add_i32 s13, s13, s62
	v_cvt_pk_bf16_f32 v0, v18, v22
	v_cvt_pk_bf16_f32 v4, v20, v24
	v_cvt_pk_bf16_f32 v1, v26, v14
	v_cvt_pk_bf16_f32 v5, v28, v16
	v_cvt_pk_bf16_f32 v2, v19, v23
	v_cvt_pk_bf16_f32 v6, v21, v25
	v_cvt_pk_bf16_f32 v3, v27, v15
	v_cvt_pk_bf16_f32 v7, v29, v17
	v_mad_i64_i32 v[8:9], s[14:15], v8, s92, v[46:47]
	s_cmpk_gt_i32 s13, 0x13a7
	global_store_dwordx4 v[8:9], v[0:3], off
	global_store_dwordx4 v[8:9], v[4:7], off offset:16
	s_cbranch_scc0 .LBB0_464
	v_mov_b32_e32 v66, v208

; template <int NT>
; __device__ __forceinline__ void gemm_tile(f32x4 (&acc)[4][NT], const bf16_t* A, int lda, const bf16_t* B, int ldb, int K, bf16_t* sm) {
;     const int tid_ = tidx();
;     bf16_t* sA = sm; bf16_t* sB = sm + 128 * LDT;
;     const int tid = tid_, lane = tid & 63, wid = tid >> 6, wr = wid >> 1, wc = wid & 1;
;     const int fr = lane & 15, fq = lane >> 4;
;     const int lrow = tid >> 3, lkc = tid & 7;
;     const bf16_t* ga = A + (size_t)lrow * lda + lkc * 8;
;     const bf16_t* gb = B + (size_t)lrow * ldb + lkc * 8;
;     int sbrow[NT];
; #pragma unroll
;     for (int i = 0; i < NT; ++i) { const int g = lrow + 32 * i, W_ = 16 * NT, rem = g % W_; sbrow[i] = (g / W_) * W_ + (rem % NT) * 16 + rem / NT; }
;     u32x4 ra0[4], rb0[NT];
; #pragma unroll
;     for (int i = 0; i < 4; ++i) ra0[i] = *(const u32x4*)(ga + (size_t)(32 * i) * lda);
; #pragma unroll
;     for (int i = 0; i < NT; ++i) rb0[i] = *(const u32x4*)(gb + (size_t)(32 * i) * ldb);
;     const int nk = K >> 6;
;     for (int kt = 0; kt < nk; ++kt) {
;         lds_barrier();
; #pragma unroll
;         for (int i = 0; i < 4; ++i) *(u32x4*)(sA + (lrow + 32 * i) * LDT + lkc * 8) = ra0[i];
; #pragma unroll
;         for (int i = 0; i < NT; ++i) *(u32x4*)(sB + sbrow[i] * LDT + lkc * 8) = rb0[i];
;         lds_barrier();
;         if (kt + 1 < nk) {
;             ga += 64; gb += 64;
; #pragma unroll
;             for (int i = 0; i < 4; ++i) ra0[i] = *(const u32x4*)(ga + (size_t)(32 * i) * lda);
; #pragma unroll
;             for (int i = 0; i < NT; ++i) rb0[i] = *(const u32x4*)(gb + (size_t)(32 * i) * ldb);
;         }
;         __builtin_amdgcn_sched_barrier(0);
;         gemm_compute<NT>(acc, sA, sB, wr, wc, fr, fq);
; __device__ __forceinline__ void phase_merge(const bf16_t* G, const bf16_t* BO, const bf16_t* Wb, bf16_t* M, bf16_t* sm) {
;     ...
;     for (int t = blockIdx.x; t < 136 * 16; t += gridDim.x) {
;         const int tm = t >> 4, tn = t & 15;
;         const int cbase = tn * 64 + wc * 32 + fq * 8;
;         f32x4 accm[4][2]; zero_acc<2>(accm);
; #pragma unroll 1
;         for (int i = 0; i < 4; ++i) {
;             f32x4 accb[4][2]; zero_acc<2>(accb);
;             const int koff = i * 512, kk = i < 3 ? 512 : 256;
;             gemm_tile<2>(accb, BO + (size_t)tm * 128 * 1792 + koff, 1792, Wb + (size_t)tn * 64 * 1792 + koff, 1792, kk, sm);
.LBB0_475:
	v_mov_b32_e32 v28, v192
	s_lshl_b32 s2, s48, 10
	s_add_u32 s40, s44, s2
	v_ashrrev_i32_e32 v0, 31, v28
	v_ashrrev_i32_e32 v26, 3, v28
	v_lshrrev_b32_e32 v0, 27, v0
	s_addc_u32 s41, s45, 0
	v_add_u32_e32 v0, v26, v0
	s_add_u32 s50, s46, s2
	v_lshrrev_b32_e32 v1, 5, v0
	s_addc_u32 s51, s47, 0
	v_mul_i32_i24_e32 v1, 32, v1
	v_sub_u32_e32 v27, v26, v1
	v_and_b32_e32 v29, 0x7ffffe0, v0
	v_mov_b64_e32 v[0:1], s[50:51]
	v_lshlrev_b32_e32 v2, 4, v28
	v_mad_i64_i32 v[0:1], s[50:51], v26, s36, v[0:1]
	v_and_b32_e32 v12, 0x70, v2
	v_lshl_add_u64 v[0:1], v[0:1], 0, v[12:13]
	v_add_co_u32_e32 v2, vcc, s38, v0
	s_mov_b32 s2, 0x38000
	s_nop 0
	v_addc_co_u32_e32 v3, vcc, 0, v1, vcc
	v_mov_b32_e32 v250, v0
	v_mov_b32_e32 v251, v1
	v_mov_b64_e32 v[0:1], s[40:41]
	v_mad_i64_i32 v[0:1], s[40:41], v26, s36, v[0:1]
	s_waitcnt vmcnt(10)
	v_lshl_add_u64 v[18:19], v[0:1], 0, v[12:13]
	v_add_co_u32_e32 v0, vcc, s38, v18
	s_waitcnt vmcnt(8)
	v_lshrrev_b16_e32 v30, 7, v27
	v_addc_co_u32_e32 v1, vcc, 0, v19, vcc
	v_add_co_u32_e32 v20, vcc, s2, v18
	s_mov_b32 s2, 0x54000
	s_nop 0
	v_addc_co_u32_e32 v21, vcc, 0, v19, vcc
	v_add_co_u32_e32 v22, vcc, s2, v18
	v_mov_b32_e32 v248, v18
	v_mov_b32_e32 v249, v19
	s_nop 0
	v_addc_co_u32_e32 v23, vcc, 0, v19, vcc
	s_nop 0
	v_and_b32_e32 v30, 1, v30
	v_add_u16_e32 v30, v27, v30
	v_ashrrev_i16_sdwa v31, v195, sext(v30) dst_sel:DWORD dst_unused:UNUSED_PAD src0_sel:DWORD src1_sel:BYTE_0
	v_and_b32_e32 v30, 0xfe, v30
	v_sub_u16_e32 v27, v27, v30
	v_lshlrev_b32_sdwa v27, v198, sext(v27) dst_sel:DWORD dst_unused:UNUSED_PAD src0_sel:DWORD src1_sel:BYTE_0
	v_bfe_i32 v30, v31, 0, 16
	v_add3_u32 v27, v29, v30, v27
	v_add_u32_e32 v29, 32, v26
	v_ashrrev_i32_e32 v30, 31, v29
	v_lshrrev_b32_e32 v30, 27, v30
	v_add_u32_e32 v30, v29, v30
	v_and_b32_e32 v30, 0xffffffe0, v30
	v_sub_u32_e32 v29, v29, v30
	v_lshrrev_b16_e32 v31, 7, v29
	v_and_b32_e32 v31, 1, v31
	v_add_u16_e32 v31, v29, v31
	v_ashrrev_i16_sdwa v32, v195, sext(v31) dst_sel:DWORD dst_unused:UNUSED_PAD src0_sel:DWORD src1_sel:BYTE_0
	v_and_b32_e32 v31, 0xfe, v31
	v_sub_u16_e32 v29, v29, v31
	v_lshlrev_b32_sdwa v29, v198, sext(v29) dst_sel:DWORD dst_unused:UNUSED_PAD src0_sel:DWORD src1_sel:BYTE_0
	v_bfe_i32 v31, v32, 0, 16
	v_add3_u32 v29, v30, v31, v29
	v_and_b32_e32 v31, 15, v28
	v_lshrrev_b32_e32 v32, 1, v28
	v_and_or_b32 v33, v32, s3, v31
	v_and_b32_e32 v30, 48, v28
	v_and_or_b32 v31, v32, 32, v31
	v_mul_lo_u32 v32, v33, s89
	v_mul_lo_u32 v33, v26, s89
	v_mul_lo_u32 v34, v27, s89
	v_mad_i64_i32 v[26:27], s[40:41], v26, s36, 0
	v_and_b32_e32 v28, 7, v28
	s_cmp_eq_u32 s48, 3
	v_mul_u32_u24_e32 v31, 0xa0, v31
	v_mul_lo_u32 v29, v29, s89
	s_movk_i32 s2, 0x180
	v_lshl_or_b32 v26, v28, 4, v26
	s_cselect_b32 s2, s2, 0x380
	v_lshl_add_u64 v[110:111], s[24:25], 0, v[26:27]
	v_lshl_add_u64 v[112:113], s[22:23], 0, v[26:27]
	s_mov_b64 s[40:41], 0
	v_add_u32_e32 v117, v12, v33
	v_add_u32_e32 v118, v12, v34
	v_add_u32_e32 v119, v12, v29
	v_add_u32_e32 v116, v30, v32
	v_add_u32_e32 v12, v30, v31
	v_mov_b32_e32 v26, 0
	v_mov_b32_e32 v27, v115
	v_mov_b32_e32 v28, v115
	v_mov_b32_e32 v29, v115
	v_mov_b32_e32 v30, 0
	v_mov_b32_e32 v31, v115
	v_mov_b32_e32 v32, v115
	v_mov_b32_e32 v33, v115
	v_mov_b32_e32 v34, 0
	v_mov_b32_e32 v35, v115
	v_mov_b32_e32 v36, v115
	v_mov_b32_e32 v37, v115
	v_mov_b32_e32 v38, 0
	v_mov_b32_e32 v39, v115
	v_mov_b32_e32 v40, v115
	s_waitcnt lgkmcnt(0)
	v_mov_b32_e32 v41, v115
	v_mov_b32_e32 v42, 0
	v_mov_b32_e32 v43, v115
	v_mov_b32_e32 v44, v115
	v_mov_b32_e32 v45, v115
	v_mov_b32_e32 v46, 0
	v_mov_b32_e32 v47, v115
	v_mov_b32_e32 v48, v115
	v_mov_b32_e32 v49, v115
	v_mov_b32_e32 v50, 0
	v_mov_b32_e32 v51, v115
	v_mov_b32_e32 v52, v115
	v_mov_b32_e32 v53, v115
	v_mov_b32_e32 v54, 0
	v_mov_b32_e32 v55, v115
	v_mov_b32_e32 v56, v115
	v_mov_b32_e32 v57, v115
	v_writelane_b32 v234, s90, 0
	v_writelane_b32 v234, s91, 1
	v_writelane_b32 v234, s92, 2
	v_writelane_b32 v234, s93, 3
	v_writelane_b32 v234, s94, 4
	v_writelane_b32 v234, s95, 5
	v_bfe_u32 v160, v192, 3, 3
	v_and_b32_e32 v161, 7, v192
	v_xor_b32_e32 v161, v160, v161
	v_lshlrev_b32_e32 v161, 4, v161
	v_lshrrev_b32_e32 v162, 6, v192
	v_lshl_add_u32 v163, v162, 5, v160
	v_mul_u32_u24_e32 v163, 0xe00, v163
	v_add_u32_e32 v236, v163, v161
	v_add_u32_e32 v237, 0x6c00, v236
	v_add_u32_e32 v238, 0x6c00, v237
	v_add_u32_e32 v239, 0x6c00, v238
	v_lshrrev_b32_e32 v163, 7, v192
	v_bfe_u32 v162, v192, 6, 1
	v_lshlrev_b32_e32 v163, 5, v163
	v_lshl_add_u32 v163, v160, 1, v163
	v_add_u32_e32 v163, v162, v163
	v_mul_u32_u24_e32 v163, 0xe00, v163
	v_add_u32_e32 v240, v163, v161
	v_add_u32_e32 v241, 0xdc00, v240
	v_and_b32_e32 v160, 15, v192
	v_bfe_u32 v161, v192, 4, 2
	v_and_b32_e32 v162, 7, v160
	v_xor_b32_e32 v161, v161, v162
	v_lshlrev_b32_e32 v161, 4, v161
	v_lshl_add_u32 v161, v160, 7, v161
	v_lshrrev_b32_e32 v162, 7, v192
	v_lshl_add_u32 v244, v162, 13, v161
	v_bfe_u32 v162, v192, 6, 1
	v_lshl_add_u32 v246, v162, 12, v161
	v_add_u32_e32 v246, 0x4000, v246
	v_xor_b32_e32 v245, 64, v244
	v_xor_b32_e32 v247, 64, v246
	v_lshrrev_b32_e32 v160, 6, v192
	s_nop 0
	v_readfirstlane_b32 s94, v160
	v_readfirstlane_b32 s90, v248
	v_readfirstlane_b32 s91, v249
	v_readfirstlane_b32 s92, v250
	v_readfirstlane_b32 s93, v251
	s_mul_i32 s95, s94, 0x7000
	s_sub_u32 s90, s90, s95
	s_subb_u32 s91, s91, 0
	s_mul_i32 s95, s94, 0x7000
	s_sub_u32 s92, s92, s95
	s_subb_u32 s93, s93, 0
	s_lshl_b32 s94, s94, 10
	s_waitcnt lgkmcnt(0)
	s_barrier
	s_lshl_b32 s95, s94, 2
	s_add_u32 m0, s95, 0x0
	s_nop 0
	global_load_lds_dwordx4 v236, s[90:91]
	global_load_lds_dwordx4 v237, s[90:91] offset:1024
	global_load_lds_dwordx4 v238, s[90:91] offset:2048
	global_load_lds_dwordx4 v239, s[90:91] offset:3072
	s_mul_i32 s95, s94, 2
	s_add_u32 m0, s95, 0x4000
	s_nop 0
	global_load_lds_dwordx4 v240, s[92:93]
	global_load_lds_dwordx4 v241, s[92:93] offset:1024
	s_add_u32 s90, s90, 0x80
	s_addc_u32 s91, s91, 0
	s_add_u32 s92, s92, 0x80
	s_addc_u32 s93, s93, 0
	s_waitcnt vmcnt(0)
	s_barrier
	s_lshl_b32 s95, s94, 2
	s_add_u32 m0, s95, 0x8000
	s_nop 0
	global_load_lds_dwordx4 v236, s[90:91]
	global_load_lds_dwordx4 v237, s[90:91] offset:1024
	global_load_lds_dwordx4 v238, s[90:91] offset:2048
	global_load_lds_dwordx4 v239, s[90:91] offset:3072
	s_mul_i32 s95, s94, 2
	s_add_u32 m0, s95, 0xc000
	s_nop 0
	global_load_lds_dwordx4 v240, s[92:93]
	global_load_lds_dwordx4 v241, s[92:93] offset:1024
	s_add_u32 s90, s90, 0x80
	s_addc_u32 s91, s91, 0
	s_add_u32 s92, s92, 0x80
	s_addc_u32 s93, s93, 0
	ds_read_b128 v[120:123], v244 offset:0
	ds_read_b128 v[124:127], v244 offset:2048
	ds_read_b128 v[128:131], v244 offset:4096
	ds_read_b128 v[132:135], v244 offset:6144
	ds_read_b128 v[136:139], v246 offset:0
	ds_read_b128 v[140:143], v246 offset:2048
	s_lshr_b32 s95, s2, 8
	s_add_i32 s95, s95, -1
	s_cmp_eq_u32 s95, 0
	s_cbranch_scc1 .Lgemm_x476
; template <int NT>
; __device__ __forceinline__ void gemm_compute(f32x4 (&acc)[4][NT], const bf16_t* sA, const bf16_t* sB, int wr, int wc, int fr, int fq) {
;     ...
;     for (int ks = 0; ks < 2; ++ks) {
;         bf16x8 a[4], b[NT];
; #pragma unroll
;         for (int mt = 0; mt < 4; ++mt) a[mt] = *(const bf16x8*)(sA + (wr * 64 + mt * 16 + fr) * LDT + ks * 32 + fq * 8);
; #pragma unroll
;         for (int nt = 0; nt < NT; ++nt) b[nt] = *(const bf16x8*)(sB + (wc * 16 * NT + nt * 16 + fr) * LDT + ks * 32 + fq * 8);
;         __builtin_amdgcn_s_setprio(1);
; #pragma unroll
;         for (int mt = 0; mt < 4; ++mt)
; #pragma unroll
;             for (int nt = 0; nt < NT; ++nt)
;                 acc[mt][nt] = __builtin_amdgcn_mfma_f32_16x16x32_bf16(b[nt], a[mt], acc[mt][nt], 0, 0, 0);
;         __builtin_amdgcn_s_setprio(0);
;     }
; template <int NT>
; __device__ __forceinline__ void gemm_tile(f32x4 (&acc)[4][NT], const bf16_t* A, int lda, const bf16_t* B, int ldb, int K, bf16_t* sm) {
;     ...
;     for (int kt = 0; kt < nk; ++kt) {
;         lds_barrier();
; #pragma unroll
;         for (int i = 0; i < 4; ++i) *(u32x4*)(sA + (lrow + 32 * i) * LDT + lkc * 8) = ra0[i];
; #pragma unroll
;         for (int i = 0; i < NT; ++i) *(u32x4*)(sB + sbrow[i] * LDT + lkc * 8) = rb0[i];
;         lds_barrier();
;         if (kt + 1 < nk) {
;             ga += 64; gb += 64;
; #pragma unroll
;             for (int i = 0; i < 4; ++i) ra0[i] = *(const u32x4*)(ga + (size_t)(32 * i) * lda);
; #pragma unroll
;             for (int i = 0; i < NT; ++i) rb0[i] = *(const u32x4*)(gb + (size_t)(32 * i) * ldb);
;         }
;         __builtin_amdgcn_sched_barrier(0);
;         gemm_compute<NT>(acc, sA, sB, wr, wc, fr, fq);
;         __builtin_amdgcn_sched_barrier(0);
;     }
.Lgemm_k476:
	v_writelane_b32 v234, s95, 6
	ds_read_b128 v[160:163], v245 offset:0
	ds_read_b128 v[164:167], v245 offset:2048
	ds_read_b128 v[168:171], v245 offset:4096
	ds_read_b128 v[172:175], v245 offset:6144
	ds_read_b128 v[176:179], v247 offset:0
	ds_read_b128 v[180:183], v247 offset:2048
	s_setprio 1
	s_waitcnt lgkmcnt(7)
	v_mfma_f32_16x16x32_bf16 v[54:57], v[136:139], v[120:123], v[54:57]
	s_waitcnt lgkmcnt(6)
	v_mfma_f32_16x16x32_bf16 v[50:53], v[140:143], v[120:123], v[50:53]
	v_mfma_f32_16x16x32_bf16 v[46:49], v[136:139], v[124:127], v[46:49]
	v_mfma_f32_16x16x32_bf16 v[42:45], v[140:143], v[124:127], v[42:45]
	v_mfma_f32_16x16x32_bf16 v[38:41], v[136:139], v[128:131], v[38:41]
	v_mfma_f32_16x16x32_bf16 v[34:37], v[140:143], v[128:131], v[34:37]
	v_mfma_f32_16x16x32_bf16 v[30:33], v[136:139], v[132:135], v[30:33]
	v_mfma_f32_16x16x32_bf16 v[26:29], v[140:143], v[132:135], v[26:29]
	s_setprio 0
	s_waitcnt vmcnt(0) lgkmcnt(0)
	s_barrier
	ds_read_b128 v[120:123], v244 offset:32768
	ds_read_b128 v[124:127], v244 offset:34816
	ds_read_b128 v[128:131], v244 offset:36864
	ds_read_b128 v[132:135], v244 offset:38912
	ds_read_b128 v[136:139], v246 offset:32768
	ds_read_b128 v[140:143], v246 offset:34816
	s_setprio 1
	v_mfma_f32_16x16x32_bf16 v[54:57], v[176:179], v[160:163], v[54:57]
	s_lshl_b32 s95, s94, 2
	s_add_u32 m0, s95, 0x0
	s_nop 0
	global_load_lds_dwordx4 v236, s[90:91]
	v_mfma_f32_16x16x32_bf16 v[50:53], v[180:183], v[160:163], v[50:53]
	v_mfma_f32_16x16x32_bf16 v[46:49], v[176:179], v[164:167], v[46:49]
	global_load_lds_dwordx4 v237, s[90:91] offset:1024
	v_mfma_f32_16x16x32_bf16 v[42:45], v[180:183], v[164:167], v[42:45]
	v_mfma_f32_16x16x32_bf16 v[38:41], v[176:179], v[168:171], v[38:41]
	global_load_lds_dwordx4 v238, s[90:91] offset:2048
	v_mfma_f32_16x16x32_bf16 v[34:37], v[180:183], v[168:171], v[34:37]
	v_mfma_f32_16x16x32_bf16 v[30:33], v[176:179], v[172:175], v[30:33]
	global_load_lds_dwordx4 v239, s[90:91] offset:3072
	v_mfma_f32_16x16x32_bf16 v[26:29], v[180:183], v[172:175], v[26:29]
	s_mul_i32 s95, s94, 2
	s_add_u32 m0, s95, 0x4000
	s_nop 0
	global_load_lds_dwordx4 v240, s[92:93]
	global_load_lds_dwordx4 v241, s[92:93] offset:1024
	s_add_u32 s90, s90, 0x80
	s_addc_u32 s91, s91, 0
	s_add_u32 s92, s92, 0x80
	s_addc_u32 s93, s93, 0
	s_setprio 0
	ds_read_b128 v[160:163], v245 offset:32768
	ds_read_b128 v[164:167], v245 offset:34816
	ds_read_b128 v[168:171], v245 offset:36864
	ds_read_b128 v[172:175], v245 offset:38912
	ds_read_b128 v[176:179], v247 offset:32768
	ds_read_b128 v[180:183], v247 offset:34816
	s_setprio 1
	s_waitcnt lgkmcnt(7)
	v_mfma_f32_16x16x32_bf16 v[54:57], v[136:139], v[120:123], v[54:57]
	s_waitcnt lgkmcnt(6)
	v_mfma_f32_16x16x32_bf16 v[50:53], v[140:143], v[120:123], v[50:53]
	v_mfma_f32_16x16x32_bf16 v[46:49], v[136:139], v[124:127], v[46:49]
	v_mfma_f32_16x16x32_bf16 v[42:45], v[140:143], v[124:127], v[42:45]
	v_mfma_f32_16x16x32_bf16 v[38:41], v[136:139], v[128:131], v[38:41]
	v_mfma_f32_16x16x32_bf16 v[34:37], v[140:143], v[128:131], v[34:37]
	v_mfma_f32_16x16x32_bf16 v[30:33], v[136:139], v[132:135], v[30:33]
	v_mfma_f32_16x16x32_bf16 v[26:29], v[140:143], v[132:135], v[26:29]
	s_setprio 0
	s_waitcnt vmcnt(0) lgkmcnt(0)
	s_barrier
	ds_read_b128 v[120:123], v244 offset:0
	ds_read_b128 v[124:127], v244 offset:2048
	ds_read_b128 v[128:131], v244 offset:4096
	ds_read_b128 v[132:135], v244 offset:6144
	ds_read_b128 v[136:139], v246 offset:0
	ds_read_b128 v[140:143], v246 offset:2048
	s_setprio 1
	v_mfma_f32_16x16x32_bf16 v[54:57], v[176:179], v[160:163], v[54:57]
	s_lshl_b32 s95, s94, 2
	s_add_u32 m0, s95, 0x8000
	s_nop 0
	global_load_lds_dwordx4 v236, s[90:91]
	v_mfma_f32_16x16x32_bf16 v[50:53], v[180:183], v[160:163], v[50:53]
	v_mfma_f32_16x16x32_bf16 v[46:49], v[176:179], v[164:167], v[46:49]
	global_load_lds_dwordx4 v237, s[90:91] offset:1024
	v_mfma_f32_16x16x32_bf16 v[42:45], v[180:183], v[164:167], v[42:45]
	v_mfma_f32_16x16x32_bf16 v[38:41], v[176:179], v[168:171], v[38:41]
	global_load_lds_dwordx4 v238, s[90:91] offset:2048
	v_mfma_f32_16x16x32_bf16 v[34:37], v[180:183], v[168:171], v[34:37]
	v_mfma_f32_16x16x32_bf16 v[30:33], v[176:179], v[172:175], v[30:33]
	global_load_lds_dwordx4 v239, s[90:91] offset:3072
	v_mfma_f32_16x16x32_bf16 v[26:29], v[180:183], v[172:175], v[26:29]
	s_mul_i32 s95, s94, 2
	s_add_u32 m0, s95, 0xc000
	s_nop 0
	global_load_lds_dwordx4 v240, s[92:93]
	global_load_lds_dwordx4 v241, s[92:93] offset:1024
	s_add_u32 s90, s90, 0x80
	s_addc_u32 s91, s91, 0
	s_add_u32 s92, s92, 0x80
	s_addc_u32 s93, s93, 0
	s_setprio 0
	v_readlane_b32 s95, v234, 6
	s_add_i32 s95, s95, -1
	s_cmp_lg_u32 s95, 0
	s_cbranch_scc1 .Lgemm_k476
; template <int NT>
; __device__ __forceinline__ void gemm_compute(f32x4 (&acc)[4][NT], const bf16_t* sA, const bf16_t* sB, int wr, int wc, int fr, int fq) {
;     ...
;     for (int ks = 0; ks < 2; ++ks) {
;         bf16x8 a[4], b[NT];
; #pragma unroll
;         for (int mt = 0; mt < 4; ++mt) a[mt] = *(const bf16x8*)(sA + (wr * 64 + mt * 16 + fr) * LDT + ks * 32 + fq * 8);
; #pragma unroll
;         for (int nt = 0; nt < NT; ++nt) b[nt] = *(const bf16x8*)(sB + (wc * 16 * NT + nt * 16 + fr) * LDT + ks * 32 + fq * 8);
;         __builtin_amdgcn_s_setprio(1);
; #pragma unroll
;         for (int mt = 0; mt < 4; ++mt)
; #pragma unroll
;             for (int nt = 0; nt < NT; ++nt)
;                 acc[mt][nt] = __builtin_amdgcn_mfma_f32_16x16x32_bf16(b[nt], a[mt], acc[mt][nt], 0, 0, 0);
;         __builtin_amdgcn_s_setprio(0);
;     }
; template <int NT>
; __device__ __forceinline__ void gemm_tile(f32x4 (&acc)[4][NT], const bf16_t* A, int lda, const bf16_t* B, int ldb, int K, bf16_t* sm) {
;     ...
;     for (int kt = 0; kt < nk; ++kt) {
;         lds_barrier();
; #pragma unroll
;         for (int i = 0; i < 4; ++i) *(u32x4*)(sA + (lrow + 32 * i) * LDT + lkc * 8) = ra0[i];
; #pragma unroll
;         for (int i = 0; i < NT; ++i) *(u32x4*)(sB + sbrow[i] * LDT + lkc * 8) = rb0[i];
;         lds_barrier();
;         if (kt + 1 < nk) {
;             ga += 64; gb += 64;
; #pragma unroll
;             for (int i = 0; i < 4; ++i) ra0[i] = *(const u32x4*)(ga + (size_t)(32 * i) * lda);
; #pragma unroll
;             for (int i = 0; i < NT; ++i) rb0[i] = *(const u32x4*)(gb + (size_t)(32 * i) * ldb);
;         }
;         __builtin_amdgcn_sched_barrier(0);
;         gemm_compute<NT>(acc, sA, sB, wr, wc, fr, fq);
;         __builtin_amdgcn_sched_barrier(0);
;     }
.Lgemm_x476:
	ds_read_b128 v[160:163], v245 offset:0
	ds_read_b128 v[164:167], v245 offset:2048
	ds_read_b128 v[168:171], v245 offset:4096
	ds_read_b128 v[172:175], v245 offset:6144
	ds_read_b128 v[176:179], v247 offset:0
	ds_read_b128 v[180:183], v247 offset:2048
	s_setprio 1
	s_waitcnt lgkmcnt(7)
	v_mfma_f32_16x16x32_bf16 v[54:57], v[136:139], v[120:123], v[54:57]
	s_waitcnt lgkmcnt(6)
	v_mfma_f32_16x16x32_bf16 v[50:53], v[140:143], v[120:123], v[50:53]
	v_mfma_f32_16x16x32_bf16 v[46:49], v[136:139], v[124:127], v[46:49]
	v_mfma_f32_16x16x32_bf16 v[42:45], v[140:143], v[124:127], v[42:45]
	v_mfma_f32_16x16x32_bf16 v[38:41], v[136:139], v[128:131], v[38:41]
	v_mfma_f32_16x16x32_bf16 v[34:37], v[140:143], v[128:131], v[34:37]
	v_mfma_f32_16x16x32_bf16 v[30:33], v[136:139], v[132:135], v[30:33]
	v_mfma_f32_16x16x32_bf16 v[26:29], v[140:143], v[132:135], v[26:29]
	s_setprio 0
	s_waitcnt vmcnt(0) lgkmcnt(0)
	s_barrier
	ds_read_b128 v[120:123], v244 offset:32768
	ds_read_b128 v[124:127], v244 offset:34816
	ds_read_b128 v[128:131], v244 offset:36864
	ds_read_b128 v[132:135], v244 offset:38912
	ds_read_b128 v[136:139], v246 offset:32768
	ds_read_b128 v[140:143], v246 offset:34816
	s_setprio 1
	v_mfma_f32_16x16x32_bf16 v[54:57], v[176:179], v[160:163], v[54:57]
	s_lshl_b32 s95, s94, 2
	s_add_u32 m0, s95, 0x0
	s_nop 0
	global_load_lds_dwordx4 v236, s[90:91]
	v_mfma_f32_16x16x32_bf16 v[50:53], v[180:183], v[160:163], v[50:53]
	v_mfma_f32_16x16x32_bf16 v[46:49], v[176:179], v[164:167], v[46:49]
	global_load_lds_dwordx4 v237, s[90:91] offset:1024
	v_mfma_f32_16x16x32_bf16 v[42:45], v[180:183], v[164:167], v[42:45]
	v_mfma_f32_16x16x32_bf16 v[38:41], v[176:179], v[168:171], v[38:41]
	global_load_lds_dwordx4 v238, s[90:91] offset:2048
	v_mfma_f32_16x16x32_bf16 v[34:37], v[180:183], v[168:171], v[34:37]
	v_mfma_f32_16x16x32_bf16 v[30:33], v[176:179], v[172:175], v[30:33]
	global_load_lds_dwordx4 v239, s[90:91] offset:3072
	v_mfma_f32_16x16x32_bf16 v[26:29], v[180:183], v[172:175], v[26:29]
	s_mul_i32 s95, s94, 2
	s_add_u32 m0, s95, 0x4000
	s_nop 0
	global_load_lds_dwordx4 v240, s[92:93]
	global_load_lds_dwordx4 v241, s[92:93] offset:1024
	s_add_u32 s90, s90, 0x80
	s_addc_u32 s91, s91, 0
	s_add_u32 s92, s92, 0x80
	s_addc_u32 s93, s93, 0
	s_setprio 0
	ds_read_b128 v[160:163], v245 offset:32768
	ds_read_b128 v[164:167], v245 offset:34816
	ds_read_b128 v[168:171], v245 offset:36864
	ds_read_b128 v[172:175], v245 offset:38912
	ds_read_b128 v[176:179], v247 offset:32768
	ds_read_b128 v[180:183], v247 offset:34816
	s_setprio 1
	s_waitcnt lgkmcnt(7)
	v_mfma_f32_16x16x32_bf16 v[54:57], v[136:139], v[120:123], v[54:57]
	s_waitcnt lgkmcnt(6)
	v_mfma_f32_16x16x32_bf16 v[50:53], v[140:143], v[120:123], v[50:53]
	v_mfma_f32_16x16x32_bf16 v[46:49], v[136:139], v[124:127], v[46:49]
	v_mfma_f32_16x16x32_bf16 v[42:45], v[140:143], v[124:127], v[42:45]
	v_mfma_f32_16x16x32_bf16 v[38:41], v[136:139], v[128:131], v[38:41]
	v_mfma_f32_16x16x32_bf16 v[34:37], v[140:143], v[128:131], v[34:37]
	v_mfma_f32_16x16x32_bf16 v[30:33], v[136:139], v[132:135], v[30:33]
	v_mfma_f32_16x16x32_bf16 v[26:29], v[140:143], v[132:135], v[26:29]
	s_setprio 0
	s_waitcnt vmcnt(0) lgkmcnt(0)
	s_barrier
	ds_read_b128 v[120:123], v244 offset:0
	ds_read_b128 v[124:127], v244 offset:2048
	ds_read_b128 v[128:131], v244 offset:4096
	ds_read_b128 v[132:135], v244 offset:6144
	ds_read_b128 v[136:139], v246 offset:0
	ds_read_b128 v[140:143], v246 offset:2048
	s_setprio 1
	v_mfma_f32_16x16x32_bf16 v[54:57], v[176:179], v[160:163], v[54:57]
	s_sub_u32 s40, s2, 0x80
	s_mov_b32 s41, 0
	v_readlane_b32 s90, v234, 0
	v_readlane_b32 s91, v234, 1
	v_readlane_b32 s92, v234, 2
	v_readlane_b32 s93, v234, 3
	v_readlane_b32 s94, v234, 4
	v_readlane_b32 s95, v234, 5
	s_nop 3
	v_mfma_f32_16x16x32_bf16 v[50:53], v[180:183], v[160:163], v[50:53]
	v_mfma_f32_16x16x32_bf16 v[46:49], v[176:179], v[164:167], v[46:49]
	v_lshl_add_u64 v[8:9], v[110:111], 0, s[40:41]
	v_mfma_f32_16x16x32_bf16 v[42:45], v[180:183], v[164:167], v[42:45]
	v_mfma_f32_16x16x32_bf16 v[38:41], v[176:179], v[168:171], v[38:41]
	v_add_co_u32_e32 v0, vcc, s93, v8
	v_mfma_f32_16x16x32_bf16 v[34:37], v[180:183], v[168:171], v[34:37]
	v_mfma_f32_16x16x32_bf16 v[30:33], v[176:179], v[172:175], v[30:33]
	s_mov_b32 s49, 0x1627c000
	v_mfma_f32_16x16x32_bf16 v[26:29], v[180:183], v[172:175], v[26:29]
	s_nop 0
	v_addc_co_u32_e32 v1, vcc, 0, v9, vcc
	v_add_co_u32_e32 v2, vcc, s49, v8
	s_mov_b32 s49, 0x16298000
	s_nop 0
	v_addc_co_u32_e32 v3, vcc, 0, v9, vcc
	v_add_co_u32_e32 v10, vcc, s49, v8
	s_mov_b32 s49, 0x162b4000
	s_nop 0
	v_addc_co_u32_e32 v11, vcc, 0, v9, vcc
	v_add_co_u32_e32 v8, vcc, s49, v8
	s_nop 0
	s_nop 0
	v_addc_co_u32_e32 v9, vcc, 0, v9, vcc
	global_load_dwordx4 v[4:7], v[0:1], off offset:128
	s_nop 0
	global_load_dwordx4 v[0:3], v[2:3], off offset:128
	s_nop 0
	global_load_dwordx4 v[18:21], v[10:11], off offset:128
	global_load_dwordx4 v[22:25], v[8:9], off offset:128
	v_lshl_add_u64 v[8:9], v[112:113], 0, s[40:41]
	s_mov_b32 s49, 0x2940000
	v_add_co_u32_e32 v10, vcc, s49, v8
	s_mov_b32 s49, 0x295c000
	s_nop 0
	v_addc_co_u32_e32 v11, vcc, 0, v9, vcc
	v_add_co_u32_e32 v14, vcc, s49, v8
	s_nop 1
	v_addc_co_u32_e32 v15, vcc, 0, v9, vcc
	global_load_dwordx4 v[8:11], v[10:11], off offset:128
	s_nop 0
	global_load_dwordx4 v[14:17], v[14:15], off offset:128
	s_setprio 0
	ds_read_b128 v[160:163], v245 offset:0
	ds_read_b128 v[164:167], v245 offset:2048
	ds_read_b128 v[168:171], v245 offset:4096
	ds_read_b128 v[172:175], v245 offset:6144
	ds_read_b128 v[176:179], v247 offset:0
	ds_read_b128 v[180:183], v247 offset:2048
	s_setprio 1
	s_waitcnt lgkmcnt(7)
	v_mfma_f32_16x16x32_bf16 v[54:57], v[136:139], v[120:123], v[54:57]
	s_waitcnt lgkmcnt(6)
	v_mfma_f32_16x16x32_bf16 v[50:53], v[140:143], v[120:123], v[50:53]
	v_mfma_f32_16x16x32_bf16 v[46:49], v[136:139], v[124:127], v[46:49]
	v_mfma_f32_16x16x32_bf16 v[42:45], v[140:143], v[124:127], v[42:45]
	v_mfma_f32_16x16x32_bf16 v[38:41], v[136:139], v[128:131], v[38:41]
	v_mfma_f32_16x16x32_bf16 v[34:37], v[140:143], v[128:131], v[34:37]
	v_mfma_f32_16x16x32_bf16 v[30:33], v[136:139], v[132:135], v[30:33]
	v_mfma_f32_16x16x32_bf16 v[26:29], v[140:143], v[132:135], v[26:29]
	s_setprio 0
	s_waitcnt lgkmcnt(0)
	s_setprio 1
	v_mfma_f32_16x16x32_bf16 v[54:57], v[176:179], v[160:163], v[54:57]
	v_mfma_f32_16x16x32_bf16 v[50:53], v[180:183], v[160:163], v[50:53]
	v_mfma_f32_16x16x32_bf16 v[46:49], v[176:179], v[164:167], v[46:49]
	v_mfma_f32_16x16x32_bf16 v[42:45], v[180:183], v[164:167], v[42:45]
	v_mfma_f32_16x16x32_bf16 v[38:41], v[176:179], v[168:171], v[38:41]
	v_mfma_f32_16x16x32_bf16 v[34:37], v[180:183], v[168:171], v[34:37]
	v_mfma_f32_16x16x32_bf16 v[30:33], v[176:179], v[172:175], v[30:33]
	v_mfma_f32_16x16x32_bf16 v[26:29], v[180:183], v[172:175], v[26:29]
	s_setprio 0
	s_waitcnt lgkmcnt(0)
	s_barrier
; __device__ __forceinline__ float lo2f(unsigned u) { return __uint_as_float(u << 16); }
; __device__ __forceinline__ float hi2f(unsigned u) { return __uint_as_float(u & 0xffff0000u); }
; __device__ __forceinline__ u32x4 ldntu4(const bf16_t* p) { return __builtin_nontemporal_load((const u32x4*)p); }
; template <int NT>
; __device__ __forceinline__ void gemm_tile(f32x4 (&acc)[4][NT], const bf16_t* A, int lda, const bf16_t* B, int ldb, int K, bf16_t* sm) {
;     ...
;         lds_barrier();
; #pragma unroll
;         for (int i = 0; i < 4; ++i) *(u32x4*)(sA + (lrow + 32 * i) * LDT + lkc * 8) = ra0[i];
; #pragma unroll
;         for (int i = 0; i < NT; ++i) *(u32x4*)(sB + sbrow[i] * LDT + lkc * 8) = rb0[i];
;         lds_barrier();
;         if (kt + 1 < nk) {
;             ga += 64; gb += 64;
; #pragma unroll
;             for (int i = 0; i < 4; ++i) ra0[i] = *(const u32x4*)(ga + (size_t)(32 * i) * lda);
; #pragma unroll
;             for (int i = 0; i < NT; ++i) rb0[i] = *(const u32x4*)(gb + (size_t)(32 * i) * ldb);
;         }
;         __builtin_amdgcn_sched_barrier(0);
;         gemm_compute<NT>(acc, sA, sB, wr, wc, fr, fq);
; __device__ __forceinline__ void phase_merge(const bf16_t* G, const bf16_t* BO, const bf16_t* Wb, bf16_t* M, bf16_t* sm) {
;     ...
; #pragma unroll
;             for (int mt = 0; mt < 4; ++mt) {
;                 const int row = tm * 128 + wr * 64 + mt * 16 + fr;
;                 const u32x4 gu = ldntu4(G + (size_t)row * 4096 + i * 1024 + cbase);
; #pragma unroll
;                 for (int e = 0; e < 8; ++e) {
;                     const float gv = (e & 1) ? hi2f(gu[e >> 1]) : lo2f(gu[e >> 1]);
;                     accm[mt][e % 2][e / 2] += gv * accb[mt][e % 2][e / 2];
;                 }
;             }
;         }
; #pragma unroll
;         for (int mt = 0; mt < 4; ++mt) {
;             const int row = tm * 128 + wr * 64 + mt * 16 + fr;
;             float v[8]; gather_cols<2>(accm, mt, v);
;             u32x4 o;
; #pragma unroll
;             for (int q = 0; q < 4; ++q) o[q] = pack2(v[2 * q], v[2 * q + 1]);
;             *(u32x4*)(M + (size_t)row * 1024 + cbase) = o;
;         }
	s_waitcnt vmcnt(5)
	ds_write_b128 v117, v[4:7]
	s_waitcnt vmcnt(4)
	ds_write_b128 v117, v[0:3] offset:5120
	s_waitcnt vmcnt(3)
	ds_write_b128 v117, v[18:21] offset:10240
	s_waitcnt vmcnt(2)
	ds_write_b128 v117, v[22:25] offset:15360
	s_waitcnt vmcnt(1)
	ds_write_b128 v118, v[8:11] offset:20480
	s_waitcnt vmcnt(0)
	ds_write_b128 v119, v[14:17] offset:20480
	s_waitcnt lgkmcnt(0)
	s_barrier
	ds_read_b128 v[0:3], v116
	ds_read_b128 v[4:7], v116 offset:2560
	ds_read_b128 v[8:11], v116 offset:5120
	ds_read_b128 v[14:17], v116 offset:7680
	ds_read_b128 v[18:21], v12 offset:20480
	ds_read_b128 v[22:25], v12 offset:23040
	s_setprio 1
	s_waitcnt lgkmcnt(1)
	v_mfma_f32_16x16x32_bf16 v[54:57], v[18:21], v[0:3], v[54:57]
	s_waitcnt lgkmcnt(0)
	v_mfma_f32_16x16x32_bf16 v[0:3], v[22:25], v[0:3], v[50:53]
	v_mfma_f32_16x16x32_bf16 v[46:49], v[18:21], v[4:7], v[46:49]
	v_mfma_f32_16x16x32_bf16 v[4:7], v[22:25], v[4:7], v[42:45]
	v_mfma_f32_16x16x32_bf16 v[38:41], v[18:21], v[8:11], v[38:41]
	v_mfma_f32_16x16x32_bf16 v[34:37], v[22:25], v[8:11], v[34:37]
	v_mfma_f32_16x16x32_bf16 v[18:21], v[18:21], v[14:17], v[30:33]
	v_mfma_f32_16x16x32_bf16 v[22:25], v[22:25], v[14:17], v[26:29]
	s_setprio 0
	ds_read_b128 v[8:11], v116 offset:64
	ds_read_b128 v[14:17], v116 offset:2624
	ds_read_b128 v[26:29], v116 offset:5184
	ds_read_b128 v[30:33], v116 offset:7744
	ds_read_b128 v[42:45], v12 offset:20544
	ds_read_b128 v[50:53], v12 offset:23104
	s_setprio 1
	s_waitcnt lgkmcnt(1)
	v_mfma_f32_16x16x32_bf16 v[54:57], v[42:45], v[8:11], v[54:57]
	s_waitcnt lgkmcnt(0)
	v_mfma_f32_16x16x32_bf16 v[110:113], v[50:53], v[8:11], v[0:3]
	v_mfma_f32_16x16x32_bf16 v[46:49], v[42:45], v[14:17], v[46:49]
	v_mfma_f32_16x16x32_bf16 v[116:119], v[50:53], v[14:17], v[4:7]
	v_mfma_f32_16x16x32_bf16 v[8:11], v[42:45], v[26:29], v[38:41]
	v_mfma_f32_16x16x32_bf16 v[14:17], v[50:53], v[26:29], v[34:37]
	v_mfma_f32_16x16x32_bf16 v[0:3], v[42:45], v[30:33], v[18:21]
	v_mfma_f32_16x16x32_bf16 v[4:7], v[50:53], v[30:33], v[22:25]
	s_setprio 0
	s_lshl_b32 s86, s48, 11
	v_lshl_add_u64 v[18:19], v[76:77], 0, s[86:87]
	v_lshl_add_u64 v[20:21], v[18:19], 0, v[78:79]
	global_load_dwordx4 v[20:23], v[20:21], off nt
	v_mov_b32_e32 v26, v54
	v_mov_b32_e32 v27, v110
	v_mov_b32_e32 v110, v55
	s_add_i32 s48, s48, 1
	s_add_u32 s24, s24, 0x400
	s_addc_u32 s25, s25, 0
	s_add_u32 s22, s22, 0x400
	s_addc_u32 s23, s23, 0
	s_cmp_eq_u32 s48, 4
	s_waitcnt vmcnt(0)
	v_lshlrev_b32_e32 v24, 16, v20
	v_and_b32_e32 v25, 0xffff0000, v20
	v_lshlrev_b32_e32 v20, 16, v21
	v_and_b32_e32 v21, 0xffff0000, v21
	v_pk_fma_f32 v[108:109], v[26:27], v[24:25], v[108:109]
	v_pk_fma_f32 v[106:107], v[110:111], v[20:21], v[106:107]
	v_lshlrev_b32_e32 v20, 16, v22
	v_and_b32_e32 v21, 0xffff0000, v22
	v_mov_b32_e32 v24, v56
	v_mov_b32_e32 v25, v112
	v_pk_fma_f32 v[104:105], v[24:25], v[20:21], v[104:105]
	v_lshlrev_b32_e32 v20, 16, v23
	v_and_b32_e32 v21, 0xffff0000, v23
	v_mov_b32_e32 v112, v57
	v_pk_fma_f32 v[102:103], v[112:113], v[20:21], v[102:103]
	v_lshl_add_u64 v[20:21], v[18:19], 0, v[80:81]
	global_load_dwordx4 v[20:23], v[20:21], off nt
	v_mov_b32_e32 v26, v46
	v_mov_b32_e32 v27, v116
	v_mov_b32_e32 v116, v47
	s_waitcnt vmcnt(0)
	v_lshlrev_b32_e32 v24, 16, v20
	v_and_b32_e32 v25, 0xffff0000, v20
	v_lshlrev_b32_e32 v20, 16, v21
	v_and_b32_e32 v21, 0xffff0000, v21
	v_pk_fma_f32 v[100:101], v[26:27], v[24:25], v[100:101]
	v_pk_fma_f32 v[98:99], v[116:117], v[20:21], v[98:99]
	v_lshlrev_b32_e32 v20, 16, v22
	v_and_b32_e32 v21, 0xffff0000, v22
	v_mov_b32_e32 v24, v48
	v_mov_b32_e32 v25, v118
	v_pk_fma_f32 v[96:97], v[24:25], v[20:21], v[96:97]
	v_lshlrev_b32_e32 v20, 16, v23
	v_and_b32_e32 v21, 0xffff0000, v23
	v_mov_b32_e32 v118, v49
	v_pk_fma_f32 v[94:95], v[118:119], v[20:21], v[94:95]
	v_lshl_add_u64 v[20:21], v[18:19], 0, v[90:91]
	global_load_dwordx4 v[20:23], v[20:21], off nt
	v_mov_b32_e32 v27, v14
	v_mov_b32_e32 v14, v9
	v_mov_b32_e32 v26, v8
	s_waitcnt vmcnt(0)
	v_lshlrev_b32_e32 v24, 16, v20
	v_and_b32_e32 v25, 0xffff0000, v20
	v_lshlrev_b32_e32 v20, 16, v21
	v_and_b32_e32 v21, 0xffff0000, v21
	v_pk_fma_f32 v[86:87], v[14:15], v[20:21], v[86:87]
	v_lshlrev_b32_e32 v8, 16, v22
	v_and_b32_e32 v9, 0xffff0000, v22
	v_mov_b32_e32 v14, v10
	v_mov_b32_e32 v15, v16
	v_pk_fma_f32 v[84:85], v[14:15], v[8:9], v[84:85]
	v_lshlrev_b32_e32 v8, 16, v23
	v_and_b32_e32 v9, 0xffff0000, v23
	v_mov_b32_e32 v16, v11
	v_pk_fma_f32 v[82:83], v[16:17], v[8:9], v[82:83]
	v_lshl_add_u64 v[8:9], v[18:19], 0, v[92:93]
	global_load_dwordx4 v[8:11], v[8:9], off nt
	v_mov_b32_e32 v17, v4
	v_mov_b32_e32 v4, v1
	v_mov_b32_e32 v16, v0
	v_pk_fma_f32 v[88:89], v[26:27], v[24:25], v[88:89]
	s_waitcnt vmcnt(0)
	v_lshlrev_b32_e32 v14, 16, v8
	v_and_b32_e32 v15, 0xffff0000, v8
	v_lshlrev_b32_e32 v8, 16, v9
	v_and_b32_e32 v9, 0xffff0000, v9
	v_pk_fma_f32 v[72:73], v[4:5], v[8:9], v[72:73]
	v_lshlrev_b32_e32 v0, 16, v10
	v_and_b32_e32 v1, 0xffff0000, v10
	v_mov_b32_e32 v4, v2
	v_mov_b32_e32 v5, v6
	v_pk_fma_f32 v[70:71], v[4:5], v[0:1], v[70:71]
	v_lshlrev_b32_e32 v0, 16, v11
	v_and_b32_e32 v1, 0xffff0000, v11
	v_mov_b32_e32 v6, v3
	v_pk_fma_f32 v[74:75], v[16:17], v[14:15], v[74:75]
	v_pk_fma_f32 v[68:69], v[6:7], v[0:1], v[68:69]
	s_cbranch_scc0 .LBB0_475
	v_lshlrev_b32_e32 v12, 1, v66
	v_lshl_add_u64 v[4:5], s[18:19], 0, v[12:13]
	v_lshlrev_b64 v[6:7], 11, v[64:65]
	v_cvt_pk_bf16_f32 v0, v108, v109
	v_cvt_pk_bf16_f32 v1, v106, v107
	v_cvt_pk_bf16_f32 v2, v104, v105
	v_cvt_pk_bf16_f32 v3, v102, v103
	v_lshl_add_u64 v[6:7], v[4:5], 0, v[6:7]
	global_store_dwordx4 v[6:7], v[0:3], off
	v_lshlrev_b64 v[6:7], 11, v[62:63]
	v_lshl_add_u64 v[6:7], v[4:5], 0, v[6:7]
	v_cvt_pk_bf16_f32 v0, v100, v101
	v_cvt_pk_bf16_f32 v1, v98, v99
	v_cvt_pk_bf16_f32 v2, v96, v97
	v_cvt_pk_bf16_f32 v3, v94, v95
	global_store_dwordx4 v[6:7], v[0:3], off
	v_lshlrev_b64 v[6:7], 11, v[60:61]
	v_lshl_add_u64 v[6:7], v[4:5], 0, v[6:7]
	v_cvt_pk_bf16_f32 v0, v88, v89
	v_cvt_pk_bf16_f32 v1, v86, v87
	v_cvt_pk_bf16_f32 v2, v84, v85
	v_cvt_pk_bf16_f32 v3, v82, v83
	global_store_dwordx4 v[6:7], v[0:3], off
	v_lshlrev_b64 v[6:7], 11, v[58:59]
	s_add_i32 s43, s43, s62
	s_add_i32 s42, s42, s62
	v_cvt_pk_bf16_f32 v0, v74, v75
	v_cvt_pk_bf16_f32 v1, v72, v73
	v_cvt_pk_bf16_f32 v2, v70, v71
	v_cvt_pk_bf16_f32 v3, v68, v69
	v_lshl_add_u64 v[4:5], v[4:5], 0, v[6:7]
	s_cmpk_gt_i32 s43, 0x87f
	global_store_dwordx4 v[4:5], v[0:3], off
	s_cbranch_scc0 .LBB0_474

; __device__ __forceinline__ int tidx() { int t = threadIdx.x; asm volatile("" : "+v"(t)); return t; }
; template <int NT>
; __device__ __forceinline__ void gemm_tile(f32x4 (&acc)[4][NT], const bf16_t* A, int lda, const bf16_t* B, int ldb, int K, bf16_t* sm) {
;     const int tid_ = tidx();
;     bf16_t* sA = sm; bf16_t* sB = sm + 128 * LDT;
;     const int tid = tid_, lane = tid & 63, wid = tid >> 6, wr = wid >> 1, wc = wid & 1;
;     const int fr = lane & 15, fq = lane >> 4;
;     const int lrow = tid >> 3, lkc = tid & 7;
;     const bf16_t* ga = A + (size_t)lrow * lda + lkc * 8;
;     const bf16_t* gb = B + (size_t)lrow * ldb + lkc * 8;
;     int sbrow[NT];
; #pragma unroll
;     for (int i = 0; i < NT; ++i) { const int g = lrow + 32 * i, W_ = 16 * NT, rem = g % W_; sbrow[i] = (g / W_) * W_ + (rem % NT) * 16 + rem / NT; }
;     u32x4 ra0[4], rb0[NT];
; #pragma unroll
;     for (int i = 0; i < 4; ++i) ra0[i] = *(const u32x4*)(ga + (size_t)(32 * i) * lda);
; #pragma unroll
;     for (int i = 0; i < NT; ++i) rb0[i] = *(const u32x4*)(gb + (size_t)(32 * i) * ldb);
;     const int nk = K >> 6;
; __device__ __forceinline__ void phase_ffn_in(const bf16_t* xb, const bf16_t* W, bf16_t* H, bf16_t* sm) {
;     ...
;     for (int t = blockIdx.x; t < 136 * 32; t += gridDim.x) {
;         const int tm = t >> 5, tn = t & 31;
;         f32x4 acc[4][4]; zero_acc<4>(acc);
;         gemm_tile<4>(acc, xb + (size_t)tm * 128 * 1024, 1024, W + (size_t)tn * 128 * 1024, 1024, 1024, sm);
.LBB0_1479:
	v_mov_b32_e32 v38, v192
	s_ashr_i32 s18, s11, 5
	v_ashrrev_i32_e32 v0, 31, v38
	v_ashrrev_i32_e32 v30, 3, v38
	v_lshrrev_b32_e32 v0, 26, v0
	v_add_u32_e32 v0, v30, v0
	v_lshrrev_b32_e32 v1, 6, v0
	v_mul_i32_i24_e32 v1, 64, v1
	v_sub_u32_e32 v1, v30, v1
	v_lshrrev_b16_sdwa v2, v196, sext(v1) dst_sel:DWORD dst_unused:UNUSED_PAD src0_sel:DWORD src1_sel:BYTE_0
	v_and_b32_e32 v2, 3, v2
	v_add_u16_e32 v2, v1, v2
	v_ashrrev_i16_sdwa v3, v197, sext(v2) dst_sel:DWORD dst_unused:UNUSED_PAD src0_sel:DWORD src1_sel:BYTE_0
	v_and_b32_e32 v2, 0xfc, v2
	v_sub_u16_e32 v1, v1, v2
	v_and_b32_e32 v0, 0x7ffffc0, v0
	v_lshlrev_b32_sdwa v1, v198, sext(v1) dst_sel:DWORD dst_unused:UNUSED_PAD src0_sel:DWORD src1_sel:BYTE_0
	v_bfe_i32 v2, v3, 0, 16
	v_add3_u32 v39, v0, v2, v1
	v_add_u32_e32 v0, 32, v30
	v_ashrrev_i32_e32 v1, 31, v0
	v_lshrrev_b32_e32 v1, 26, v1
	v_add_u32_e32 v1, v0, v1
	v_lshrrev_b32_e32 v2, 6, v1
	v_mul_i32_i24_e32 v2, 64, v2
	v_sub_u32_e32 v0, v0, v2
	v_lshrrev_b16_sdwa v2, v196, sext(v0) dst_sel:DWORD dst_unused:UNUSED_PAD src0_sel:DWORD src1_sel:BYTE_0
	v_and_b32_e32 v2, 3, v2
	v_add_u16_e32 v2, v0, v2
	v_ashrrev_i16_sdwa v3, v197, sext(v2) dst_sel:DWORD dst_unused:UNUSED_PAD src0_sel:DWORD src1_sel:BYTE_0
	v_and_b32_e32 v2, 0xfc, v2
	v_sub_u16_e32 v0, v0, v2
	v_and_b32_e32 v1, 0x7ffffc0, v1
	v_lshlrev_b32_sdwa v0, v198, sext(v0) dst_sel:DWORD dst_unused:UNUSED_PAD src0_sel:DWORD src1_sel:BYTE_0
	v_bfe_i32 v2, v3, 0, 16
	v_add3_u32 v40, v1, v2, v0
	v_add_u32_e32 v0, 64, v30
	v_ashrrev_i32_e32 v1, 31, v0
	v_lshrrev_b32_e32 v1, 26, v1
	v_add_u32_e32 v1, v0, v1
	v_lshrrev_b32_e32 v2, 6, v1
	v_mul_i32_i24_e32 v2, 64, v2
	v_sub_u32_e32 v0, v0, v2
	v_lshrrev_b16_sdwa v2, v196, sext(v0) dst_sel:DWORD dst_unused:UNUSED_PAD src0_sel:DWORD src1_sel:BYTE_0
	v_and_b32_e32 v2, 3, v2
	v_add_u16_e32 v2, v0, v2
	v_ashrrev_i16_sdwa v3, v197, sext(v2) dst_sel:DWORD dst_unused:UNUSED_PAD src0_sel:DWORD src1_sel:BYTE_0
	v_and_b32_e32 v2, 0xfc, v2
	v_sub_u16_e32 v0, v0, v2
	v_and_b32_e32 v1, 0x7ffffc0, v1
	v_lshlrev_b32_sdwa v0, v198, sext(v0) dst_sel:DWORD dst_unused:UNUSED_PAD src0_sel:DWORD src1_sel:BYTE_0
	v_bfe_i32 v2, v3, 0, 16
	s_waitcnt lgkmcnt(0)
	v_add3_u32 v41, v1, v2, v0
	v_add_u32_e32 v0, 0x60, v30
	v_ashrrev_i32_e32 v1, 31, v0
	v_lshrrev_b32_e32 v1, 26, v1
	v_add_u32_e32 v1, v0, v1
	v_lshrrev_b32_e32 v2, 6, v1
	v_mul_i32_i24_e32 v2, 64, v2
	v_sub_u32_e32 v0, v0, v2
	v_lshrrev_b16_sdwa v2, v196, sext(v0) dst_sel:DWORD dst_unused:UNUSED_PAD src0_sel:DWORD src1_sel:BYTE_0
	s_and_b32 s2, s10, 31
	s_ashr_i32 s19, s18, 31
	v_and_b32_e32 v2, 3, v2
	s_lshl_b32 s86, s2, 18
	s_and_b32 s12, s11, 31
	s_lshl_b64 s[22:23], s[18:19], 18
	v_add_u16_e32 v2, v0, v2
	s_add_u32 s24, s80, s22
	v_ashrrev_i16_sdwa v3, v197, sext(v2) dst_sel:DWORD dst_unused:UNUSED_PAD src0_sel:DWORD src1_sel:BYTE_0
	v_and_b32_e32 v2, 0xfc, v2
	s_addc_u32 s25, s81, s23
	s_lshl_b32 s2, s12, 18
	v_sub_u16_e32 v0, v0, v2
	s_add_u32 s40, s16, s2
	v_and_b32_e32 v1, 0x7ffffc0, v1
	v_lshlrev_b32_sdwa v0, v198, sext(v0) dst_sel:DWORD dst_unused:UNUSED_PAD src0_sel:DWORD src1_sel:BYTE_0
	v_bfe_i32 v2, v3, 0, 16
	v_ashrrev_i32_e32 v31, 31, v30
	s_addc_u32 s41, s17, 0
	v_add3_u32 v42, v1, v2, v0
	v_lshlrev_b64 v[32:33], 11, v[30:31]
	v_lshlrev_b32_e32 v2, 4, v38
	v_lshl_add_u64 v[0:1], s[40:41], 0, v[32:33]
	v_and_b32_e32 v12, 0x70, v2
	v_lshl_add_u64 v[8:9], v[0:1], 0, v[12:13]
	v_add_co_u32_e32 v0, vcc, s7, v8
	v_lshl_add_u64 v[18:19], s[24:25], 0, v[32:33]
	s_nop 0
	v_addc_co_u32_e32 v1, vcc, 0, v9, vcc
	v_add_co_u32_e32 v10, vcc, s37, v8
	v_lshl_add_u64 v[26:27], v[18:19], 0, v[12:13]
	s_nop 0
	v_addc_co_u32_e32 v11, vcc, 0, v9, vcc
	v_add_co_u32_e32 v14, vcc, s73, v8
	v_mov_b32_e32 v250, v8
	v_mov_b32_e32 v251, v9
	s_nop 0
	v_addc_co_u32_e32 v15, vcc, 0, v9, vcc
	v_add_co_u32_e32 v18, vcc, s7, v26
	s_nop 0
	v_addc_co_u32_e32 v19, vcc, 0, v27, vcc
	v_add_co_u32_e32 v28, vcc, s37, v26
	v_mov_b32_e32 v248, v26
	v_mov_b32_e32 v249, v27
	s_nop 0
	v_addc_co_u32_e32 v29, vcc, 0, v27, vcc
	v_add_co_u32_e32 v34, vcc, s73, v26
	v_and_b32_e32 v31, 15, v38
	s_nop 0
	v_addc_co_u32_e32 v35, vcc, 0, v27, vcc
	s_nop 0
	v_lshrrev_b32_e32 v44, 1, v38
	v_and_or_b32 v31, v44, s3, v31
	v_mul_lo_u32 v44, v31, s89
	v_mul_lo_u32 v45, v30, s89
	v_lshl_add_u64 v[30:31], s[22:23], 0, v[32:33]
	v_or_b32_e32 v30, v30, v12
	v_lshl_add_u64 v[98:99], s[58:59], 0, v[30:31]
	v_lshl_add_u64 v[30:31], s[86:87], 0, v[32:33]
	v_and_b32_e32 v43, 48, v38
	v_and_b32_e32 v38, 0x4f, v38
	v_or_b32_e32 v30, v30, v12
	v_mul_u32_u24_e32 v38, 0xa0, v38
	v_mul_lo_u32 v39, v39, s89
	v_mul_lo_u32 v40, v40, s89
	v_mul_lo_u32 v41, v41, s89
	v_mul_lo_u32 v42, v42, s89
	v_lshl_add_u64 v[100:101], s[16:17], 0, v[30:31]
	v_mov_b32_e32 v30, 0
	s_mov_b64 s[22:23], 0
	v_add_u32_e32 v105, v12, v45
	v_add_u32_e32 v106, v12, v39
	v_add_u32_e32 v107, v12, v40
	v_add_u32_e32 v108, v12, v41
	v_add_u32_e32 v109, v12, v42
	v_add_u32_e32 v104, v43, v44
; template <int NT>
; __device__ __forceinline__ void gemm_tile(f32x4 (&acc)[4][NT], const bf16_t* A, int lda, const bf16_t* B, int ldb, int K, bf16_t* sm) {
;     ...
;     const bf16_t* ga = A + (size_t)lrow * lda + lkc * 8;
;     const bf16_t* gb = B + (size_t)lrow * ldb + lkc * 8;
;     int sbrow[NT];
; #pragma unroll
;     for (int i = 0; i < NT; ++i) { const int g = lrow + 32 * i, W_ = 16 * NT, rem = g % W_; sbrow[i] = (g / W_) * W_ + (rem % NT) * 16 + rem / NT; }
;     u32x4 ra0[4], rb0[NT];
; #pragma unroll
;     for (int i = 0; i < 4; ++i) ra0[i] = *(const u32x4*)(ga + (size_t)(32 * i) * lda);
; #pragma unroll
;     for (int i = 0; i < NT; ++i) rb0[i] = *(const u32x4*)(gb + (size_t)(32 * i) * ldb);
;     const int nk = K >> 6;
;     for (int kt = 0; kt < nk; ++kt) {
;         lds_barrier();
; #pragma unroll
;         for (int i = 0; i < 4; ++i) *(u32x4*)(sA + (lrow + 32 * i) * LDT + lkc * 8) = ra0[i];
; #pragma unroll
;         for (int i = 0; i < NT; ++i) *(u32x4*)(sB + sbrow[i] * LDT + lkc * 8) = rb0[i];
;         lds_barrier();
;         if (kt + 1 < nk) {
;             ga += 64; gb += 64;
; #pragma unroll
;             for (int i = 0; i < 4; ++i) ra0[i] = *(const u32x4*)(ga + (size_t)(32 * i) * lda);
; #pragma unroll
;             for (int i = 0; i < NT; ++i) rb0[i] = *(const u32x4*)(gb + (size_t)(32 * i) * ldb);
;         }
	v_add_u32_e32 v12, v43, v38
	v_mov_b32_e32 v31, v30
	v_mov_b32_e32 v32, v30
	v_mov_b32_e32 v33, v30
	v_mov_b32_e32 v38, v30
	v_mov_b32_e32 v39, v30
	v_mov_b32_e32 v40, v30
	v_mov_b32_e32 v41, v30
	v_mov_b32_e32 v42, v30
	v_mov_b32_e32 v43, v30
	v_mov_b32_e32 v44, v30
	v_mov_b32_e32 v45, v30
	v_mov_b32_e32 v46, v30
	v_mov_b32_e32 v47, v30
	v_mov_b32_e32 v48, v30
	v_mov_b32_e32 v49, v30
	v_mov_b32_e32 v50, v30
	v_mov_b32_e32 v51, v30
	v_mov_b32_e32 v52, v30
	v_mov_b32_e32 v53, v30
	v_mov_b32_e32 v54, v30
	v_mov_b32_e32 v55, v30
	v_mov_b32_e32 v56, v30
	v_mov_b32_e32 v57, v30
	v_mov_b32_e32 v58, v30
	v_mov_b32_e32 v59, v30
	v_mov_b32_e32 v60, v30
	v_mov_b32_e32 v61, v30
	v_mov_b32_e32 v62, v30
	v_mov_b32_e32 v63, v30
	v_mov_b32_e32 v64, v30
	v_mov_b32_e32 v65, v30
	v_mov_b32_e32 v66, v30
	v_mov_b32_e32 v67, v30
	v_mov_b32_e32 v68, v30
	v_mov_b32_e32 v69, v30
	v_mov_b32_e32 v70, v30
	v_mov_b32_e32 v71, v30
	v_mov_b32_e32 v72, v30
	v_mov_b32_e32 v73, v30
	v_mov_b32_e32 v74, v30
	v_mov_b32_e32 v75, v30
	v_mov_b32_e32 v76, v30
	v_mov_b32_e32 v77, v30
	v_mov_b32_e32 v78, v30
	v_mov_b32_e32 v79, v30
	v_mov_b32_e32 v80, v30
	v_mov_b32_e32 v81, v30
	v_mov_b32_e32 v82, v30
	v_mov_b32_e32 v83, v30
	v_mov_b32_e32 v84, v30
	v_mov_b32_e32 v85, v30
	v_mov_b32_e32 v86, v30
	v_mov_b32_e32 v87, v30
	v_mov_b32_e32 v88, v30
	v_mov_b32_e32 v89, v30
	v_mov_b32_e32 v90, v30
	v_mov_b32_e32 v91, v30
	v_mov_b32_e32 v92, v30
	v_mov_b32_e32 v93, v30
	v_mov_b32_e32 v94, v30
	v_mov_b32_e32 v95, v30
	v_mov_b32_e32 v96, v30
	v_mov_b32_e32 v97, v30
	v_writelane_b32 v234, s90, 0
	v_writelane_b32 v234, s91, 1
	v_writelane_b32 v234, s92, 2
	v_writelane_b32 v234, s93, 3
	v_writelane_b32 v234, s94, 4
	v_writelane_b32 v234, s95, 5
	v_bfe_u32 v160, v192, 3, 3
	v_and_b32_e32 v161, 7, v192
	v_xor_b32_e32 v161, v160, v161
	v_lshlrev_b32_e32 v161, 4, v161
	v_lshrrev_b32_e32 v162, 6, v192
	v_lshl_add_u32 v163, v162, 5, v160
	v_mul_u32_u24_e32 v163, 0x800, v163
	v_add_u32_e32 v236, v163, v161
	v_add_u32_e32 v237, 0x3c00, v236
	v_add_u32_e32 v238, 0x3c00, v237
	v_add_u32_e32 v239, 0x3c00, v238
	v_lshrrev_b32_e32 v163, 7, v192
	v_bfe_u32 v162, v192, 6, 1
	v_lshlrev_b32_e32 v163, 6, v163
	v_lshl_add_u32 v163, v160, 2, v163
	v_lshl_add_u32 v163, v162, 1, v163
	v_mul_u32_u24_e32 v163, 0x800, v163
	v_add_u32_e32 v240, v163, v161
	v_add_u32_e32 v241, 0xfc00, v240
	v_subrev_u32_e32 v242, 0xfc00, v241
	v_add_u32_e32 v243, 0xfc00, v242
	v_and_b32_e32 v160, 15, v192
	v_bfe_u32 v161, v192, 4, 2
	v_and_b32_e32 v162, 7, v160
	v_xor_b32_e32 v161, v161, v162
	v_lshlrev_b32_e32 v161, 4, v161
	v_lshl_add_u32 v161, v160, 7, v161
	v_lshrrev_b32_e32 v162, 7, v192
	v_lshl_add_u32 v244, v162, 13, v161
	v_bfe_u32 v162, v192, 6, 1
	v_lshl_add_u32 v246, v162, 13, v161
	v_add_u32_e32 v246, 0x4000, v246
	v_xor_b32_e32 v245, 64, v244
	v_xor_b32_e32 v247, 64, v246
	v_lshrrev_b32_e32 v160, 6, v192
	s_nop 0
	v_readfirstlane_b32 s94, v160
	v_readfirstlane_b32 s90, v248
	v_readfirstlane_b32 s91, v249
	v_readfirstlane_b32 s92, v250
	v_readfirstlane_b32 s93, v251
	s_mul_i32 s95, s94, 0x4000
	s_sub_u32 s90, s90, s95
	s_subb_u32 s91, s91, 0
	s_mul_i32 s95, s94, 0x4000
	s_sub_u32 s92, s92, s95
	s_subb_u32 s93, s93, 0
	s_lshl_b32 s94, s94, 10
	s_waitcnt lgkmcnt(0)
	s_barrier
	s_lshl_b32 s95, s94, 2
	s_add_u32 m0, s95, 0x0
	s_nop 0
	global_load_lds_dwordx4 v236, s[90:91]
	global_load_lds_dwordx4 v237, s[90:91] offset:1024
	global_load_lds_dwordx4 v238, s[90:91] offset:2048
	global_load_lds_dwordx4 v239, s[90:91] offset:3072
	s_mul_i32 s95, s94, 4
	s_add_u32 m0, s95, 0x4000
	s_nop 0
	global_load_lds_dwordx4 v240, s[92:93]
	global_load_lds_dwordx4 v241, s[92:93] offset:1024
	global_load_lds_dwordx4 v242, s[92:93] offset:2048
	global_load_lds_dwordx4 v243, s[92:93] offset:3072
	s_add_u32 s90, s90, 0x80
	s_addc_u32 s91, s91, 0
	s_add_u32 s92, s92, 0x80
	s_addc_u32 s93, s93, 0
	s_waitcnt vmcnt(0)
	s_barrier
	s_lshl_b32 s95, s94, 2
	s_add_u32 m0, s95, 0x8000
	s_nop 0
	global_load_lds_dwordx4 v236, s[90:91]
	global_load_lds_dwordx4 v237, s[90:91] offset:1024
	global_load_lds_dwordx4 v238, s[90:91] offset:2048
	global_load_lds_dwordx4 v239, s[90:91] offset:3072
	s_mul_i32 s95, s94, 4
	s_add_u32 m0, s95, 0xc000
	s_nop 0
	global_load_lds_dwordx4 v240, s[92:93]
	global_load_lds_dwordx4 v241, s[92:93] offset:1024
	global_load_lds_dwordx4 v242, s[92:93] offset:2048
	global_load_lds_dwordx4 v243, s[92:93] offset:3072
	s_add_u32 s90, s90, 0x80
	s_addc_u32 s91, s91, 0
	s_add_u32 s92, s92, 0x80
	s_addc_u32 s93, s93, 0
	ds_read_b128 v[110:113], v244 offset:0
	ds_read_b128 v[114:117], v244 offset:2048
	ds_read_b128 v[118:121], v244 offset:4096
	ds_read_b128 v[122:125], v244 offset:6144
	ds_read_b128 v[126:129], v246 offset:0
	ds_read_b128 v[130:133], v246 offset:2048
	ds_read_b128 v[134:137], v246 offset:4096
	ds_read_b128 v[138:141], v246 offset:6144
	s_movk_i32 s95, 0x6
	s_cmp_eq_u32 s95, 0
	s_cbranch_scc1 .Lgemm_x1480

; template <int NT>
; __device__ __forceinline__ void gemm_compute(f32x4 (&acc)[4][NT], const bf16_t* sA, const bf16_t* sB, int wr, int wc, int fr, int fq) {
;     ...
;     for (int ks = 0; ks < 2; ++ks) {
;         bf16x8 a[4], b[NT];
; #pragma unroll
;         for (int mt = 0; mt < 4; ++mt) a[mt] = *(const bf16x8*)(sA + (wr * 64 + mt * 16 + fr) * LDT + ks * 32 + fq * 8);
; #pragma unroll
;         for (int nt = 0; nt < NT; ++nt) b[nt] = *(const bf16x8*)(sB + (wc * 16 * NT + nt * 16 + fr) * LDT + ks * 32 + fq * 8);
;         __builtin_amdgcn_s_setprio(1);
; #pragma unroll
;         for (int mt = 0; mt < 4; ++mt)
; #pragma unroll
;             for (int nt = 0; nt < NT; ++nt)
;                 acc[mt][nt] = __builtin_amdgcn_mfma_f32_16x16x32_bf16(b[nt], a[mt], acc[mt][nt], 0, 0, 0);
;         __builtin_amdgcn_s_setprio(0);
;     }
; template <int NT>
; __device__ __forceinline__ void gemm_tile(f32x4 (&acc)[4][NT], const bf16_t* A, int lda, const bf16_t* B, int ldb, int K, bf16_t* sm) {
;     ...
;     for (int kt = 0; kt < nk; ++kt) {
;         lds_barrier();
; #pragma unroll
;         for (int i = 0; i < 4; ++i) *(u32x4*)(sA + (lrow + 32 * i) * LDT + lkc * 8) = ra0[i];
; #pragma unroll
;         for (int i = 0; i < NT; ++i) *(u32x4*)(sB + sbrow[i] * LDT + lkc * 8) = rb0[i];
;         lds_barrier();
;         if (kt + 1 < nk) {
;             ga += 64; gb += 64;
; #pragma unroll
;             for (int i = 0; i < 4; ++i) ra0[i] = *(const u32x4*)(ga + (size_t)(32 * i) * lda);
; #pragma unroll
;             for (int i = 0; i < NT; ++i) rb0[i] = *(const u32x4*)(gb + (size_t)(32 * i) * ldb);
;         }
;         __builtin_amdgcn_sched_barrier(0);
;         gemm_compute<NT>(acc, sA, sB, wr, wc, fr, fq);
;         __builtin_amdgcn_sched_barrier(0);
;     }
.Lgemm_x1480:
	ds_read_b128 v[160:163], v245 offset:0
	ds_read_b128 v[164:167], v245 offset:2048
	ds_read_b128 v[168:171], v245 offset:4096
	ds_read_b128 v[172:175], v245 offset:6144
	ds_read_b128 v[176:179], v247 offset:0
	ds_read_b128 v[180:183], v247 offset:2048
	ds_read_b128 v[184:187], v247 offset:4096
	ds_read_b128 v[188:191], v247 offset:6144
	s_setprio 1
	s_waitcnt lgkmcnt(11)
	v_mfma_f32_16x16x32_bf16 v[94:97], v[126:129], v[110:113], v[94:97]
	s_waitcnt lgkmcnt(10)
	v_mfma_f32_16x16x32_bf16 v[90:93], v[130:133], v[110:113], v[90:93]
	s_waitcnt lgkmcnt(9)
	v_mfma_f32_16x16x32_bf16 v[86:89], v[134:137], v[110:113], v[86:89]
	s_waitcnt lgkmcnt(8)
	v_mfma_f32_16x16x32_bf16 v[82:85], v[138:141], v[110:113], v[82:85]
	v_mfma_f32_16x16x32_bf16 v[78:81], v[126:129], v[114:117], v[78:81]
	v_mfma_f32_16x16x32_bf16 v[74:77], v[130:133], v[114:117], v[74:77]
	v_mfma_f32_16x16x32_bf16 v[70:73], v[134:137], v[114:117], v[70:73]
	v_mfma_f32_16x16x32_bf16 v[66:69], v[138:141], v[114:117], v[66:69]
	v_mfma_f32_16x16x32_bf16 v[62:65], v[126:129], v[118:121], v[62:65]
	v_mfma_f32_16x16x32_bf16 v[58:61], v[130:133], v[118:121], v[58:61]
	v_mfma_f32_16x16x32_bf16 v[54:57], v[134:137], v[118:121], v[54:57]
	v_mfma_f32_16x16x32_bf16 v[50:53], v[138:141], v[118:121], v[50:53]
	v_mfma_f32_16x16x32_bf16 v[46:49], v[126:129], v[122:125], v[46:49]
	v_mfma_f32_16x16x32_bf16 v[42:45], v[130:133], v[122:125], v[42:45]
	v_mfma_f32_16x16x32_bf16 v[38:41], v[134:137], v[122:125], v[38:41]
	v_mfma_f32_16x16x32_bf16 v[30:33], v[138:141], v[122:125], v[30:33]
	s_setprio 0
	s_waitcnt vmcnt(0) lgkmcnt(0)
	s_barrier
	ds_read_b128 v[110:113], v244 offset:32768
	ds_read_b128 v[114:117], v244 offset:34816
	ds_read_b128 v[118:121], v244 offset:36864
	ds_read_b128 v[122:125], v244 offset:38912
	ds_read_b128 v[126:129], v246 offset:32768
	ds_read_b128 v[130:133], v246 offset:34816
	ds_read_b128 v[134:137], v246 offset:36864
	ds_read_b128 v[138:141], v246 offset:38912
	s_setprio 1
	v_mfma_f32_16x16x32_bf16 v[94:97], v[176:179], v[160:163], v[94:97]
	s_lshl_b32 s95, s94, 2
	s_add_u32 m0, s95, 0x0
	s_nop 0
	global_load_lds_dwordx4 v236, s[90:91]
	v_mfma_f32_16x16x32_bf16 v[90:93], v[180:183], v[160:163], v[90:93]
	v_mfma_f32_16x16x32_bf16 v[86:89], v[184:187], v[160:163], v[86:89]
	global_load_lds_dwordx4 v237, s[90:91] offset:1024
	v_mfma_f32_16x16x32_bf16 v[82:85], v[188:191], v[160:163], v[82:85]
	v_mfma_f32_16x16x32_bf16 v[78:81], v[176:179], v[164:167], v[78:81]
	global_load_lds_dwordx4 v238, s[90:91] offset:2048
	v_mfma_f32_16x16x32_bf16 v[74:77], v[180:183], v[164:167], v[74:77]
	v_mfma_f32_16x16x32_bf16 v[70:73], v[184:187], v[164:167], v[70:73]
	global_load_lds_dwordx4 v239, s[90:91] offset:3072
	v_mfma_f32_16x16x32_bf16 v[66:69], v[188:191], v[164:167], v[66:69]
	v_mfma_f32_16x16x32_bf16 v[62:65], v[176:179], v[168:171], v[62:65]
	s_mul_i32 s95, s94, 4
	s_add_u32 m0, s95, 0x4000
	s_nop 0
	global_load_lds_dwordx4 v240, s[92:93]
	v_mfma_f32_16x16x32_bf16 v[58:61], v[180:183], v[168:171], v[58:61]
	v_mfma_f32_16x16x32_bf16 v[54:57], v[184:187], v[168:171], v[54:57]
	global_load_lds_dwordx4 v241, s[92:93] offset:1024
	v_mfma_f32_16x16x32_bf16 v[50:53], v[188:191], v[168:171], v[50:53]
	v_mfma_f32_16x16x32_bf16 v[46:49], v[176:179], v[172:175], v[46:49]
	global_load_lds_dwordx4 v242, s[92:93] offset:2048
	v_mfma_f32_16x16x32_bf16 v[42:45], v[180:183], v[172:175], v[42:45]
	v_mfma_f32_16x16x32_bf16 v[38:41], v[184:187], v[172:175], v[38:41]
	global_load_lds_dwordx4 v243, s[92:93] offset:3072
	v_mfma_f32_16x16x32_bf16 v[30:33], v[188:191], v[172:175], v[30:33]
	s_add_u32 s90, s90, 0x80
	s_addc_u32 s91, s91, 0
	s_add_u32 s92, s92, 0x80
	s_addc_u32 s93, s93, 0
	s_setprio 0
	ds_read_b128 v[160:163], v245 offset:32768
	ds_read_b128 v[164:167], v245 offset:34816
	ds_read_b128 v[168:171], v245 offset:36864
	ds_read_b128 v[172:175], v245 offset:38912
	ds_read_b128 v[176:179], v247 offset:32768
	ds_read_b128 v[180:183], v247 offset:34816
	ds_read_b128 v[184:187], v247 offset:36864
	ds_read_b128 v[188:191], v247 offset:38912
	s_setprio 1
	s_waitcnt lgkmcnt(11)
	v_mfma_f32_16x16x32_bf16 v[94:97], v[126:129], v[110:113], v[94:97]
	s_waitcnt lgkmcnt(10)
	v_mfma_f32_16x16x32_bf16 v[90:93], v[130:133], v[110:113], v[90:93]
	s_waitcnt lgkmcnt(9)
	v_mfma_f32_16x16x32_bf16 v[86:89], v[134:137], v[110:113], v[86:89]
	s_waitcnt lgkmcnt(8)
	v_mfma_f32_16x16x32_bf16 v[82:85], v[138:141], v[110:113], v[82:85]
	v_mfma_f32_16x16x32_bf16 v[78:81], v[126:129], v[114:117], v[78:81]
	v_mfma_f32_16x16x32_bf16 v[74:77], v[130:133], v[114:117], v[74:77]
	v_mfma_f32_16x16x32_bf16 v[70:73], v[134:137], v[114:117], v[70:73]
	v_mfma_f32_16x16x32_bf16 v[66:69], v[138:141], v[114:117], v[66:69]
	v_mfma_f32_16x16x32_bf16 v[62:65], v[126:129], v[118:121], v[62:65]
	v_mfma_f32_16x16x32_bf16 v[58:61], v[130:133], v[118:121], v[58:61]
	v_mfma_f32_16x16x32_bf16 v[54:57], v[134:137], v[118:121], v[54:57]
	v_mfma_f32_16x16x32_bf16 v[50:53], v[138:141], v[118:121], v[50:53]
	v_mfma_f32_16x16x32_bf16 v[46:49], v[126:129], v[122:125], v[46:49]
	v_mfma_f32_16x16x32_bf16 v[42:45], v[130:133], v[122:125], v[42:45]
	v_mfma_f32_16x16x32_bf16 v[38:41], v[134:137], v[122:125], v[38:41]
	v_mfma_f32_16x16x32_bf16 v[30:33], v[138:141], v[122:125], v[30:33]
	s_setprio 0
	s_waitcnt vmcnt(0) lgkmcnt(0)
	s_barrier
; template <int NT>
; __device__ __forceinline__ void gemm_compute(f32x4 (&acc)[4][NT], const bf16_t* sA, const bf16_t* sB, int wr, int wc, int fr, int fq) {
;     ...
;     for (int ks = 0; ks < 2; ++ks) {
;         bf16x8 a[4], b[NT];
; #pragma unroll
;         for (int mt = 0; mt < 4; ++mt) a[mt] = *(const bf16x8*)(sA + (wr * 64 + mt * 16 + fr) * LDT + ks * 32 + fq * 8);
; #pragma unroll
;         for (int nt = 0; nt < NT; ++nt) b[nt] = *(const bf16x8*)(sB + (wc * 16 * NT + nt * 16 + fr) * LDT + ks * 32 + fq * 8);
;         __builtin_amdgcn_s_setprio(1);
; #pragma unroll
;         for (int mt = 0; mt < 4; ++mt)
; #pragma unroll
;             for (int nt = 0; nt < NT; ++nt)
;                 acc[mt][nt] = __builtin_amdgcn_mfma_f32_16x16x32_bf16(b[nt], a[mt], acc[mt][nt], 0, 0, 0);
;         __builtin_amdgcn_s_setprio(0);
;     }
; template <int NT>
; __device__ __forceinline__ void gemm_tile(f32x4 (&acc)[4][NT], const bf16_t* A, int lda, const bf16_t* B, int ldb, int K, bf16_t* sm) {
;     ...
;     for (int kt = 0; kt < nk; ++kt) {
;         lds_barrier();
; #pragma unroll
;         for (int i = 0; i < 4; ++i) *(u32x4*)(sA + (lrow + 32 * i) * LDT + lkc * 8) = ra0[i];
; #pragma unroll
;         for (int i = 0; i < NT; ++i) *(u32x4*)(sB + sbrow[i] * LDT + lkc * 8) = rb0[i];
;         lds_barrier();
;         if (kt + 1 < nk) {
;             ga += 64; gb += 64;
; #pragma unroll
;             for (int i = 0; i < 4; ++i) ra0[i] = *(const u32x4*)(ga + (size_t)(32 * i) * lda);
; #pragma unroll
;             for (int i = 0; i < NT; ++i) rb0[i] = *(const u32x4*)(gb + (size_t)(32 * i) * ldb);
;         }
;         __builtin_amdgcn_sched_barrier(0);
;         gemm_compute<NT>(acc, sA, sB, wr, wc, fr, fq);
;         __builtin_amdgcn_sched_barrier(0);
;     }
	ds_read_b128 v[110:113], v244 offset:0
	ds_read_b128 v[114:117], v244 offset:2048
	ds_read_b128 v[118:121], v244 offset:4096
	ds_read_b128 v[122:125], v244 offset:6144
	ds_read_b128 v[126:129], v246 offset:0
	ds_read_b128 v[130:133], v246 offset:2048
	ds_read_b128 v[134:137], v246 offset:4096
	ds_read_b128 v[138:141], v246 offset:6144
	s_setprio 1
	v_mfma_f32_16x16x32_bf16 v[94:97], v[176:179], v[160:163], v[94:97]
	v_readlane_b32 s90, v234, 0
	v_readlane_b32 s91, v234, 1
	v_readlane_b32 s92, v234, 2
	v_readlane_b32 s93, v234, 3
	v_readlane_b32 s94, v234, 4
	v_readlane_b32 s95, v234, 5
	s_mov_b32 s22, 0x700
	s_mov_b32 s23, 0
	s_nop 3
	v_mfma_f32_16x16x32_bf16 v[90:93], v[180:183], v[160:163], v[90:93]
	v_mfma_f32_16x16x32_bf16 v[86:89], v[184:187], v[160:163], v[86:89]
	v_lshl_add_u64 v[0:1], v[98:99], 0, s[22:23]
	v_mfma_f32_16x16x32_bf16 v[82:85], v[188:191], v[160:163], v[82:85]
	v_mfma_f32_16x16x32_bf16 v[78:81], v[176:179], v[164:167], v[78:81]
	v_add_co_u32_e32 v2, vcc, s0, v0
	v_mfma_f32_16x16x32_bf16 v[74:77], v[180:183], v[164:167], v[74:77]
	v_mfma_f32_16x16x32_bf16 v[70:73], v[184:187], v[164:167], v[70:73]
	s_nop 0
	v_mfma_f32_16x16x32_bf16 v[66:69], v[188:191], v[164:167], v[66:69]
	v_mfma_f32_16x16x32_bf16 v[62:65], v[176:179], v[168:171], v[62:65]
	s_nop 0
	v_mfma_f32_16x16x32_bf16 v[58:61], v[180:183], v[168:171], v[58:61]
	v_mfma_f32_16x16x32_bf16 v[54:57], v[184:187], v[168:171], v[54:57]
	v_addc_co_u32_e32 v3, vcc, 0, v1, vcc
	v_mfma_f32_16x16x32_bf16 v[50:53], v[188:191], v[168:171], v[50:53]
	v_mfma_f32_16x16x32_bf16 v[46:49], v[176:179], v[172:175], v[46:49]
	v_add_co_u32_e32 v4, vcc, s64, v0
	v_mfma_f32_16x16x32_bf16 v[42:45], v[180:183], v[172:175], v[42:45]
	v_mfma_f32_16x16x32_bf16 v[38:41], v[184:187], v[172:175], v[38:41]
	v_lshl_add_u64 v[8:9], v[100:101], 0, s[22:23]
	v_mfma_f32_16x16x32_bf16 v[30:33], v[188:191], v[172:175], v[30:33]
	s_nop 0
	v_addc_co_u32_e32 v5, vcc, 0, v1, vcc
	global_load_dwordx4 v[22:25], v[2:3], off offset:128
	global_load_dwordx4 v[18:21], v[4:5], off offset:128
	v_add_co_u32_e32 v2, vcc, s65, v0
	s_nop 1
	v_addc_co_u32_e32 v3, vcc, 0, v1, vcc
	v_add_co_u32_e32 v0, vcc, s33, v0
	s_nop 1
	v_addc_co_u32_e32 v1, vcc, 0, v1, vcc
	global_load_dwordx4 v[26:29], v[2:3], off offset:128
	global_load_dwordx4 v[34:37], v[0:1], off offset:128
	v_add_co_u32_e32 v0, vcc, s7, v8
	s_nop 1
	v_addc_co_u32_e32 v1, vcc, 0, v9, vcc
	v_add_co_u32_e32 v10, vcc, s37, v8
	global_load_dwordx4 v[4:7], v[8:9], off offset:128
	s_nop 0
	global_load_dwordx4 v[0:3], v[0:1], off offset:128
	v_addc_co_u32_e32 v11, vcc, 0, v9, vcc
	v_add_co_u32_e32 v14, vcc, s73, v8
	s_nop 1
	v_addc_co_u32_e32 v15, vcc, 0, v9, vcc
	global_load_dwordx4 v[8:11], v[10:11], off offset:128
	s_nop 0
	global_load_dwordx4 v[14:17], v[14:15], off offset:128
	s_setprio 0
	ds_read_b128 v[160:163], v245 offset:0
	ds_read_b128 v[164:167], v245 offset:2048
	ds_read_b128 v[168:171], v245 offset:4096
	ds_read_b128 v[172:175], v245 offset:6144
	ds_read_b128 v[176:179], v247 offset:0
	ds_read_b128 v[180:183], v247 offset:2048
	ds_read_b128 v[184:187], v247 offset:4096
	ds_read_b128 v[188:191], v247 offset:6144
	s_setprio 1
	s_waitcnt lgkmcnt(11)
	v_mfma_f32_16x16x32_bf16 v[94:97], v[126:129], v[110:113], v[94:97]
	s_waitcnt lgkmcnt(10)
	v_mfma_f32_16x16x32_bf16 v[90:93], v[130:133], v[110:113], v[90:93]
	s_waitcnt lgkmcnt(9)
	v_mfma_f32_16x16x32_bf16 v[86:89], v[134:137], v[110:113], v[86:89]
	s_waitcnt lgkmcnt(8)
	v_mfma_f32_16x16x32_bf16 v[82:85], v[138:141], v[110:113], v[82:85]
	v_mfma_f32_16x16x32_bf16 v[78:81], v[126:129], v[114:117], v[78:81]
	v_mfma_f32_16x16x32_bf16 v[74:77], v[130:133], v[114:117], v[74:77]
	v_mfma_f32_16x16x32_bf16 v[70:73], v[134:137], v[114:117], v[70:73]
	v_mfma_f32_16x16x32_bf16 v[66:69], v[138:141], v[114:117], v[66:69]
	v_mfma_f32_16x16x32_bf16 v[62:65], v[126:129], v[118:121], v[62:65]
	v_mfma_f32_16x16x32_bf16 v[58:61], v[130:133], v[118:121], v[58:61]
	v_mfma_f32_16x16x32_bf16 v[54:57], v[134:137], v[118:121], v[54:57]
	v_mfma_f32_16x16x32_bf16 v[50:53], v[138:141], v[118:121], v[50:53]
	v_mfma_f32_16x16x32_bf16 v[46:49], v[126:129], v[122:125], v[46:49]
	v_mfma_f32_16x16x32_bf16 v[42:45], v[130:133], v[122:125], v[42:45]
	v_mfma_f32_16x16x32_bf16 v[38:41], v[134:137], v[122:125], v[38:41]
	v_mfma_f32_16x16x32_bf16 v[30:33], v[138:141], v[122:125], v[30:33]
	s_setprio 0
	s_waitcnt lgkmcnt(0)
	s_setprio 1
	v_mfma_f32_16x16x32_bf16 v[94:97], v[176:179], v[160:163], v[94:97]
	v_mfma_f32_16x16x32_bf16 v[90:93], v[180:183], v[160:163], v[90:93]
	v_mfma_f32_16x16x32_bf16 v[86:89], v[184:187], v[160:163], v[86:89]
	v_mfma_f32_16x16x32_bf16 v[82:85], v[188:191], v[160:163], v[82:85]
	v_mfma_f32_16x16x32_bf16 v[78:81], v[176:179], v[164:167], v[78:81]
	v_mfma_f32_16x16x32_bf16 v[74:77], v[180:183], v[164:167], v[74:77]
	v_mfma_f32_16x16x32_bf16 v[70:73], v[184:187], v[164:167], v[70:73]
	v_mfma_f32_16x16x32_bf16 v[66:69], v[188:191], v[164:167], v[66:69]
	v_mfma_f32_16x16x32_bf16 v[62:65], v[176:179], v[168:171], v[62:65]
	v_mfma_f32_16x16x32_bf16 v[58:61], v[180:183], v[168:171], v[58:61]
	v_mfma_f32_16x16x32_bf16 v[54:57], v[184:187], v[168:171], v[54:57]
	v_mfma_f32_16x16x32_bf16 v[50:53], v[188:191], v[168:171], v[50:53]
	v_mfma_f32_16x16x32_bf16 v[46:49], v[176:179], v[172:175], v[46:49]
	v_mfma_f32_16x16x32_bf16 v[42:45], v[180:183], v[172:175], v[42:45]
	v_mfma_f32_16x16x32_bf16 v[38:41], v[184:187], v[172:175], v[38:41]
	v_mfma_f32_16x16x32_bf16 v[30:33], v[188:191], v[172:175], v[30:33]
	s_setprio 0
	s_waitcnt lgkmcnt(0)
	s_barrier
; __device__ __forceinline__ float silu_(float x) { return x * __builtin_amdgcn_rcpf(1.f + __expf(-x)); }
; template <int NT>
; __device__ __forceinline__ void gemm_tile(f32x4 (&acc)[4][NT], const bf16_t* A, int lda, const bf16_t* B, int ldb, int K, bf16_t* sm) {
;     ...
;         for (int i = 0; i < 4; ++i) *(u32x4*)(sA + (lrow + 32 * i) * LDT + lkc * 8) = ra0[i];
; #pragma unroll
;         for (int i = 0; i < NT; ++i) *(u32x4*)(sB + sbrow[i] * LDT + lkc * 8) = rb0[i];
;         lds_barrier();
;         if (kt + 1 < nk) {
;             ga += 64; gb += 64;
; #pragma unroll
;             for (int i = 0; i < 4; ++i) ra0[i] = *(const u32x4*)(ga + (size_t)(32 * i) * lda);
; #pragma unroll
;             for (int i = 0; i < NT; ++i) rb0[i] = *(const u32x4*)(gb + (size_t)(32 * i) * ldb);
;         }
;         __builtin_amdgcn_sched_barrier(0);
;         gemm_compute<NT>(acc, sA, sB, wr, wc, fr, fq);
; __device__ __forceinline__ void phase_ffn_in(const bf16_t* xb, const bf16_t* W, bf16_t* H, bf16_t* sm) {
;     ...
; #pragma unroll
;         for (int mt = 0; mt < 4; ++mt) {
;             const int row = tm * 128 + wr * 64 + mt * 16 + fr;
;             const int hc = tn * 64 + wc * 32 + fq * 8;
;             float v[16]; gather_cols<4>(acc, mt, v);
;             u32x4 o;
; #pragma unroll
;             for (int q = 0; q < 4; ++q) o[q] = pack2(silu_(v[4 * q]) * v[4 * q + 1], silu_(v[4 * q + 2]) * v[4 * q + 3]);
;             *(u32x4*)(H + (size_t)row * 2048 + hc) = o;
	s_waitcnt vmcnt(7)
	ds_write_b128 v105, v[22:25]
	s_waitcnt vmcnt(6)
	ds_write_b128 v105, v[18:21] offset:5120
	s_waitcnt vmcnt(5)
	ds_write_b128 v105, v[26:29] offset:10240
	s_waitcnt vmcnt(4)
	ds_write_b128 v105, v[34:37] offset:15360
	s_waitcnt vmcnt(3)
	ds_write_b128 v106, v[4:7] offset:20480
	s_waitcnt vmcnt(2)
	ds_write_b128 v107, v[0:3] offset:20480
	s_waitcnt vmcnt(1)
	ds_write_b128 v108, v[8:11] offset:20480
	s_waitcnt vmcnt(0)
	ds_write_b128 v109, v[14:17] offset:20480
	s_waitcnt lgkmcnt(0)
	s_barrier
	ds_read_b128 v[0:3], v104
	ds_read_b128 v[4:7], v104 offset:2560
	ds_read_b128 v[8:11], v104 offset:5120
	ds_read_b128 v[14:17], v104 offset:7680
	ds_read_b128 v[18:21], v12 offset:20480
	ds_read_b128 v[22:25], v12 offset:23040
	ds_read_b128 v[26:29], v12 offset:25600
	ds_read_b128 v[34:37], v12 offset:28160
	s_setprio 1
	s_waitcnt lgkmcnt(3)
	v_mfma_f32_16x16x32_bf16 v[94:97], v[18:21], v[0:3], v[94:97]
	s_waitcnt lgkmcnt(2)
	v_mfma_f32_16x16x32_bf16 v[90:93], v[22:25], v[0:3], v[90:93]
	s_waitcnt lgkmcnt(1)
	v_mfma_f32_16x16x32_bf16 v[86:89], v[26:29], v[0:3], v[86:89]
	s_waitcnt lgkmcnt(0)
	v_mfma_f32_16x16x32_bf16 v[0:3], v[34:37], v[0:3], v[82:85]
	v_mfma_f32_16x16x32_bf16 v[78:81], v[18:21], v[4:7], v[78:81]
	v_mfma_f32_16x16x32_bf16 v[74:77], v[22:25], v[4:7], v[74:77]
	v_mfma_f32_16x16x32_bf16 v[70:73], v[26:29], v[4:7], v[70:73]
	v_mfma_f32_16x16x32_bf16 v[4:7], v[34:37], v[4:7], v[66:69]
	v_mfma_f32_16x16x32_bf16 v[62:65], v[18:21], v[8:11], v[62:65]
	v_mfma_f32_16x16x32_bf16 v[58:61], v[22:25], v[8:11], v[58:61]
	v_mfma_f32_16x16x32_bf16 v[54:57], v[26:29], v[8:11], v[54:57]
	v_mfma_f32_16x16x32_bf16 v[8:11], v[34:37], v[8:11], v[50:53]
	v_mfma_f32_16x16x32_bf16 v[46:49], v[18:21], v[14:17], v[46:49]
	v_mfma_f32_16x16x32_bf16 v[42:45], v[22:25], v[14:17], v[42:45]
	v_mfma_f32_16x16x32_bf16 v[38:41], v[26:29], v[14:17], v[38:41]
	v_mfma_f32_16x16x32_bf16 v[34:37], v[34:37], v[14:17], v[30:33]
	s_setprio 0
	ds_read_b128 v[14:17], v104 offset:64
	ds_read_b128 v[18:21], v104 offset:2624
	ds_read_b128 v[22:25], v104 offset:5184
	ds_read_b128 v[50:53], v104 offset:7744
	ds_read_b128 v[66:69], v12 offset:20544
	ds_read_b128 v[82:85], v12 offset:23104
	ds_read_b128 v[98:101], v12 offset:25664
	ds_read_b128 v[104:107], v12 offset:28224
	s_setprio 1
	s_waitcnt lgkmcnt(3)
	v_mfma_f32_16x16x32_bf16 v[94:97], v[66:69], v[14:17], v[94:97]
	s_waitcnt lgkmcnt(2)
	v_mfma_f32_16x16x32_bf16 v[90:93], v[82:85], v[14:17], v[90:93]
	s_waitcnt lgkmcnt(1)
	v_mfma_f32_16x16x32_bf16 v[86:89], v[98:101], v[14:17], v[86:89]
	s_waitcnt lgkmcnt(0)
	v_mfma_f32_16x16x32_bf16 v[108:111], v[104:107], v[14:17], v[0:3]
	v_mfma_f32_16x16x32_bf16 v[78:81], v[66:69], v[18:21], v[78:81]
	v_mfma_f32_16x16x32_bf16 v[74:77], v[82:85], v[18:21], v[74:77]
	v_mfma_f32_16x16x32_bf16 v[70:73], v[98:101], v[18:21], v[70:73]
	v_mfma_f32_16x16x32_bf16 v[112:115], v[104:107], v[18:21], v[4:7]
	v_mfma_f32_16x16x32_bf16 v[30:33], v[66:69], v[22:25], v[62:65]
	v_mfma_f32_16x16x32_bf16 v[18:21], v[82:85], v[22:25], v[58:61]
	v_mfma_f32_16x16x32_bf16 v[26:29], v[98:101], v[22:25], v[54:57]
	v_mfma_f32_16x16x32_bf16 v[22:25], v[104:107], v[22:25], v[8:11]
	v_mfma_f32_16x16x32_bf16 v[14:17], v[66:69], v[50:53], v[46:49]
	v_mfma_f32_16x16x32_bf16 v[0:3], v[82:85], v[50:53], v[42:45]
	v_mfma_f32_16x16x32_bf16 v[8:11], v[98:101], v[50:53], v[38:41]
	v_mfma_f32_16x16x32_bf16 v[4:7], v[104:107], v[50:53], v[34:37]
	s_setprio 0
	v_mul_f32_e32 v12, 0xbfb8aa3b, v94
	s_nop 0
	v_exp_f32_e32 v35, v12
	v_mul_f32_e32 v12, 0xbfb8aa3b, v86
	v_exp_f32_e32 v36, v12
	v_lshl_or_b32 v12, s12, 7, v103
	v_add_f32_e32 v35, 1.0, v35
	v_rcp_f32_e32 v38, v35
	v_add_f32_e32 v35, 1.0, v36
	v_lshl_add_u64 v[36:37], s[8:9], 0, v[12:13]
	v_mul_f32_e32 v12, 0xbfb8aa3b, v95
	v_rcp_f32_e32 v39, v35
	v_exp_f32_e32 v12, v12
	v_mul_f32_e32 v35, 0xbfb8aa3b, v87
	v_exp_f32_e32 v35, v35
	v_mov_b32_e32 v40, v94
	v_add_f32_e32 v12, 1.0, v12
	v_rcp_f32_e32 v42, v12
	v_add_f32_e32 v12, 1.0, v35
	v_rcp_f32_e32 v43, v12
	v_mul_f32_e32 v12, 0xbfb8aa3b, v96
	v_exp_f32_e32 v12, v12
	v_mul_f32_e32 v35, 0xbfb8aa3b, v88
	v_exp_f32_e32 v35, v35
	v_mov_b32_e32 v41, v86
	v_pk_mul_f32 v[38:39], v[40:41], v[38:39]
	v_mov_b32_e32 v40, v90
	v_mov_b32_e32 v41, v108
	v_mov_b32_e32 v86, v95
	v_add_f32_e32 v12, 1.0, v12
	v_pk_mul_f32 v[38:39], v[40:41], v[38:39]
	v_pk_mul_f32 v[40:41], v[86:87], v[42:43]
	v_rcp_f32_e32 v42, v12
	v_add_f32_e32 v12, 1.0, v35
	v_rcp_f32_e32 v43, v12
	v_mul_f32_e32 v12, 0xbfb8aa3b, v97
	v_exp_f32_e32 v12, v12
	v_mul_f32_e32 v35, 0xbfb8aa3b, v89
	v_exp_f32_e32 v35, v35
	v_mov_b32_e32 v108, v91
	v_add_f32_e32 v12, 1.0, v12
	v_rcp_f32_e32 v44, v12
	v_add_f32_e32 v12, 1.0, v35
	v_rcp_f32_e32 v45, v12
	v_pk_mul_f32 v[40:41], v[108:109], v[40:41]
	v_cvt_pk_bf16_f32 v38, v38, v39
	v_cvt_pk_bf16_f32 v39, v40, v41
	v_mov_b32_e32 v40, v96
	v_mov_b32_e32 v41, v88
	v_pk_mul_f32 v[40:41], v[40:41], v[42:43]
	v_mov_b32_e32 v42, v92
	v_mov_b32_e32 v43, v110
	v_mov_b32_e32 v88, v97
	v_lshl_add_u32 v34, s18, 7, v102
	v_pk_mul_f32 v[40:41], v[42:43], v[40:41]
	v_pk_mul_f32 v[42:43], v[88:89], v[44:45]
	v_mov_b32_e32 v110, v93
	v_pk_mul_f32 v[42:43], v[110:111], v[42:43]
	v_ashrrev_i32_e32 v35, 31, v34
	v_mul_f32_e32 v12, 0xbfb8aa3b, v78
	v_cvt_pk_bf16_f32 v40, v40, v41
	v_cvt_pk_bf16_f32 v41, v42, v43
	v_lshlrev_b64 v[42:43], 12, v[34:35]
	v_exp_f32_e32 v12, v12
	v_mul_f32_e32 v35, 0xbfb8aa3b, v70
	v_exp_f32_e32 v35, v35
	v_lshl_add_u64 v[42:43], v[36:37], 0, v[42:43]
; __device__ __forceinline__ float silu_(float x) { return x * __builtin_amdgcn_rcpf(1.f + __expf(-x)); }
; __device__ __forceinline__ void phase_ffn_in(const bf16_t* xb, const bf16_t* W, bf16_t* H, bf16_t* sm) {
;     ...
; #pragma unroll
;         for (int mt = 0; mt < 4; ++mt) {
;             const int row = tm * 128 + wr * 64 + mt * 16 + fr;
;             const int hc = tn * 64 + wc * 32 + fq * 8;
;             float v[16]; gather_cols<4>(acc, mt, v);
;             u32x4 o;
; #pragma unroll
;             for (int q = 0; q < 4; ++q) o[q] = pack2(silu_(v[4 * q]) * v[4 * q + 1], silu_(v[4 * q + 2]) * v[4 * q + 3]);
;             *(u32x4*)(H + (size_t)row * 2048 + hc) = o;
;         }
	v_add_f32_e32 v12, 1.0, v12
	v_rcp_f32_e32 v44, v12
	v_add_f32_e32 v12, 1.0, v35
	v_rcp_f32_e32 v45, v12
	v_mul_f32_e32 v12, 0xbfb8aa3b, v79
	v_exp_f32_e32 v12, v12
	v_mul_f32_e32 v35, 0xbfb8aa3b, v71
	v_exp_f32_e32 v35, v35
	global_store_dwordx4 v[42:43], v[38:41], off
	v_add_f32_e32 v12, 1.0, v12
	v_rcp_f32_e32 v42, v12
	v_add_f32_e32 v12, 1.0, v35
	v_rcp_f32_e32 v43, v12
	v_mul_f32_e32 v12, 0xbfb8aa3b, v80
	v_exp_f32_e32 v12, v12
	v_mul_f32_e32 v35, 0xbfb8aa3b, v72
	v_exp_f32_e32 v35, v35
	v_mov_b32_e32 v38, v78
	v_mov_b32_e32 v39, v70
	v_pk_mul_f32 v[38:39], v[38:39], v[44:45]
	v_mov_b32_e32 v40, v74
	v_mov_b32_e32 v41, v112
	v_mov_b32_e32 v70, v79
	v_add_f32_e32 v12, 1.0, v12
	v_pk_mul_f32 v[38:39], v[40:41], v[38:39]
	v_pk_mul_f32 v[40:41], v[70:71], v[42:43]
	v_rcp_f32_e32 v42, v12
	v_add_f32_e32 v12, 1.0, v35
	v_rcp_f32_e32 v43, v12
	v_mul_f32_e32 v12, 0xbfb8aa3b, v81
	v_exp_f32_e32 v12, v12
	v_mul_f32_e32 v35, 0xbfb8aa3b, v73
	v_exp_f32_e32 v35, v35
	v_mov_b32_e32 v112, v75
	v_add_f32_e32 v12, 1.0, v12
	v_rcp_f32_e32 v44, v12
	v_add_f32_e32 v12, 1.0, v35
	v_rcp_f32_e32 v45, v12
	v_pk_mul_f32 v[40:41], v[112:113], v[40:41]
	v_cvt_pk_bf16_f32 v38, v38, v39
	v_cvt_pk_bf16_f32 v39, v40, v41
	v_mov_b32_e32 v40, v80
	v_mov_b32_e32 v41, v72
	v_mul_f32_e32 v12, 0xbfb8aa3b, v30
	v_pk_mul_f32 v[40:41], v[40:41], v[42:43]
	v_mov_b32_e32 v42, v76
	v_mov_b32_e32 v43, v114
	v_mov_b32_e32 v72, v81
	v_exp_f32_e32 v12, v12
	v_mul_f32_e32 v35, 0xbfb8aa3b, v26
	v_pk_mul_f32 v[40:41], v[42:43], v[40:41]
	v_pk_mul_f32 v[42:43], v[72:73], v[44:45]
	v_mov_b32_e32 v114, v77
	v_exp_f32_e32 v35, v35
	v_pk_mul_f32 v[42:43], v[114:115], v[42:43]
	v_cvt_pk_bf16_f32 v40, v40, v41
	v_cvt_pk_bf16_f32 v41, v42, v43
	v_or_b32_e32 v42, 16, v34
	v_ashrrev_i32_e32 v43, 31, v42
	v_add_f32_e32 v12, 1.0, v12
	v_lshlrev_b64 v[42:43], 12, v[42:43]
	v_rcp_f32_e32 v44, v12
	v_add_f32_e32 v12, 1.0, v35
	v_lshl_add_u64 v[42:43], v[36:37], 0, v[42:43]
	v_rcp_f32_e32 v45, v12
	v_mul_f32_e32 v12, 0xbfb8aa3b, v31
	global_store_dwordx4 v[42:43], v[38:41], off
	v_exp_f32_e32 v12, v12
	s_add_i32 s11, s11, s62
	v_mov_b32_e32 v40, v18
	v_mul_f32_e32 v18, 0xbfb8aa3b, v27
	v_exp_f32_e32 v18, v18
	v_add_f32_e32 v12, 1.0, v12
	v_rcp_f32_e32 v42, v12
	v_mov_b32_e32 v41, v22
	v_add_f32_e32 v12, 1.0, v18
	v_rcp_f32_e32 v43, v12
	v_mul_f32_e32 v12, 0xbfb8aa3b, v32
	v_mov_b32_e32 v22, v19
	v_exp_f32_e32 v12, v12
	v_mul_f32_e32 v19, 0xbfb8aa3b, v28
	v_exp_f32_e32 v19, v19
	v_mov_b32_e32 v39, v26
	v_mov_b32_e32 v26, v31
	v_pk_mul_f32 v[26:27], v[26:27], v[42:43]
	v_add_f32_e32 v12, 1.0, v12
	v_pk_mul_f32 v[22:23], v[22:23], v[26:27]
	v_rcp_f32_e32 v26, v12
	v_add_f32_e32 v12, 1.0, v19
	v_rcp_f32_e32 v27, v12
	v_cvt_pk_bf16_f32 v19, v22, v23
	v_mov_b32_e32 v22, v32
	v_mov_b32_e32 v23, v28
	v_mul_f32_e32 v12, 0xbfb8aa3b, v33
	v_pk_mul_f32 v[22:23], v[22:23], v[26:27]
	v_mov_b32_e32 v26, v20
	v_exp_f32_e32 v12, v12
	v_mul_f32_e32 v20, 0xbfb8aa3b, v29
	v_exp_f32_e32 v20, v20
	v_mov_b32_e32 v38, v30
	v_add_f32_e32 v12, 1.0, v12
	v_rcp_f32_e32 v30, v12
	v_add_f32_e32 v12, 1.0, v20
	v_rcp_f32_e32 v31, v12
	v_mov_b32_e32 v27, v24
	v_pk_mul_f32 v[22:23], v[26:27], v[22:23]
	v_mov_b32_e32 v28, v33
	v_cvt_pk_bf16_f32 v20, v22, v23
	v_pk_mul_f32 v[22:23], v[28:29], v[30:31]
	v_mov_b32_e32 v24, v21
	v_pk_mul_f32 v[22:23], v[24:25], v[22:23]
	v_pk_mul_f32 v[38:39], v[38:39], v[44:45]
	v_cvt_pk_bf16_f32 v21, v22, v23
	v_or_b32_e32 v22, 32, v34
	v_ashrrev_i32_e32 v23, 31, v22
	v_pk_mul_f32 v[38:39], v[40:41], v[38:39]
	v_lshlrev_b64 v[22:23], 12, v[22:23]
	v_cvt_pk_bf16_f32 v18, v38, v39
	v_lshl_add_u64 v[22:23], v[36:37], 0, v[22:23]
	v_mul_f32_e32 v12, 0xbfb8aa3b, v14
	global_store_dwordx4 v[22:23], v[18:21], off
	v_exp_f32_e32 v12, v12
	v_mul_f32_e32 v24, 0xbfb8aa3b, v8
	v_mov_b32_e32 v20, v0
	v_mul_f32_e32 v0, 0xbfb8aa3b, v15
	v_mov_b32_e32 v19, v8
	v_exp_f32_e32 v0, v0
	v_mul_f32_e32 v8, 0xbfb8aa3b, v9
	v_exp_f32_e32 v25, v24
	v_exp_f32_e32 v8, v8
	v_add_f32_e32 v12, 1.0, v12
	v_add_f32_e32 v0, 1.0, v0
	v_rcp_f32_e32 v24, v12
	v_add_f32_e32 v12, 1.0, v25
	v_mov_b32_e32 v21, v4
	v_rcp_f32_e32 v22, v0
	v_add_f32_e32 v0, 1.0, v8
	v_mov_b32_e32 v4, v1
	v_mul_f32_e32 v1, 0xbfb8aa3b, v16
	v_rcp_f32_e32 v25, v12
	v_rcp_f32_e32 v23, v0
	v_exp_f32_e32 v1, v1
	v_mul_f32_e32 v12, 0xbfb8aa3b, v10
	v_exp_f32_e32 v12, v12
	v_mov_b32_e32 v8, v15
	v_pk_mul_f32 v[8:9], v[8:9], v[22:23]
	v_add_f32_e32 v1, 1.0, v1
	v_pk_mul_f32 v[4:5], v[4:5], v[8:9]
	v_rcp_f32_e32 v8, v1
	v_add_f32_e32 v1, 1.0, v12
	v_rcp_f32_e32 v9, v1
	v_cvt_pk_bf16_f32 v1, v4, v5
	v_mov_b32_e32 v4, v16
	v_mov_b32_e32 v5, v10
	v_pk_mul_f32 v[4:5], v[4:5], v[8:9]
	v_mov_b32_e32 v8, v2
	v_mul_f32_e32 v2, 0xbfb8aa3b, v17
	v_exp_f32_e32 v2, v2
	v_mul_f32_e32 v9, 0xbfb8aa3b, v11
	v_exp_f32_e32 v10, v9
	v_mov_b32_e32 v18, v14
	v_add_f32_e32 v2, 1.0, v2
	v_rcp_f32_e32 v14, v2
	v_add_f32_e32 v2, 1.0, v10
	v_rcp_f32_e32 v15, v2
	v_mov_b32_e32 v9, v6
	v_pk_mul_f32 v[4:5], v[8:9], v[4:5]
	v_mov_b32_e32 v10, v17
	v_cvt_pk_bf16_f32 v2, v4, v5
	v_pk_mul_f32 v[4:5], v[10:11], v[14:15]
	v_mov_b32_e32 v6, v3
	v_pk_mul_f32 v[4:5], v[6:7], v[4:5]
	v_pk_mul_f32 v[18:19], v[18:19], v[24:25]
	v_cvt_pk_bf16_f32 v3, v4, v5
	v_or_b32_e32 v4, 48, v34
	v_ashrrev_i32_e32 v5, 31, v4
	v_pk_mul_f32 v[18:19], v[20:21], v[18:19]
	v_lshlrev_b64 v[4:5], 12, v[4:5]
	s_add_i32 s10, s10, s62
	v_cvt_pk_bf16_f32 v0, v18, v19
	v_lshl_add_u64 v[4:5], v[36:37], 0, v[4:5]
	s_cmpk_lt_i32 s11, 0x1100
	global_store_dwordx4 v[4:5], v[0:3], off
	s_cbranch_scc1 .LBB0_1479
